# up-proj GEMMs (phases 6,12): last 6 of 16 epilogue stores held in spare VGPRs and issued one per K-phase in the next unit's peeled first iteration
# baseline (speedup 1.0000x reference)
; #define PG8_STAGE(bufoff, gbase, voff) do { _Pragma("unroll") for (int _i = 0; _i < 2; ++_i) \
;         __builtin_amdgcn_global_load_lds((const unsigned*)((const char*)(gbase) + (voff)[_i]), (LAS unsigned*)(lds + (bufoff) + ldsw + _i * 8192), 16, 0, 0); } while (0)
; #define PG8_WAIT_V(n) asm volatile("s_waitcnt vmcnt(" #n ")" ::: "memory")
; #define PG8_BAR __builtin_amdgcn_s_barrier()
; template <class Epi>
; __device__ __forceinline__ void gemm_phase(LAS unsigned char* lds, const Gemm g, const StaticOrder& S, const Epi& E) {
;     ...
;     for (int i = 0; i < 2; ++i) { int R, C; stage_rc(tid * 16 + i * 8192, R, C); const int Rb = Epi::PERM ? ((R & ~31) + perm32(R & 31)) : R;
;         voffA[i] = (unsigned)(R * lda + C) * 2u; voffB[i] = (unsigned)(Rb * K + C) * 2u; }
;     const size_t kstep = (size_t)(BK * 2);
;     const size_t hstepA = (size_t)HALF * lda * 2, hstepB = (size_t)HALF * K * 2;
;     const size_t tstepA = 2 * hstepA, tstepB = 2 * hstepB;
;     const unsigned ldsw = (unsigned)wid * 1024u;
;     const int aoff = lds_byte(wr * 64 + fr, fq * 8), boff = lds_byte(wc * 32 + fr, fq * 8);
;     ...
;     const char* cA = (const char*)g.A + (size_t)cur.pm * tstepA; const char* cB = (const char*)g.Bt + (size_t)cur.pn * tstepB;
;     PG8_STAGE(PG8_SB(0, 0), cB, voffB); PG8_STAGE(PG8_SA(0, 0), cA, voffA); PG8_STAGE(PG8_SB(0, 1), cB + hstepB, voffB); PG8_STAGE(PG8_SA(0, 1), cA + hstepA, voffA);
;     if (wr == 1) PG8_BAR;
;     PG8_WAIT_V(4); PG8_BAR;
;     PG8_STAGE(PG8_SB(1, 0), cB + kstep, voffB); PG8_STAGE(PG8_SA(1, 0), cA + kstep, voffA); PG8_STAGE(PG8_SB(1, 1), cB + hstepB + kstep, voffB);
;     PG8_WAIT_V(6); PG8_BAR;
.LBB0_762:
	s_lshl_b32 s4, s4, 5
	s_and_b32 s12, s4, 0x60
	s_mov_b64 s[4:5], 0x80
	s_add_i32 m0, s19, 0x18000
	v_lshl_add_u64 v[6:7], v[6:7], 0, s[4:5]
	s_lshl_b32 s8, s1, 13
	s_lshl_b32 s13, s12, 7
	s_waitcnt vmcnt(4)
	s_barrier
	global_load_lds_dwordx4 v[6:7], off
	v_lshl_add_u64 v[4:5], v[4:5], 0, s[4:5]
	s_add_i32 m0, s19, 0x1a000
	s_add_i32 s35, s19, 0x8000
	s_add_i32 s36, s19, 0xa000
	global_load_lds_dwordx4 v[4:5], off
	v_lshl_add_u64 v[2:3], v[2:3], 0, s[4:5]
	s_mov_b32 m0, s35
	s_add_u32 s10, s22, 0x40080
	global_load_lds_dwordx4 v[2:3], off
	v_lshl_add_u64 v[0:1], v[0:1], 0, s[4:5]
	s_mov_b32 m0, s36
	s_addc_u32 s11, s23, 0
	global_load_lds_dwordx4 v[0:1], off
	s_add_i32 m0, s19, 0x1c000
	v_lshl_add_u64 v[0:1], s[10:11], 0, v[130:131]
	global_load_lds_dwordx4 v[0:1], off
	v_lshl_add_u64 v[0:1], s[10:11], 0, v[134:135]
	s_add_i32 m0, s19, 0x1e000
	v_bfe_u32 v2, v152, 4, 2
	global_load_lds_dwordx4 v[0:1], off
	v_and_b32_e32 v1, 15, v152
	v_lshlrev_b32_e32 v0, 4, v2
	v_lshlrev_b32_e32 v3, 2, v152
	v_lshl_or_b32 v174, s1, 6, v1
	v_lshl_or_b32 v1, v1, 6, v0
	v_and_b32_e32 v3, 32, v3
	s_sext_i32_i8 s40, s0
	v_bitop3_b32 v4, v1, s8, v3 bitop3:0xde
	v_lshlrev_b32_e32 v1, 6, v152
	s_movk_i32 s0, 0x3c0
	v_and_or_b32 v1, v1, s0, v0
	v_bitop3_b32 v175, s13, v1, v3 bitop3:0xf6
	v_mov_b32_e32 v1, v131
	v_lshl_add_u64 v[136:137], s[6:7], 0, v[0:1]
	v_lshlrev_b32_e32 v0, 8, v152
	v_and_b32_e32 v0, 0x38000, v0
	v_lshlrev_b32_e32 v1, 11, v10
	v_or3_b32 v0, v8, v0, v1
	v_add_u32_e32 v138, v0, v9
	v_lshlrev_b32_e32 v0, 4, v11
	v_and_b32_e32 v0, 0x78000, v0
	s_waitcnt vmcnt(6)
	v_or3_b32 v0, v8, v0, v1
	v_add_u32_e32 v140, v0, v9
	s_add_i32 s7, 0, 0x10000
	s_add_i32 s38, 0, 0x14000
	v_mbcnt_lo_u32_b32 v0, -1, 0
	s_ashr_i32 s37, s92, 31
	v_lshl_or_b32 v176, v2, 3, s12
	v_mov_b32_e32 v139, v131
	v_mov_b32_e32 v141, v131
	v_mov_b64_e32 v[142:143], 0x1000
	v_mov_b64_e32 v[144:145], 0xfff
	v_add_u32_e32 v177, s7, v175
	v_add_u32_e32 v178, 0, v4
	v_add_u32_e32 v179, s38, v175
	v_mbcnt_hi_u32_b32 v180, -1, v0
	s_mov_b32 s6, 0x3a800000
	s_mov_b32 s8, 0x358637bd
	s_mov_b32 s39, 0x800000
	s_barrier
	s_mov_b64 s[98:99], 0x20000
	s_branch .LBB0_763

; #define PG8_STAGE(bufoff, gbase, voff) do { _Pragma("unroll") for (int _i = 0; _i < 2; ++_i) \
;         __builtin_amdgcn_global_load_lds((const unsigned*)((const char*)(gbase) + (voff)[_i]), (LAS unsigned*)(lds + (bufoff) + ldsw + _i * 8192), 16, 0, 0); } while (0)
; #define PG8_LDA(dst, b, h) do { _Pragma("unroll") for (int m = 0; m < 4; ++m) _Pragma("unroll") for (int k = 0; k < 2; ++k) dst[m][k] = *(const LAS bf16x8*)(lds + PG8_SA(b, h) + aoff + m * 2048 + k * 1024); } while (0)
; #define PG8_LDB(dst, b, h) do { _Pragma("unroll") for (int n = 0; n < 2; ++n) _Pragma("unroll") for (int k = 0; k < 2; ++k) dst[n][k] = *(const LAS bf16x8*)(lds + PG8_SB(b, h) + boff + n * 2048 + k * 1024); } while (0)
; #define PG8_MMA(ai, bj, At, Bt) do { __builtin_amdgcn_s_setprio(1); _Pragma("unroll") for (int m = 0; m < 4; ++m) _Pragma("unroll") for (int n = 0; n < 2; ++n) _Pragma("unroll") for (int k = 0; k < 2; ++k) \
;         acc[ai][bj][m][n] = __builtin_amdgcn_mfma_f32_16x16x32_bf16(Bt[n][k], At[m][k], acc[ai][bj][m][n], 0, 0, 0); __builtin_amdgcn_s_setprio(0); } while (0)
; #define PG8_BAR __builtin_amdgcn_s_barrier()
; template <class Epi>
; __device__ __forceinline__ void gemm_phase(LAS unsigned char* lds, const Gemm g, const StaticOrder& S, const Epi& E) {
;     ...
;         const bool has_next = S.next(ui + 1, nxt);
;         const char* nA = has_next ? (const char*)g.A + (size_t)nxt.pm * tstepA : cA; const char* nB = has_next ? (const char*)g.Bt + (size_t)nxt.pn * tstepB : cB;
;         for (int t = 0; t < nt; t += 2) {
;             const bool last = (t == nt - 2);
;             const char* a1 = cA + (size_t)(t + 1) * kstep;
;             const char* a2 = last ? nA : cA + (size_t)(t + 2) * kstep; const char* b2 = last ? nB : cB + (size_t)(t + 2) * kstep;
;             const char* a3 = a2 + kstep; const char* b3 = b2 + kstep;
;             if (last) E.pre(cur, wr, fr, epre);
;             PG8_LDB(B0, 0, 0); PG8_SCHED; PG8_LDA(At, 0, 0); PG8_STAGE(PG8_SA(1, 1), a1 + hstepA, voffA);
;             PG8_WAIT_L(8); PG8_BAR; PG8_WAIT_L(0); PG8_MMA(0, 0, At, B0); PG8_BAR; PG8_SCHED;
;             PG8_LDB(B1, 0, 1); PG8_STAGE(PG8_SB(0, 0), b2, voffB);
;             PG8_BAR; PG8_WAIT_L(0); PG8_MMA(0, 1, At, B1); PG8_BAR;
;             PG8_LDA(At, 0, 1); PG8_STAGE(PG8_SA(0, 0), a2, voffA);
;             PG8_BAR; PG8_WAIT_L(0); PG8_MMA(1, 0, At, B0); PG8_BAR; PG8_SCHED;
.Ldf6_769:
	s_ashr_i32 s13, s12, 31
	v_cmp_lt_i64_e32 vcc, s[14:15], v[142:143]
	s_lshl_b64 s[14:15], s[12:13], 19
	s_add_u32 s14, s76, s14
	s_addc_u32 s15, s77, s15
	s_and_b64 s[16:17], vcc, exec
	s_cselect_b32 s13, s15, s21
	s_cselect_b32 s41, s14, s20
	s_ashr_i32 s11, s10, 31
	s_lshl_b64 s[16:17], s[10:11], 19
	s_add_u32 s16, s27, s16
	s_addc_u32 s17, s28, s17
	s_and_b64 s[24:25], vcc, exec
	s_cselect_b32 s11, s17, s23
	s_cselect_b32 s42, s16, s22
	s_add_u32 s20, s20, 0x40080
	s_addc_u32 s21, s21, 0
	s_add_u32 s43, s22, 0x100
	s_addc_u32 s44, s23, 0
	s_mov_b32 s45, -2
	ds_read_b128 v[146:149], v177
	ds_read_b128 v[154:157], v177 offset:1024
	ds_read_b128 v[158:161], v177 offset:2048
	ds_read_b128 v[162:165], v177 offset:3072
	s_add_u32 s22, s20, 0xfffc0080
	s_addc_u32 s23, s21, -1
	s_cmp_eq_u32 s45, 12
	s_cselect_b32 s25, s13, s23
	s_cselect_b32 s24, s41, s22
	s_cselect_b32 s23, s11, s44
	s_cselect_b32 s22, s42, s43
	v_lshl_add_u64 v[150:151], s[20:21], 0, v[138:139]
	s_add_i32 m0, s19, 0xc000
	ds_read_b128 v[166:169], v178
	ds_read_b128 v[170:173], v178 offset:1024
	ds_read_b128 v[182:185], v178 offset:2048
	ds_read_b128 v[186:189], v178 offset:3072
	ds_read_b128 v[190:193], v178 offset:4096
	ds_read_b128 v[194:197], v178 offset:5120
	ds_read_b128 v[198:201], v178 offset:6144
	ds_read_b128 v[202:205], v178 offset:7168
	global_load_lds_dwordx4 v[150:151], off
	v_lshl_add_u64 v[150:151], s[20:21], 0, v[140:141]
	s_add_i32 m0, s19, 0xe000
	s_nop 0
	global_load_lds_dwordx4 v[150:151], off
	global_store_dwordx4 v[248:249], v[236:239], off
	s_waitcnt lgkmcnt(8)
	s_barrier
	s_waitcnt lgkmcnt(0)
	s_setprio 1
	s_waitcnt lgkmcnt(0)
	v_mfma_f32_16x16x32_bf16 v[124:127], v[146:149], v[166:169], 0
	v_mfma_f32_16x16x32_bf16 v[120:123], v[158:161], v[166:169], 0
	v_mfma_f32_16x16x32_bf16 v[108:111], v[146:149], v[182:185], 0
	v_mfma_f32_16x16x32_bf16 v[104:107], v[158:161], v[182:185], 0
	v_mfma_f32_16x16x32_bf16 v[92:95], v[146:149], v[190:193], 0
	v_mfma_f32_16x16x32_bf16 v[88:91], v[158:161], v[190:193], 0
	v_mfma_f32_16x16x32_bf16 v[76:79], v[146:149], v[198:201], 0
	v_mfma_f32_16x16x32_bf16 v[72:75], v[158:161], v[198:201], 0
	v_mfma_f32_16x16x32_bf16 v[124:127], v[154:157], v[170:173], v[124:127]
	v_mfma_f32_16x16x32_bf16 v[120:123], v[162:165], v[170:173], v[120:123]
	v_mfma_f32_16x16x32_bf16 v[108:111], v[154:157], v[186:189], v[108:111]
	v_mfma_f32_16x16x32_bf16 v[104:107], v[162:165], v[186:189], v[104:107]
	v_mfma_f32_16x16x32_bf16 v[92:95], v[154:157], v[194:197], v[92:95]
	v_mfma_f32_16x16x32_bf16 v[88:91], v[162:165], v[194:197], v[88:91]
	v_mfma_f32_16x16x32_bf16 v[76:79], v[154:157], v[202:205], v[76:79]
	v_mfma_f32_16x16x32_bf16 v[72:75], v[162:165], v[202:205], v[72:75]
	s_setprio 0
	s_barrier
	s_add_i32 s46, s7, s29
	v_lshl_add_u64 v[150:151], s[22:23], 0, v[130:131]
	s_mov_b32 m0, s46
	ds_read_b128 v[206:209], v179
	ds_read_b128 v[210:213], v179 offset:1024
	ds_read_b128 v[214:217], v179 offset:2048
	ds_read_b128 v[218:221], v179 offset:3072
	global_load_lds_dwordx4 v[150:151], off
	v_lshl_add_u64 v[222:223], s[22:23], 0, v[134:135]
	s_add_i32 m0, s46, 0x2000
	s_nop 0
	global_load_lds_dwordx4 v[222:223], off
	global_store_dwordx4 v[248:249], v[240:243], off offset:256
	v_lshl_add_u64 v[248:249], v[248:249], 0, s[98:99]
	s_barrier
	s_waitcnt lgkmcnt(0)
	s_setprio 1
	s_waitcnt lgkmcnt(0)
	v_mfma_f32_16x16x32_bf16 v[116:119], v[206:209], v[166:169], 0
	v_mfma_f32_16x16x32_bf16 v[112:115], v[214:217], v[166:169], 0
	v_mfma_f32_16x16x32_bf16 v[100:103], v[206:209], v[182:185], 0
	v_mfma_f32_16x16x32_bf16 v[96:99], v[214:217], v[182:185], 0
	v_mfma_f32_16x16x32_bf16 v[84:87], v[206:209], v[190:193], 0
	v_mfma_f32_16x16x32_bf16 v[80:83], v[214:217], v[190:193], 0
	v_mfma_f32_16x16x32_bf16 v[68:71], v[206:209], v[198:201], 0
	v_mfma_f32_16x16x32_bf16 v[64:67], v[214:217], v[198:201], 0
	v_mfma_f32_16x16x32_bf16 v[116:119], v[210:213], v[170:173], v[116:119]
	v_mfma_f32_16x16x32_bf16 v[112:115], v[218:221], v[170:173], v[112:115]
	v_mfma_f32_16x16x32_bf16 v[100:103], v[210:213], v[186:189], v[100:103]
	v_mfma_f32_16x16x32_bf16 v[96:99], v[218:221], v[186:189], v[96:99]
	v_mfma_f32_16x16x32_bf16 v[84:87], v[210:213], v[194:197], v[84:87]
	v_mfma_f32_16x16x32_bf16 v[80:83], v[218:221], v[194:197], v[80:83]
	v_mfma_f32_16x16x32_bf16 v[68:71], v[210:213], v[202:205], v[68:71]
	v_mfma_f32_16x16x32_bf16 v[64:67], v[218:221], v[202:205], v[64:67]
	s_setprio 0
	s_mov_b32 m0, s19
	v_lshl_add_u64 v[224:225], s[24:25], 0, v[128:129]
	s_barrier
	ds_read_b128 v[166:169], v178 offset:16384
	ds_read_b128 v[170:173], v178 offset:17408
	ds_read_b128 v[182:185], v178 offset:18432
	ds_read_b128 v[186:189], v178 offset:19456
	ds_read_b128 v[190:193], v178 offset:20480
	ds_read_b128 v[194:197], v178 offset:21504
	ds_read_b128 v[198:201], v178 offset:22528
	ds_read_b128 v[202:205], v178 offset:23552
	global_load_lds_dwordx4 v[224:225], off
	v_lshl_add_u64 v[226:227], s[24:25], 0, v[132:133]
	s_mov_b32 m0, s30
	s_nop 0
	global_load_lds_dwordx4 v[226:227], off
	global_store_dwordx4 v[248:249], v[244:247], off
	s_barrier
; #define PG8_STAGE(bufoff, gbase, voff) do { _Pragma("unroll") for (int _i = 0; _i < 2; ++_i) \
;         __builtin_amdgcn_global_load_lds((const unsigned*)((const char*)(gbase) + (voff)[_i]), (LAS unsigned*)(lds + (bufoff) + ldsw + _i * 8192), 16, 0, 0); } while (0)
; #define PG8_LDA(dst, b, h) do { _Pragma("unroll") for (int m = 0; m < 4; ++m) _Pragma("unroll") for (int k = 0; k < 2; ++k) dst[m][k] = *(const LAS bf16x8*)(lds + PG8_SA(b, h) + aoff + m * 2048 + k * 1024); } while (0)
; #define PG8_LDB(dst, b, h) do { _Pragma("unroll") for (int n = 0; n < 2; ++n) _Pragma("unroll") for (int k = 0; k < 2; ++k) dst[n][k] = *(const LAS bf16x8*)(lds + PG8_SB(b, h) + boff + n * 2048 + k * 1024); } while (0)
; #define PG8_MMA(ai, bj, At, Bt) do { __builtin_amdgcn_s_setprio(1); _Pragma("unroll") for (int m = 0; m < 4; ++m) _Pragma("unroll") for (int n = 0; n < 2; ++n) _Pragma("unroll") for (int k = 0; k < 2; ++k) \
;         acc[ai][bj][m][n] = __builtin_amdgcn_mfma_f32_16x16x32_bf16(Bt[n][k], At[m][k], acc[ai][bj][m][n], 0, 0, 0); __builtin_amdgcn_s_setprio(0); } while (0)
; #define PG8_WAIT_V(n) asm volatile("s_waitcnt vmcnt(" #n ")" ::: "memory")
; #define PG8_WAIT_L(n) asm volatile("s_waitcnt lgkmcnt(" #n ")" ::: "memory")
; #define PG8_BAR __builtin_amdgcn_s_barrier()
; #define PG8_SCHED __builtin_amdgcn_sched_barrier(0)
; template <class Epi>
; __device__ __forceinline__ void gemm_phase(LAS unsigned char* lds, const Gemm g, const StaticOrder& S, const Epi& E) {
;     ...
;             PG8_BAR; PG8_WAIT_L(0); PG8_MMA(1, 0, At, B0); PG8_BAR; PG8_SCHED;
;             PG8_STAGE(PG8_SB(0, 1), b2 + hstepB, voffB);
;             PG8_WAIT_V(6); PG8_BAR; PG8_MMA(1, 1, At, B1); PG8_BAR;
;             PG8_LDB(B0, 1, 0); PG8_SCHED; PG8_LDA(At, 1, 0); PG8_STAGE(PG8_SA(0, 1), a2 + hstepA, voffA);
;             PG8_WAIT_L(8); PG8_BAR; PG8_WAIT_L(0); PG8_MMA(0, 0, At, B0); PG8_BAR; PG8_SCHED;
	s_waitcnt lgkmcnt(0)
	s_setprio 1
	s_waitcnt lgkmcnt(0)
	v_mfma_f32_16x16x32_bf16 v[60:63], v[146:149], v[166:169], 0
	v_mfma_f32_16x16x32_bf16 v[56:59], v[158:161], v[166:169], 0
	v_mfma_f32_16x16x32_bf16 v[44:47], v[146:149], v[182:185], 0
	v_mfma_f32_16x16x32_bf16 v[40:43], v[158:161], v[182:185], 0
	v_mfma_f32_16x16x32_bf16 v[28:31], v[146:149], v[190:193], 0
	v_mfma_f32_16x16x32_bf16 v[24:27], v[158:161], v[190:193], 0
	v_mfma_f32_16x16x32_bf16 v[12:15], v[146:149], v[198:201], 0
	v_mfma_f32_16x16x32_bf16 v[8:11], v[158:161], v[198:201], 0
	v_mfma_f32_16x16x32_bf16 v[60:63], v[154:157], v[170:173], v[60:63]
	v_mfma_f32_16x16x32_bf16 v[56:59], v[162:165], v[170:173], v[56:59]
	v_mfma_f32_16x16x32_bf16 v[44:47], v[154:157], v[186:189], v[44:47]
	v_mfma_f32_16x16x32_bf16 v[40:43], v[162:165], v[186:189], v[40:43]
	v_mfma_f32_16x16x32_bf16 v[28:31], v[154:157], v[194:197], v[28:31]
	v_mfma_f32_16x16x32_bf16 v[24:27], v[162:165], v[194:197], v[24:27]
	v_mfma_f32_16x16x32_bf16 v[12:15], v[154:157], v[202:205], v[12:15]
	v_mfma_f32_16x16x32_bf16 v[8:11], v[162:165], v[202:205], v[8:11]
	s_setprio 0
	s_barrier
	s_add_u32 s46, s22, 0x40000
	s_addc_u32 s47, s23, 0
	s_add_i32 s48, s38, s29
	v_lshl_add_u64 v[146:147], s[46:47], 0, v[130:131]
	s_mov_b32 m0, s48
	s_nop 0
	global_load_lds_dwordx4 v[146:147], off
	v_lshl_add_u64 v[146:147], s[46:47], 0, v[134:135]
	s_add_i32 m0, s48, 0x2000
	s_nop 0
	global_load_lds_dwordx4 v[146:147], off
	global_store_dwordx4 v[248:249], v[252:255], off offset:256
	v_lshl_add_u64 v[248:249], v[248:249], 0, s[98:99]
	s_waitcnt vmcnt(10)
	s_barrier
	s_setprio 1
	v_mfma_f32_16x16x32_bf16 v[52:55], v[206:209], v[166:169], 0
	v_mfma_f32_16x16x32_bf16 v[48:51], v[214:217], v[166:169], 0
	v_mfma_f32_16x16x32_bf16 v[36:39], v[206:209], v[182:185], 0
	v_mfma_f32_16x16x32_bf16 v[32:35], v[214:217], v[182:185], 0
	v_mfma_f32_16x16x32_bf16 v[20:23], v[206:209], v[190:193], 0
	v_mfma_f32_16x16x32_bf16 v[16:19], v[214:217], v[190:193], 0
	v_mfma_f32_16x16x32_bf16 v[4:7], v[206:209], v[198:201], 0
	v_mfma_f32_16x16x32_bf16 v[0:3], v[214:217], v[198:201], 0
	v_mfma_f32_16x16x32_bf16 v[52:55], v[210:213], v[170:173], v[52:55]
	v_mfma_f32_16x16x32_bf16 v[48:51], v[218:221], v[170:173], v[48:51]
	v_mfma_f32_16x16x32_bf16 v[36:39], v[210:213], v[186:189], v[36:39]
	v_mfma_f32_16x16x32_bf16 v[32:35], v[218:221], v[186:189], v[32:35]
	v_mfma_f32_16x16x32_bf16 v[20:23], v[210:213], v[194:197], v[20:23]
	v_mfma_f32_16x16x32_bf16 v[16:19], v[218:221], v[194:197], v[16:19]
	v_mfma_f32_16x16x32_bf16 v[4:7], v[210:213], v[202:205], v[4:7]
	v_mfma_f32_16x16x32_bf16 v[0:3], v[218:221], v[202:205], v[0:3]
	s_setprio 0
	s_add_i32 s46, 0, 0x18000
	v_add_u32_e32 v162, s46, v175
	s_barrier
	ds_read_b128 v[146:149], v162
	ds_read_b128 v[154:157], v162 offset:1024
	ds_read_b128 v[158:161], v162 offset:2048
	ds_read_b128 v[162:165], v162 offset:3072
	s_add_u32 s24, s24, 0x40000
	s_addc_u32 s25, s25, 0
	s_mov_b32 m0, s31
	v_lshl_add_u64 v[206:207], s[24:25], 0, v[128:129]
	ds_read_b128 v[166:169], v178 offset:32768
	ds_read_b128 v[170:173], v178 offset:33792
	ds_read_b128 v[182:185], v178 offset:34816
	ds_read_b128 v[186:189], v178 offset:35840
	ds_read_b128 v[190:193], v178 offset:36864
	ds_read_b128 v[194:197], v178 offset:37888
	ds_read_b128 v[198:201], v178 offset:38912
	ds_read_b128 v[202:205], v178 offset:39936
	global_load_lds_dwordx4 v[206:207], off
	v_lshl_add_u64 v[206:207], s[24:25], 0, v[132:133]
	s_mov_b32 m0, s33
	s_nop 0
	global_load_lds_dwordx4 v[206:207], off
	global_store_dwordx4 v[248:249], v[228:231], off
	s_waitcnt lgkmcnt(8)
	s_barrier
	s_waitcnt lgkmcnt(0)
	s_setprio 1
	s_waitcnt lgkmcnt(0)
	v_mfma_f32_16x16x32_bf16 v[124:127], v[146:149], v[166:169], v[124:127]
	v_mfma_f32_16x16x32_bf16 v[120:123], v[158:161], v[166:169], v[120:123]
	v_mfma_f32_16x16x32_bf16 v[108:111], v[146:149], v[182:185], v[108:111]
	v_mfma_f32_16x16x32_bf16 v[104:107], v[158:161], v[182:185], v[104:107]
	v_mfma_f32_16x16x32_bf16 v[92:95], v[146:149], v[190:193], v[92:95]
	v_mfma_f32_16x16x32_bf16 v[88:91], v[158:161], v[190:193], v[88:91]
	v_mfma_f32_16x16x32_bf16 v[76:79], v[146:149], v[198:201], v[76:79]
	v_mfma_f32_16x16x32_bf16 v[72:75], v[158:161], v[198:201], v[72:75]
	v_mfma_f32_16x16x32_bf16 v[124:127], v[154:157], v[170:173], v[124:127]
	v_mfma_f32_16x16x32_bf16 v[120:123], v[162:165], v[170:173], v[120:123]
	v_mfma_f32_16x16x32_bf16 v[108:111], v[154:157], v[186:189], v[108:111]
	v_mfma_f32_16x16x32_bf16 v[104:107], v[162:165], v[186:189], v[104:107]
	v_mfma_f32_16x16x32_bf16 v[92:95], v[154:157], v[194:197], v[92:95]
	v_mfma_f32_16x16x32_bf16 v[88:91], v[162:165], v[194:197], v[88:91]
	v_mfma_f32_16x16x32_bf16 v[76:79], v[154:157], v[202:205], v[76:79]
	v_mfma_f32_16x16x32_bf16 v[72:75], v[162:165], v[202:205], v[72:75]
	s_setprio 0
	s_barrier
; #define PG8_STAGE(bufoff, gbase, voff) do { _Pragma("unroll") for (int _i = 0; _i < 2; ++_i) \
;         __builtin_amdgcn_global_load_lds((const unsigned*)((const char*)(gbase) + (voff)[_i]), (LAS unsigned*)(lds + (bufoff) + ldsw + _i * 8192), 16, 0, 0); } while (0)
; #define PG8_LDA(dst, b, h) do { _Pragma("unroll") for (int m = 0; m < 4; ++m) _Pragma("unroll") for (int k = 0; k < 2; ++k) dst[m][k] = *(const LAS bf16x8*)(lds + PG8_SA(b, h) + aoff + m * 2048 + k * 1024); } while (0)
; #define PG8_LDB(dst, b, h) do { _Pragma("unroll") for (int n = 0; n < 2; ++n) _Pragma("unroll") for (int k = 0; k < 2; ++k) dst[n][k] = *(const LAS bf16x8*)(lds + PG8_SB(b, h) + boff + n * 2048 + k * 1024); } while (0)
; #define PG8_MMA(ai, bj, At, Bt) do { __builtin_amdgcn_s_setprio(1); _Pragma("unroll") for (int m = 0; m < 4; ++m) _Pragma("unroll") for (int n = 0; n < 2; ++n) _Pragma("unroll") for (int k = 0; k < 2; ++k) \
;         acc[ai][bj][m][n] = __builtin_amdgcn_mfma_f32_16x16x32_bf16(Bt[n][k], At[m][k], acc[ai][bj][m][n], 0, 0, 0); __builtin_amdgcn_s_setprio(0); } while (0)
; #define PG8_WAIT_V(n) asm volatile("s_waitcnt vmcnt(" #n ")" ::: "memory")
; #define PG8_WAIT_L(n) asm volatile("s_waitcnt lgkmcnt(" #n ")" ::: "memory")
; #define PG8_BAR __builtin_amdgcn_s_barrier()
; #define PG8_SCHED __builtin_amdgcn_sched_barrier(0)
; template <class Epi>
; __device__ __forceinline__ void gemm_phase(LAS unsigned char* lds, const Gemm g, const StaticOrder& S, const Epi& E) {
;     ...
;             PG8_LDB(B1, 1, 1); PG8_STAGE(PG8_SB(1, 0), b3, voffB);
;             PG8_BAR; PG8_WAIT_L(0); PG8_MMA(0, 1, At, B1); PG8_BAR;
;             PG8_LDA(At, 1, 1); PG8_STAGE(PG8_SA(1, 0), a3, voffA);
;             PG8_BAR; PG8_WAIT_L(0); PG8_MMA(1, 0, At, B0); PG8_BAR; PG8_SCHED;
;             PG8_STAGE(PG8_SB(1, 1), b3 + hstepB, voffB);
;             PG8_WAIT_V(6); PG8_BAR; PG8_MMA(1, 1, At, B1); PG8_BAR;
	s_add_i32 s24, 0, 0x1c000
	s_add_i32 s25, s46, s29
	v_add_u32_e32 v181, s24, v175
	v_lshl_add_u64 v[150:151], v[150:151], 0, s[4:5]
	s_mov_b32 m0, s25
	ds_read_b128 v[206:209], v181
	ds_read_b128 v[210:213], v181 offset:1024
	ds_read_b128 v[214:217], v181 offset:2048
	ds_read_b128 v[218:221], v181 offset:3072
	global_load_lds_dwordx4 v[150:151], off
	v_lshl_add_u64 v[150:151], v[222:223], 0, s[4:5]
	s_add_i32 m0, s25, 0x2000
	s_nop 0
	global_load_lds_dwordx4 v[150:151], off
	global_store_dwordx4 v[248:249], v[232:235], off offset:256
	s_barrier
	s_waitcnt lgkmcnt(0)
	s_setprio 1
	s_waitcnt lgkmcnt(0)
	v_mfma_f32_16x16x32_bf16 v[116:119], v[206:209], v[166:169], v[116:119]
	v_mfma_f32_16x16x32_bf16 v[112:115], v[214:217], v[166:169], v[112:115]
	v_mfma_f32_16x16x32_bf16 v[100:103], v[206:209], v[182:185], v[100:103]
	v_mfma_f32_16x16x32_bf16 v[96:99], v[214:217], v[182:185], v[96:99]
	v_mfma_f32_16x16x32_bf16 v[84:87], v[206:209], v[190:193], v[84:87]
	v_mfma_f32_16x16x32_bf16 v[80:83], v[214:217], v[190:193], v[80:83]
	v_mfma_f32_16x16x32_bf16 v[68:71], v[206:209], v[198:201], v[68:71]
	v_mfma_f32_16x16x32_bf16 v[64:67], v[214:217], v[198:201], v[64:67]
	v_mfma_f32_16x16x32_bf16 v[116:119], v[210:213], v[170:173], v[116:119]
	v_mfma_f32_16x16x32_bf16 v[112:115], v[218:221], v[170:173], v[112:115]
	v_mfma_f32_16x16x32_bf16 v[100:103], v[210:213], v[186:189], v[100:103]
	v_mfma_f32_16x16x32_bf16 v[96:99], v[218:221], v[186:189], v[96:99]
	v_mfma_f32_16x16x32_bf16 v[84:87], v[210:213], v[194:197], v[84:87]
	v_mfma_f32_16x16x32_bf16 v[80:83], v[218:221], v[194:197], v[80:83]
	v_mfma_f32_16x16x32_bf16 v[68:71], v[210:213], v[202:205], v[68:71]
	v_mfma_f32_16x16x32_bf16 v[64:67], v[218:221], v[202:205], v[64:67]
	s_setprio 0
	s_mov_b32 m0, s35
	v_lshl_add_u64 v[150:151], v[224:225], 0, s[4:5]
	s_barrier
	ds_read_b128 v[166:169], v178 offset:49152
	ds_read_b128 v[170:173], v178 offset:50176
	ds_read_b128 v[182:185], v178 offset:51200
	ds_read_b128 v[186:189], v178 offset:52224
	ds_read_b128 v[190:193], v178 offset:53248
	ds_read_b128 v[194:197], v178 offset:54272
	ds_read_b128 v[198:201], v178 offset:55296
	ds_read_b128 v[202:205], v178 offset:56320
	global_load_lds_dwordx4 v[150:151], off
	v_lshl_add_u64 v[150:151], v[226:227], 0, s[4:5]
	s_mov_b32 m0, s36
	s_nop 0
	global_load_lds_dwordx4 v[150:151], off
	s_barrier
	s_waitcnt lgkmcnt(0)
	s_setprio 1
	s_waitcnt lgkmcnt(0)
	v_mfma_f32_16x16x32_bf16 v[60:63], v[146:149], v[166:169], v[60:63]
	v_mfma_f32_16x16x32_bf16 v[56:59], v[158:161], v[166:169], v[56:59]
	v_mfma_f32_16x16x32_bf16 v[44:47], v[146:149], v[182:185], v[44:47]
	v_mfma_f32_16x16x32_bf16 v[40:43], v[158:161], v[182:185], v[40:43]
	v_mfma_f32_16x16x32_bf16 v[28:31], v[146:149], v[190:193], v[28:31]
	v_mfma_f32_16x16x32_bf16 v[24:27], v[158:161], v[190:193], v[24:27]
	v_mfma_f32_16x16x32_bf16 v[12:15], v[146:149], v[198:201], v[12:15]
	v_mfma_f32_16x16x32_bf16 v[8:11], v[158:161], v[198:201], v[8:11]
	v_mfma_f32_16x16x32_bf16 v[60:63], v[154:157], v[170:173], v[60:63]
	v_mfma_f32_16x16x32_bf16 v[56:59], v[162:165], v[170:173], v[56:59]
	v_mfma_f32_16x16x32_bf16 v[44:47], v[154:157], v[186:189], v[44:47]
	v_mfma_f32_16x16x32_bf16 v[40:43], v[162:165], v[186:189], v[40:43]
	v_mfma_f32_16x16x32_bf16 v[28:31], v[154:157], v[194:197], v[28:31]
	v_mfma_f32_16x16x32_bf16 v[24:27], v[162:165], v[194:197], v[24:27]
	v_mfma_f32_16x16x32_bf16 v[12:15], v[154:157], v[202:205], v[12:15]
	v_mfma_f32_16x16x32_bf16 v[8:11], v[162:165], v[202:205], v[8:11]
	s_setprio 0
	s_barrier
	s_add_u32 s22, s22, 0x40080
	s_addc_u32 s23, s23, 0
	s_add_i32 s24, s24, s29
	v_lshl_add_u64 v[146:147], s[22:23], 0, v[130:131]
	s_mov_b32 m0, s24
	s_nop 0
	global_load_lds_dwordx4 v[146:147], off
	v_lshl_add_u64 v[146:147], s[22:23], 0, v[134:135]
	s_add_i32 m0, s24, 0x2000
	s_nop 0
	global_load_lds_dwordx4 v[146:147], off
	s_waitcnt vmcnt(8)
	s_barrier
	s_setprio 1
	v_mfma_f32_16x16x32_bf16 v[52:55], v[206:209], v[166:169], v[52:55]
	v_mfma_f32_16x16x32_bf16 v[48:51], v[214:217], v[166:169], v[48:51]
	v_mfma_f32_16x16x32_bf16 v[36:39], v[206:209], v[182:185], v[36:39]
	v_mfma_f32_16x16x32_bf16 v[32:35], v[214:217], v[182:185], v[32:35]
	v_mfma_f32_16x16x32_bf16 v[20:23], v[206:209], v[190:193], v[20:23]
	v_mfma_f32_16x16x32_bf16 v[16:19], v[214:217], v[190:193], v[16:19]
	v_mfma_f32_16x16x32_bf16 v[4:7], v[206:209], v[198:201], v[4:7]
	v_mfma_f32_16x16x32_bf16 v[0:3], v[214:217], v[198:201], v[0:3]
	v_mfma_f32_16x16x32_bf16 v[52:55], v[210:213], v[170:173], v[52:55]
	v_mfma_f32_16x16x32_bf16 v[48:51], v[218:221], v[170:173], v[48:51]
	v_mfma_f32_16x16x32_bf16 v[36:39], v[210:213], v[186:189], v[36:39]
	v_mfma_f32_16x16x32_bf16 v[32:35], v[218:221], v[186:189], v[32:35]
	v_mfma_f32_16x16x32_bf16 v[20:23], v[210:213], v[194:197], v[20:23]
	v_mfma_f32_16x16x32_bf16 v[16:19], v[218:221], v[194:197], v[16:19]
	v_mfma_f32_16x16x32_bf16 v[4:7], v[210:213], v[202:205], v[4:7]
	v_mfma_f32_16x16x32_bf16 v[0:3], v[218:221], v[202:205], v[0:3]
	s_setprio 0
	s_add_i32 s45, s45, 2
	s_add_u32 s20, s20, 0x100
	s_addc_u32 s21, s21, 0
	s_add_u32 s43, s43, 0x100
	s_addc_u32 s44, s44, 0
	s_cmp_gt_u32 s45, 13
	s_barrier
	s_branch .LBB0_770

; #define PG8_STAGE(bufoff, gbase, voff) do { _Pragma("unroll") for (int _i = 0; _i < 2; ++_i) \
;         __builtin_amdgcn_global_load_lds((const unsigned*)((const char*)(gbase) + (voff)[_i]), (LAS unsigned*)(lds + (bufoff) + ldsw + _i * 8192), 16, 0, 0); } while (0)
; #define PG8_LDA(dst, b, h) do { _Pragma("unroll") for (int m = 0; m < 4; ++m) _Pragma("unroll") for (int k = 0; k < 2; ++k) dst[m][k] = *(const LAS bf16x8*)(lds + PG8_SA(b, h) + aoff + m * 2048 + k * 1024); } while (0)
; #define PG8_LDB(dst, b, h) do { _Pragma("unroll") for (int n = 0; n < 2; ++n) _Pragma("unroll") for (int k = 0; k < 2; ++k) dst[n][k] = *(const LAS bf16x8*)(lds + PG8_SB(b, h) + boff + n * 2048 + k * 1024); } while (0)
; #define PG8_MMA(ai, bj, At, Bt) do { __builtin_amdgcn_s_setprio(1); _Pragma("unroll") for (int m = 0; m < 4; ++m) _Pragma("unroll") for (int n = 0; n < 2; ++n) _Pragma("unroll") for (int k = 0; k < 2; ++k) \
;         acc[ai][bj][m][n] = __builtin_amdgcn_mfma_f32_16x16x32_bf16(Bt[n][k], At[m][k], acc[ai][bj][m][n], 0, 0, 0); __builtin_amdgcn_s_setprio(0); } while (0)
; #define PG8_WAIT_V(n) asm volatile("s_waitcnt vmcnt(" #n ")" ::: "memory")
; #define PG8_WAIT_L(n) asm volatile("s_waitcnt lgkmcnt(" #n ")" ::: "memory")
; #define PG8_BAR __builtin_amdgcn_s_barrier()
; #define PG8_SCHED __builtin_amdgcn_sched_barrier(0)
; template <class Epi>
; __device__ __forceinline__ void gemm_phase(LAS unsigned char* lds, const Gemm g, const StaticOrder& S, const Epi& E) {
;     ...
;             PG8_LDB(B0, 0, 0); PG8_SCHED; PG8_LDA(At, 0, 0); PG8_STAGE(PG8_SA(1, 1), a1 + hstepA, voffA);
;             PG8_WAIT_L(8); PG8_BAR; PG8_WAIT_L(0); PG8_MMA(0, 0, At, B0); PG8_BAR; PG8_SCHED;
;             PG8_LDB(B1, 0, 1); PG8_STAGE(PG8_SB(0, 0), b2, voffB);
;             PG8_BAR; PG8_WAIT_L(0); PG8_MMA(0, 1, At, B1); PG8_BAR;
;             PG8_LDA(At, 0, 1); PG8_STAGE(PG8_SA(0, 0), a2, voffA);
;             PG8_BAR; PG8_WAIT_L(0); PG8_MMA(1, 0, At, B0); PG8_BAR; PG8_SCHED;
;             PG8_STAGE(PG8_SB(0, 1), b2 + hstepB, voffB);
;             PG8_WAIT_V(6); PG8_BAR; PG8_MMA(1, 1, At, B1); PG8_BAR;
.LBB0_770:
	ds_read_b128 v[146:149], v177
	ds_read_b128 v[154:157], v177 offset:1024
	ds_read_b128 v[158:161], v177 offset:2048
	ds_read_b128 v[162:165], v177 offset:3072
	s_add_u32 s22, s20, 0xfffc0080
	s_addc_u32 s23, s21, -1
	s_cmp_eq_u32 s45, 12
	s_cselect_b32 s25, s13, s23
	s_cselect_b32 s24, s41, s22
	s_cselect_b32 s23, s11, s44
	s_cselect_b32 s22, s42, s43
	v_lshl_add_u64 v[150:151], s[20:21], 0, v[138:139]
	s_add_i32 m0, s19, 0xc000
	ds_read_b128 v[166:169], v178
	ds_read_b128 v[170:173], v178 offset:1024
	ds_read_b128 v[182:185], v178 offset:2048
	ds_read_b128 v[186:189], v178 offset:3072
	ds_read_b128 v[190:193], v178 offset:4096
	ds_read_b128 v[194:197], v178 offset:5120
	ds_read_b128 v[198:201], v178 offset:6144
	ds_read_b128 v[202:205], v178 offset:7168
	global_load_lds_dwordx4 v[150:151], off
	v_lshl_add_u64 v[150:151], s[20:21], 0, v[140:141]
	s_add_i32 m0, s19, 0xe000
	s_nop 0
	global_load_lds_dwordx4 v[150:151], off
	s_waitcnt lgkmcnt(8)
	s_barrier
	s_waitcnt lgkmcnt(0)
	s_setprio 1
	s_waitcnt lgkmcnt(0)
	v_mfma_f32_16x16x32_bf16 v[124:127], v[146:149], v[166:169], v[124:127]
	v_mfma_f32_16x16x32_bf16 v[120:123], v[158:161], v[166:169], v[120:123]
	v_mfma_f32_16x16x32_bf16 v[108:111], v[146:149], v[182:185], v[108:111]
	v_mfma_f32_16x16x32_bf16 v[104:107], v[158:161], v[182:185], v[104:107]
	v_mfma_f32_16x16x32_bf16 v[92:95], v[146:149], v[190:193], v[92:95]
	v_mfma_f32_16x16x32_bf16 v[88:91], v[158:161], v[190:193], v[88:91]
	v_mfma_f32_16x16x32_bf16 v[76:79], v[146:149], v[198:201], v[76:79]
	v_mfma_f32_16x16x32_bf16 v[72:75], v[158:161], v[198:201], v[72:75]
	v_mfma_f32_16x16x32_bf16 v[124:127], v[154:157], v[170:173], v[124:127]
	v_mfma_f32_16x16x32_bf16 v[120:123], v[162:165], v[170:173], v[120:123]
	v_mfma_f32_16x16x32_bf16 v[108:111], v[154:157], v[186:189], v[108:111]
	v_mfma_f32_16x16x32_bf16 v[104:107], v[162:165], v[186:189], v[104:107]
	v_mfma_f32_16x16x32_bf16 v[92:95], v[154:157], v[194:197], v[92:95]
	v_mfma_f32_16x16x32_bf16 v[88:91], v[162:165], v[194:197], v[88:91]
	v_mfma_f32_16x16x32_bf16 v[76:79], v[154:157], v[202:205], v[76:79]
	v_mfma_f32_16x16x32_bf16 v[72:75], v[162:165], v[202:205], v[72:75]
	s_setprio 0
	s_barrier
	s_add_i32 s46, s7, s29
	v_lshl_add_u64 v[150:151], s[22:23], 0, v[130:131]
	s_mov_b32 m0, s46
	ds_read_b128 v[206:209], v179
	ds_read_b128 v[210:213], v179 offset:1024
	ds_read_b128 v[214:217], v179 offset:2048
	ds_read_b128 v[218:221], v179 offset:3072
	global_load_lds_dwordx4 v[150:151], off
	v_lshl_add_u64 v[222:223], s[22:23], 0, v[134:135]
	s_add_i32 m0, s46, 0x2000
	s_nop 0
	global_load_lds_dwordx4 v[222:223], off
	s_barrier
	s_waitcnt lgkmcnt(0)
	s_setprio 1
	s_waitcnt lgkmcnt(0)
	v_mfma_f32_16x16x32_bf16 v[116:119], v[206:209], v[166:169], v[116:119]
	v_mfma_f32_16x16x32_bf16 v[112:115], v[214:217], v[166:169], v[112:115]
	v_mfma_f32_16x16x32_bf16 v[100:103], v[206:209], v[182:185], v[100:103]
	v_mfma_f32_16x16x32_bf16 v[96:99], v[214:217], v[182:185], v[96:99]
	v_mfma_f32_16x16x32_bf16 v[84:87], v[206:209], v[190:193], v[84:87]
	v_mfma_f32_16x16x32_bf16 v[80:83], v[214:217], v[190:193], v[80:83]
	v_mfma_f32_16x16x32_bf16 v[68:71], v[206:209], v[198:201], v[68:71]
	v_mfma_f32_16x16x32_bf16 v[64:67], v[214:217], v[198:201], v[64:67]
	v_mfma_f32_16x16x32_bf16 v[116:119], v[210:213], v[170:173], v[116:119]
	v_mfma_f32_16x16x32_bf16 v[112:115], v[218:221], v[170:173], v[112:115]
	v_mfma_f32_16x16x32_bf16 v[100:103], v[210:213], v[186:189], v[100:103]
	v_mfma_f32_16x16x32_bf16 v[96:99], v[218:221], v[186:189], v[96:99]
	v_mfma_f32_16x16x32_bf16 v[84:87], v[210:213], v[194:197], v[84:87]
	v_mfma_f32_16x16x32_bf16 v[80:83], v[218:221], v[194:197], v[80:83]
	v_mfma_f32_16x16x32_bf16 v[68:71], v[210:213], v[202:205], v[68:71]
	v_mfma_f32_16x16x32_bf16 v[64:67], v[218:221], v[202:205], v[64:67]
	s_setprio 0
	s_mov_b32 m0, s19
	v_lshl_add_u64 v[224:225], s[24:25], 0, v[128:129]
	s_barrier
	ds_read_b128 v[166:169], v178 offset:16384
	ds_read_b128 v[170:173], v178 offset:17408
	ds_read_b128 v[182:185], v178 offset:18432
	ds_read_b128 v[186:189], v178 offset:19456
	ds_read_b128 v[190:193], v178 offset:20480
	ds_read_b128 v[194:197], v178 offset:21504
	ds_read_b128 v[198:201], v178 offset:22528
	ds_read_b128 v[202:205], v178 offset:23552
	global_load_lds_dwordx4 v[224:225], off
	v_lshl_add_u64 v[226:227], s[24:25], 0, v[132:133]
	s_mov_b32 m0, s30
	s_nop 0
	global_load_lds_dwordx4 v[226:227], off
	s_barrier
	s_waitcnt lgkmcnt(0)
	s_setprio 1
	s_waitcnt lgkmcnt(0)
	v_mfma_f32_16x16x32_bf16 v[60:63], v[146:149], v[166:169], v[60:63]
	v_mfma_f32_16x16x32_bf16 v[56:59], v[158:161], v[166:169], v[56:59]
	v_mfma_f32_16x16x32_bf16 v[44:47], v[146:149], v[182:185], v[44:47]
	v_mfma_f32_16x16x32_bf16 v[40:43], v[158:161], v[182:185], v[40:43]
	v_mfma_f32_16x16x32_bf16 v[28:31], v[146:149], v[190:193], v[28:31]
	v_mfma_f32_16x16x32_bf16 v[24:27], v[158:161], v[190:193], v[24:27]
	v_mfma_f32_16x16x32_bf16 v[12:15], v[146:149], v[198:201], v[12:15]
	v_mfma_f32_16x16x32_bf16 v[8:11], v[158:161], v[198:201], v[8:11]
	v_mfma_f32_16x16x32_bf16 v[60:63], v[154:157], v[170:173], v[60:63]
	v_mfma_f32_16x16x32_bf16 v[56:59], v[162:165], v[170:173], v[56:59]
	v_mfma_f32_16x16x32_bf16 v[44:47], v[154:157], v[186:189], v[44:47]
	v_mfma_f32_16x16x32_bf16 v[40:43], v[162:165], v[186:189], v[40:43]
	v_mfma_f32_16x16x32_bf16 v[28:31], v[154:157], v[194:197], v[28:31]
	v_mfma_f32_16x16x32_bf16 v[24:27], v[162:165], v[194:197], v[24:27]
	v_mfma_f32_16x16x32_bf16 v[12:15], v[154:157], v[202:205], v[12:15]
	v_mfma_f32_16x16x32_bf16 v[8:11], v[162:165], v[202:205], v[8:11]
	s_setprio 0
	s_barrier
; #define PG8_STAGE(bufoff, gbase, voff) do { _Pragma("unroll") for (int _i = 0; _i < 2; ++_i) \
;         __builtin_amdgcn_global_load_lds((const unsigned*)((const char*)(gbase) + (voff)[_i]), (LAS unsigned*)(lds + (bufoff) + ldsw + _i * 8192), 16, 0, 0); } while (0)
; #define PG8_LDA(dst, b, h) do { _Pragma("unroll") for (int m = 0; m < 4; ++m) _Pragma("unroll") for (int k = 0; k < 2; ++k) dst[m][k] = *(const LAS bf16x8*)(lds + PG8_SA(b, h) + aoff + m * 2048 + k * 1024); } while (0)
; #define PG8_LDB(dst, b, h) do { _Pragma("unroll") for (int n = 0; n < 2; ++n) _Pragma("unroll") for (int k = 0; k < 2; ++k) dst[n][k] = *(const LAS bf16x8*)(lds + PG8_SB(b, h) + boff + n * 2048 + k * 1024); } while (0)
; #define PG8_MMA(ai, bj, At, Bt) do { __builtin_amdgcn_s_setprio(1); _Pragma("unroll") for (int m = 0; m < 4; ++m) _Pragma("unroll") for (int n = 0; n < 2; ++n) _Pragma("unroll") for (int k = 0; k < 2; ++k) \
;         acc[ai][bj][m][n] = __builtin_amdgcn_mfma_f32_16x16x32_bf16(Bt[n][k], At[m][k], acc[ai][bj][m][n], 0, 0, 0); __builtin_amdgcn_s_setprio(0); } while (0)
; #define PG8_WAIT_V(n) asm volatile("s_waitcnt vmcnt(" #n ")" ::: "memory")
; #define PG8_WAIT_L(n) asm volatile("s_waitcnt lgkmcnt(" #n ")" ::: "memory")
; #define PG8_BAR __builtin_amdgcn_s_barrier()
; #define PG8_SCHED __builtin_amdgcn_sched_barrier(0)
; template <class Epi>
; __device__ __forceinline__ void gemm_phase(LAS unsigned char* lds, const Gemm g, const StaticOrder& S, const Epi& E) {
;     ...
;             PG8_WAIT_V(6); PG8_BAR; PG8_MMA(1, 1, At, B1); PG8_BAR;
;             PG8_LDB(B0, 1, 0); PG8_SCHED; PG8_LDA(At, 1, 0); PG8_STAGE(PG8_SA(0, 1), a2 + hstepA, voffA);
;             PG8_WAIT_L(8); PG8_BAR; PG8_WAIT_L(0); PG8_MMA(0, 0, At, B0); PG8_BAR; PG8_SCHED;
;             PG8_LDB(B1, 1, 1); PG8_STAGE(PG8_SB(1, 0), b3, voffB);
;             PG8_BAR; PG8_WAIT_L(0); PG8_MMA(0, 1, At, B1); PG8_BAR;
;             PG8_LDA(At, 1, 1); PG8_STAGE(PG8_SA(1, 0), a3, voffA);
;             PG8_BAR; PG8_WAIT_L(0); PG8_MMA(1, 0, At, B0); PG8_BAR; PG8_SCHED;
	s_add_u32 s46, s22, 0x40000
	s_addc_u32 s47, s23, 0
	s_add_i32 s48, s38, s29
	v_lshl_add_u64 v[146:147], s[46:47], 0, v[130:131]
	s_mov_b32 m0, s48
	s_nop 0
	global_load_lds_dwordx4 v[146:147], off
	v_lshl_add_u64 v[146:147], s[46:47], 0, v[134:135]
	s_add_i32 m0, s48, 0x2000
	s_nop 0
	global_load_lds_dwordx4 v[146:147], off
	s_waitcnt vmcnt(6)
	s_barrier
	s_setprio 1
	v_mfma_f32_16x16x32_bf16 v[52:55], v[206:209], v[166:169], v[52:55]
	v_mfma_f32_16x16x32_bf16 v[48:51], v[214:217], v[166:169], v[48:51]
	v_mfma_f32_16x16x32_bf16 v[36:39], v[206:209], v[182:185], v[36:39]
	v_mfma_f32_16x16x32_bf16 v[32:35], v[214:217], v[182:185], v[32:35]
	v_mfma_f32_16x16x32_bf16 v[20:23], v[206:209], v[190:193], v[20:23]
	v_mfma_f32_16x16x32_bf16 v[16:19], v[214:217], v[190:193], v[16:19]
	v_mfma_f32_16x16x32_bf16 v[4:7], v[206:209], v[198:201], v[4:7]
	v_mfma_f32_16x16x32_bf16 v[0:3], v[214:217], v[198:201], v[0:3]
	v_mfma_f32_16x16x32_bf16 v[52:55], v[210:213], v[170:173], v[52:55]
	v_mfma_f32_16x16x32_bf16 v[48:51], v[218:221], v[170:173], v[48:51]
	v_mfma_f32_16x16x32_bf16 v[36:39], v[210:213], v[186:189], v[36:39]
	v_mfma_f32_16x16x32_bf16 v[32:35], v[218:221], v[186:189], v[32:35]
	v_mfma_f32_16x16x32_bf16 v[20:23], v[210:213], v[194:197], v[20:23]
	v_mfma_f32_16x16x32_bf16 v[16:19], v[218:221], v[194:197], v[16:19]
	v_mfma_f32_16x16x32_bf16 v[4:7], v[210:213], v[202:205], v[4:7]
	v_mfma_f32_16x16x32_bf16 v[0:3], v[218:221], v[202:205], v[0:3]
	s_setprio 0
	s_add_i32 s46, 0, 0x18000
	v_add_u32_e32 v162, s46, v175
	s_barrier
	ds_read_b128 v[146:149], v162
	ds_read_b128 v[154:157], v162 offset:1024
	ds_read_b128 v[158:161], v162 offset:2048
	ds_read_b128 v[162:165], v162 offset:3072
	s_add_u32 s24, s24, 0x40000
	s_addc_u32 s25, s25, 0
	s_mov_b32 m0, s31
	v_lshl_add_u64 v[206:207], s[24:25], 0, v[128:129]
	ds_read_b128 v[166:169], v178 offset:32768
	ds_read_b128 v[170:173], v178 offset:33792
	ds_read_b128 v[182:185], v178 offset:34816
	ds_read_b128 v[186:189], v178 offset:35840
	ds_read_b128 v[190:193], v178 offset:36864
	ds_read_b128 v[194:197], v178 offset:37888
	ds_read_b128 v[198:201], v178 offset:38912
	ds_read_b128 v[202:205], v178 offset:39936
	global_load_lds_dwordx4 v[206:207], off
	v_lshl_add_u64 v[206:207], s[24:25], 0, v[132:133]
	s_mov_b32 m0, s33
	s_nop 0
	global_load_lds_dwordx4 v[206:207], off
	s_waitcnt lgkmcnt(8)
	s_barrier
	s_waitcnt lgkmcnt(0)
	s_setprio 1
	s_waitcnt lgkmcnt(0)
	v_mfma_f32_16x16x32_bf16 v[124:127], v[146:149], v[166:169], v[124:127]
	v_mfma_f32_16x16x32_bf16 v[120:123], v[158:161], v[166:169], v[120:123]
	v_mfma_f32_16x16x32_bf16 v[108:111], v[146:149], v[182:185], v[108:111]
	v_mfma_f32_16x16x32_bf16 v[104:107], v[158:161], v[182:185], v[104:107]
	v_mfma_f32_16x16x32_bf16 v[92:95], v[146:149], v[190:193], v[92:95]
	v_mfma_f32_16x16x32_bf16 v[88:91], v[158:161], v[190:193], v[88:91]
	v_mfma_f32_16x16x32_bf16 v[76:79], v[146:149], v[198:201], v[76:79]
	v_mfma_f32_16x16x32_bf16 v[72:75], v[158:161], v[198:201], v[72:75]
	v_mfma_f32_16x16x32_bf16 v[124:127], v[154:157], v[170:173], v[124:127]
	v_mfma_f32_16x16x32_bf16 v[120:123], v[162:165], v[170:173], v[120:123]
	v_mfma_f32_16x16x32_bf16 v[108:111], v[154:157], v[186:189], v[108:111]
	v_mfma_f32_16x16x32_bf16 v[104:107], v[162:165], v[186:189], v[104:107]
	v_mfma_f32_16x16x32_bf16 v[92:95], v[154:157], v[194:197], v[92:95]
	v_mfma_f32_16x16x32_bf16 v[88:91], v[162:165], v[194:197], v[88:91]
	v_mfma_f32_16x16x32_bf16 v[76:79], v[154:157], v[202:205], v[76:79]
	v_mfma_f32_16x16x32_bf16 v[72:75], v[162:165], v[202:205], v[72:75]
	s_setprio 0
	s_barrier
	s_add_i32 s24, 0, 0x1c000
	s_add_i32 s25, s46, s29
	v_add_u32_e32 v181, s24, v175
	v_lshl_add_u64 v[150:151], v[150:151], 0, s[4:5]
	s_mov_b32 m0, s25
	ds_read_b128 v[206:209], v181
	ds_read_b128 v[210:213], v181 offset:1024
	ds_read_b128 v[214:217], v181 offset:2048
	ds_read_b128 v[218:221], v181 offset:3072
	global_load_lds_dwordx4 v[150:151], off
	v_lshl_add_u64 v[150:151], v[222:223], 0, s[4:5]
	s_add_i32 m0, s25, 0x2000
	s_nop 0
	global_load_lds_dwordx4 v[150:151], off
	s_barrier
	s_waitcnt lgkmcnt(0)
	s_setprio 1
	s_waitcnt lgkmcnt(0)
	v_mfma_f32_16x16x32_bf16 v[116:119], v[206:209], v[166:169], v[116:119]
	v_mfma_f32_16x16x32_bf16 v[112:115], v[214:217], v[166:169], v[112:115]
	v_mfma_f32_16x16x32_bf16 v[100:103], v[206:209], v[182:185], v[100:103]
	v_mfma_f32_16x16x32_bf16 v[96:99], v[214:217], v[182:185], v[96:99]
	v_mfma_f32_16x16x32_bf16 v[84:87], v[206:209], v[190:193], v[84:87]
	v_mfma_f32_16x16x32_bf16 v[80:83], v[214:217], v[190:193], v[80:83]
	v_mfma_f32_16x16x32_bf16 v[68:71], v[206:209], v[198:201], v[68:71]
	v_mfma_f32_16x16x32_bf16 v[64:67], v[214:217], v[198:201], v[64:67]
	v_mfma_f32_16x16x32_bf16 v[116:119], v[210:213], v[170:173], v[116:119]
	v_mfma_f32_16x16x32_bf16 v[112:115], v[218:221], v[170:173], v[112:115]
	v_mfma_f32_16x16x32_bf16 v[100:103], v[210:213], v[186:189], v[100:103]
	v_mfma_f32_16x16x32_bf16 v[96:99], v[218:221], v[186:189], v[96:99]
	v_mfma_f32_16x16x32_bf16 v[84:87], v[210:213], v[194:197], v[84:87]
	v_mfma_f32_16x16x32_bf16 v[80:83], v[218:221], v[194:197], v[80:83]
	v_mfma_f32_16x16x32_bf16 v[68:71], v[210:213], v[202:205], v[68:71]
	v_mfma_f32_16x16x32_bf16 v[64:67], v[218:221], v[202:205], v[64:67]
	s_setprio 0
	s_mov_b32 m0, s35
	v_lshl_add_u64 v[150:151], v[224:225], 0, s[4:5]
	s_barrier
	ds_read_b128 v[166:169], v178 offset:49152
	ds_read_b128 v[170:173], v178 offset:50176
	ds_read_b128 v[182:185], v178 offset:51200
	ds_read_b128 v[186:189], v178 offset:52224
	ds_read_b128 v[190:193], v178 offset:53248
	ds_read_b128 v[194:197], v178 offset:54272
	ds_read_b128 v[198:201], v178 offset:55296
	ds_read_b128 v[202:205], v178 offset:56320
	global_load_lds_dwordx4 v[150:151], off
	v_lshl_add_u64 v[150:151], v[226:227], 0, s[4:5]
	s_mov_b32 m0, s36
	s_nop 0
	global_load_lds_dwordx4 v[150:151], off
	s_barrier
; __device__ __forceinline__ unsigned pk2(float lo, float hi) { const f32x2 v = (f32x2){lo, hi}; const bf16x2_t b = __builtin_convertvector(v, bf16x2_t); return __builtin_bit_cast(unsigned, b); }
; #define PG8_STAGE(bufoff, gbase, voff) do { _Pragma("unroll") for (int _i = 0; _i < 2; ++_i) \
;         __builtin_amdgcn_global_load_lds((const unsigned*)((const char*)(gbase) + (voff)[_i]), (LAS unsigned*)(lds + (bufoff) + ldsw + _i * 8192), 16, 0, 0); } while (0)
; #define PG8_MMA(ai, bj, At, Bt) do { __builtin_amdgcn_s_setprio(1); _Pragma("unroll") for (int m = 0; m < 4; ++m) _Pragma("unroll") for (int n = 0; n < 2; ++n) _Pragma("unroll") for (int k = 0; k < 2; ++k) \
;         acc[ai][bj][m][n] = __builtin_amdgcn_mfma_f32_16x16x32_bf16(Bt[n][k], At[m][k], acc[ai][bj][m][n], 0, 0, 0); __builtin_amdgcn_s_setprio(0); } while (0)
; #define PG8_WAIT_V(n) asm volatile("s_waitcnt vmcnt(" #n ")" ::: "memory")
; #define PG8_WAIT_L(n) asm volatile("s_waitcnt lgkmcnt(" #n ")" ::: "memory")
;     __device__ __forceinline__ void operator()(const f32x4 (&acc)[2][2][4][2], const Unit& u, int wr, int wc, int fr, int fq, const float (&)[8]) const {
;     ...
;         const int col0 = u.pn * BM + wc * 32 + 8 * fq;
; #pragma unroll
;         for (int ai = 0; ai < 2; ++ai)
; #pragma unroll
;             for (int m = 0; m < 4; ++m) { const int row = row0 + ai * HALF + m * 16; const float rs = rsqrtf(ep[ai * 4 + m] * (1.0f / 1024.0f) + EPS);
;                 u16* rowp = O + (size_t)row * ldc + col0;
; #pragma unroll
;                 for (int bj = 0; bj < 2; ++bj) { f32x4 v0 = acc[ai][bj][m][0] * rs, v1 = acc[ai][bj][m][1] * rs;
;                     if (ACT == 1) {
; #pragma unroll
;                         for (int j = 0; j < 4; ++j) { const float a0 = fmaxf(v0[j], 0.f), a1 = fmaxf(v1[j], 0.f); v0[j] = a0 * a0; v1[j] = a1 * a1; } }
;                     u32x4 w; w.x = pk2(v0[0], v0[1]); w.y = pk2(v0[2], v0[3]); w.z = pk2(v1[0], v1[1]); w.w = pk2(v1[2], v1[3]);
;                     *(u32x4*)(rowp + bj * HALF) = w; } }
; template <class Epi>
; __device__ __forceinline__ void gemm_phase(LAS unsigned char* lds, const Gemm g, const StaticOrder& S, const Epi& E) {
;     ...
;             PG8_BAR; PG8_WAIT_L(0); PG8_MMA(1, 0, At, B0); PG8_BAR; PG8_SCHED;
;             PG8_STAGE(PG8_SB(1, 1), b3 + hstepB, voffB);
;             PG8_WAIT_V(6); PG8_BAR; PG8_MMA(1, 1, At, B1); PG8_BAR;
	s_waitcnt lgkmcnt(0)
	s_setprio 1
	s_waitcnt lgkmcnt(0)
	v_mfma_f32_16x16x32_bf16 v[60:63], v[146:149], v[166:169], v[60:63]
	v_mfma_f32_16x16x32_bf16 v[56:59], v[158:161], v[166:169], v[56:59]
	v_mfma_f32_16x16x32_bf16 v[44:47], v[146:149], v[182:185], v[44:47]
	v_mfma_f32_16x16x32_bf16 v[40:43], v[158:161], v[182:185], v[40:43]
	v_mfma_f32_16x16x32_bf16 v[28:31], v[146:149], v[190:193], v[28:31]
	v_mfma_f32_16x16x32_bf16 v[24:27], v[158:161], v[190:193], v[24:27]
	v_mfma_f32_16x16x32_bf16 v[12:15], v[146:149], v[198:201], v[12:15]
	v_mfma_f32_16x16x32_bf16 v[8:11], v[158:161], v[198:201], v[8:11]
	v_mfma_f32_16x16x32_bf16 v[60:63], v[154:157], v[170:173], v[60:63]
	v_mfma_f32_16x16x32_bf16 v[56:59], v[162:165], v[170:173], v[56:59]
	v_mfma_f32_16x16x32_bf16 v[44:47], v[154:157], v[186:189], v[44:47]
	v_mfma_f32_16x16x32_bf16 v[40:43], v[162:165], v[186:189], v[40:43]
	v_mfma_f32_16x16x32_bf16 v[28:31], v[154:157], v[194:197], v[28:31]
	v_mfma_f32_16x16x32_bf16 v[24:27], v[162:165], v[194:197], v[24:27]
	v_mfma_f32_16x16x32_bf16 v[12:15], v[154:157], v[202:205], v[12:15]
	v_mfma_f32_16x16x32_bf16 v[8:11], v[162:165], v[202:205], v[8:11]
	s_setprio 0
	s_barrier
	s_add_u32 s22, s22, 0x40080
	s_addc_u32 s23, s23, 0
	s_add_i32 s24, s24, s29
	v_lshl_add_u64 v[146:147], s[22:23], 0, v[130:131]
	s_mov_b32 m0, s24
	s_nop 0
	global_load_lds_dwordx4 v[146:147], off
	v_lshl_add_u64 v[146:147], s[22:23], 0, v[134:135]
	s_add_i32 m0, s24, 0x2000
	s_nop 0
	global_load_lds_dwordx4 v[146:147], off
	s_waitcnt vmcnt(6)
	s_barrier
	s_setprio 1
	v_mfma_f32_16x16x32_bf16 v[52:55], v[206:209], v[166:169], v[52:55]
	v_mfma_f32_16x16x32_bf16 v[48:51], v[214:217], v[166:169], v[48:51]
	v_mfma_f32_16x16x32_bf16 v[36:39], v[206:209], v[182:185], v[36:39]
	v_mfma_f32_16x16x32_bf16 v[32:35], v[214:217], v[182:185], v[32:35]
	v_mfma_f32_16x16x32_bf16 v[20:23], v[206:209], v[190:193], v[20:23]
	v_mfma_f32_16x16x32_bf16 v[16:19], v[214:217], v[190:193], v[16:19]
	v_mfma_f32_16x16x32_bf16 v[4:7], v[206:209], v[198:201], v[4:7]
	v_mfma_f32_16x16x32_bf16 v[0:3], v[214:217], v[198:201], v[0:3]
	v_mfma_f32_16x16x32_bf16 v[52:55], v[210:213], v[170:173], v[52:55]
	v_mfma_f32_16x16x32_bf16 v[48:51], v[218:221], v[170:173], v[48:51]
	v_mfma_f32_16x16x32_bf16 v[36:39], v[210:213], v[186:189], v[36:39]
	v_mfma_f32_16x16x32_bf16 v[32:35], v[218:221], v[186:189], v[32:35]
	v_mfma_f32_16x16x32_bf16 v[20:23], v[210:213], v[194:197], v[20:23]
	v_mfma_f32_16x16x32_bf16 v[16:19], v[218:221], v[194:197], v[16:19]
	v_mfma_f32_16x16x32_bf16 v[4:7], v[210:213], v[202:205], v[4:7]
	v_mfma_f32_16x16x32_bf16 v[0:3], v[218:221], v[202:205], v[0:3]
	s_setprio 0
	s_add_i32 s45, s45, 2
	s_add_u32 s20, s20, 0x100
	s_addc_u32 s21, s21, 0
	s_add_u32 s43, s43, 0x100
	s_addc_u32 s44, s44, 0
	s_cmp_gt_u32 s45, 13
	s_barrier
	s_cbranch_scc0 .LBB0_770
	s_bfe_u32 vcc_lo, s18, 0x20003
	s_lshl_b32 vcc_lo, vcc_lo, 10
	s_add_i32 vcc_lo, vcc_lo, 0x20010
	v_lshl_add_u32 v236, v174, 2, vcc_lo
	ds_read_b32 v228, v236
	ds_read_b32 v229, v236 offset:64
	ds_read_b32 v230, v236 offset:128
	ds_read_b32 v231, v236 offset:192
	ds_read_b32 v232, v236 offset:512
	ds_read_b32 v233, v236 offset:576
	ds_read_b32 v234, v236 offset:640
	ds_read_b32 v235, v236 offset:704
	s_waitcnt lgkmcnt(0)
	v_lshl_add_u32 v148, s18, 8, v174
	v_ashrrev_i32_e32 v149, 31, v148
	v_or_b32_e32 v172, 16, v148
	v_ashrrev_i32_e32 v173, 31, v172
	v_or_b32_e32 v168, 32, v148
	v_or_b32_e32 v164, 48, v148
	v_ashrrev_i32_e32 v169, 31, v168
	v_ashrrev_i32_e32 v165, 31, v164
	v_add_u32_e32 v162, 0x80, v148
	v_add_u32_e32 v156, 0x90, v148
	v_ashrrev_i32_e32 v163, 31, v162
	v_ashrrev_i32_e32 v157, 31, v156
	v_add_u32_e32 v150, 0xa0, v148
	v_ashrrev_i32_e32 v151, 31, v150
	v_add_u32_e32 v146, 0xb0, v148
	v_ashrrev_i32_e32 v147, 31, v146
	v_lshl_or_b32 v166, s40, 8, v176
	v_ashrrev_i32_e32 v167, 31, v166
	v_lshlrev_b64 v[170:171], 13, v[148:149]
	v_lshlrev_b64 v[148:149], 1, v[166:167]
	v_lshl_add_u64 v[166:167], s[96:97], 0, v[170:171]
	v_lshl_add_u64 v[212:213], v[166:167], 0, v[148:149]
	s_mov_b32 s40, s10
	s_mov_b32 s18, s12
	s_mov_b64 s[22:23], s[16:17]
	s_mov_b64 s[20:21], s[14:15]
	s_waitcnt vmcnt(8)
	s_waitcnt lgkmcnt(0)
	s_waitcnt lgkmcnt(0)
	v_mov_b32_e32 v184, v228
	v_pk_mul_f32 v[120:121], v[120:121], v[184:185] op_sel_hi:[1,0]
	v_pk_mul_f32 v[126:127], v[126:127], v[184:185] op_sel_hi:[1,0]
	v_pk_mul_f32 v[124:125], v[124:125], v[184:185] op_sel_hi:[1,0]
	v_pk_mul_f32 v[122:123], v[122:123], v[184:185] op_sel_hi:[1,0]
	v_max_f32_e32 v120, 0, v120
	v_max_f32_e32 v121, 0, v121
	v_max_f32_e32 v124, 0, v124
	v_max_f32_e32 v125, 0, v125
	v_pk_mul_f32 v[190:191], v[120:121], v[120:121]
	v_max_f32_e32 v120, 0, v126
	v_max_f32_e32 v122, 0, v122
	v_max_f32_e32 v121, 0, v127
	v_max_f32_e32 v123, 0, v123
	v_pk_mul_f32 v[124:125], v[124:125], v[124:125]
	v_pk_mul_f32 v[126:127], v[120:121], v[120:121]
	v_pk_mul_f32 v[194:195], v[122:123], v[122:123]
	v_pk_mul_f32 v[114:115], v[114:115], v[184:185] op_sel_hi:[1,0]
	v_cvt_pk_bf16_f32 v120, v124, v125
	v_cvt_pk_bf16_f32 v121, v126, v127
	v_cvt_pk_bf16_f32 v122, v190, v191
	v_cvt_pk_bf16_f32 v123, v194, v195
	v_pk_mul_f32 v[116:117], v[116:117], v[184:185] op_sel_hi:[1,0]
	v_pk_mul_f32 v[112:113], v[112:113], v[184:185] op_sel_hi:[1,0]
	v_max_f32_e32 v114, 0, v114
	v_max_f32_e32 v115, 0, v115
	global_store_dwordx4 v[212:213], v[120:123], off
	v_pk_mul_f32 v[118:119], v[118:119], v[184:185] op_sel_hi:[1,0]
	v_max_f32_e32 v116, 0, v116
	v_max_f32_e32 v112, 0, v112
	v_max_f32_e32 v117, 0, v117
	v_max_f32_e32 v113, 0, v113
	v_pk_mul_f32 v[122:123], v[114:115], v[114:115]
	v_pk_mul_f32 v[116:117], v[116:117], v[116:117]
; __device__ __forceinline__ unsigned pk2(float lo, float hi) { const f32x2 v = (f32x2){lo, hi}; const bf16x2_t b = __builtin_convertvector(v, bf16x2_t); return __builtin_bit_cast(unsigned, b); }
;     __device__ __forceinline__ void operator()(const f32x4 (&acc)[2][2][4][2], const Unit& u, int wr, int wc, int fr, int fq, const float (&)[8]) const {
;     ...
;             for (int m = 0; m < 4; ++m) { const int row = row0 + ai * HALF + m * 16; const float rs = rsqrtf(ep[ai * 4 + m] * (1.0f / 1024.0f) + EPS);
;                 u16* rowp = O + (size_t)row * ldc + col0;
; #pragma unroll
;                 for (int bj = 0; bj < 2; ++bj) { f32x4 v0 = acc[ai][bj][m][0] * rs, v1 = acc[ai][bj][m][1] * rs;
;                     if (ACT == 1) {
; #pragma unroll
;                         for (int j = 0; j < 4; ++j) { const float a0 = fmaxf(v0[j], 0.f), a1 = fmaxf(v1[j], 0.f); v0[j] = a0 * a0; v1[j] = a1 * a1; } }
;                     u32x4 w; w.x = pk2(v0[0], v0[1]); w.y = pk2(v0[2], v0[3]); w.z = pk2(v1[0], v1[1]); w.w = pk2(v1[2], v1[3]);
;                     *(u32x4*)(rowp + bj * HALF) = w; } }
	v_pk_mul_f32 v[120:121], v[112:113], v[112:113]
	v_max_f32_e32 v112, 0, v118
	v_max_f32_e32 v113, 0, v119
	v_pk_mul_f32 v[118:119], v[112:113], v[112:113]
	v_cvt_pk_bf16_f32 v112, v116, v117
	v_cvt_pk_bf16_f32 v113, v118, v119
	v_cvt_pk_bf16_f32 v114, v120, v121
	v_cvt_pk_bf16_f32 v115, v122, v123
	global_store_dwordx4 v[212:213], v[112:115], off offset:256
	s_nop 1
	v_mov_b32_e32 v112, v229
	v_pk_mul_f32 v[104:105], v[104:105], v[112:113] op_sel_hi:[1,0]
	v_pk_mul_f32 v[110:111], v[110:111], v[112:113] op_sel_hi:[1,0]
	v_pk_mul_f32 v[108:109], v[108:109], v[112:113] op_sel_hi:[1,0]
	v_pk_mul_f32 v[106:107], v[106:107], v[112:113] op_sel_hi:[1,0]
	v_max_f32_e32 v104, 0, v104
	v_max_f32_e32 v105, 0, v105
	v_lshlrev_b64 v[114:115], 13, v[172:173]
	v_max_f32_e32 v108, 0, v108
	v_max_f32_e32 v109, 0, v109
	v_pk_mul_f32 v[116:117], v[104:105], v[104:105]
	v_max_f32_e32 v104, 0, v110
	v_max_f32_e32 v106, 0, v106
	v_max_f32_e32 v105, 0, v111
	v_max_f32_e32 v107, 0, v107
	v_lshl_add_u64 v[114:115], s[96:97], 0, v[114:115]
	v_pk_mul_f32 v[108:109], v[108:109], v[108:109]
	v_pk_mul_f32 v[110:111], v[104:105], v[104:105]
	v_pk_mul_f32 v[118:119], v[106:107], v[106:107]
	v_pk_mul_f32 v[96:97], v[96:97], v[112:113] op_sel_hi:[1,0]
	v_lshl_add_u64 v[114:115], v[114:115], 0, v[148:149]
	v_cvt_pk_bf16_f32 v104, v108, v109
	v_cvt_pk_bf16_f32 v105, v110, v111
	v_cvt_pk_bf16_f32 v106, v116, v117
	v_cvt_pk_bf16_f32 v107, v118, v119
	v_pk_mul_f32 v[102:103], v[102:103], v[112:113] op_sel_hi:[1,0]
	v_max_f32_e32 v96, 0, v96
	v_max_f32_e32 v97, 0, v97
	global_store_dwordx4 v[114:115], v[104:107], off
	v_pk_mul_f32 v[100:101], v[100:101], v[112:113] op_sel_hi:[1,0]
	v_pk_mul_f32 v[98:99], v[98:99], v[112:113] op_sel_hi:[1,0]
	v_pk_mul_f32 v[104:105], v[96:97], v[96:97]
	v_max_f32_e32 v96, 0, v102
	v_max_f32_e32 v97, 0, v103
	v_max_f32_e32 v100, 0, v100
	v_max_f32_e32 v101, 0, v101
	v_pk_mul_f32 v[100:101], v[100:101], v[100:101]
	v_pk_mul_f32 v[108:109], v[96:97], v[96:97]
	v_cvt_pk_bf16_f32 v96, v100, v101
	s_waitcnt lgkmcnt(0)
	v_max_f32_e32 v98, 0, v98
	v_max_f32_e32 v99, 0, v99
	v_pk_mul_f32 v[110:111], v[98:99], v[98:99]
	v_cvt_pk_bf16_f32 v97, v108, v109
	v_cvt_pk_bf16_f32 v98, v104, v105
	v_cvt_pk_bf16_f32 v99, v110, v111
	global_store_dwordx4 v[114:115], v[96:99], off offset:256
	s_waitcnt lgkmcnt(0)
	s_nop 0
	s_nop 0
	s_nop 0
	s_nop 1
	v_lshlrev_b64 v[98:99], 13, v[168:169]
	v_lshl_add_u64 v[98:99], s[96:97], 0, v[98:99]
	v_lshl_add_u64 v[98:99], v[98:99], 0, v[148:149]
	v_mov_b32_e32 v100, v230
	v_pk_mul_f32 v[88:89], v[88:89], v[100:101] op_sel_hi:[1,0]
	v_pk_mul_f32 v[94:95], v[94:95], v[100:101] op_sel_hi:[1,0]
	v_pk_mul_f32 v[92:93], v[92:93], v[100:101] op_sel_hi:[1,0]
	v_pk_mul_f32 v[90:91], v[90:91], v[100:101] op_sel_hi:[1,0]
	v_max_f32_e32 v88, 0, v88
	v_max_f32_e32 v89, 0, v89
	v_max_f32_e32 v92, 0, v92
	v_max_f32_e32 v93, 0, v93
	v_pk_mul_f32 v[102:103], v[88:89], v[88:89]
	v_max_f32_e32 v88, 0, v94
	v_max_f32_e32 v90, 0, v90
	v_max_f32_e32 v89, 0, v95
	v_max_f32_e32 v91, 0, v91
	v_pk_mul_f32 v[92:93], v[92:93], v[92:93]
	v_pk_mul_f32 v[94:95], v[88:89], v[88:89]
	v_pk_mul_f32 v[104:105], v[90:91], v[90:91]
	v_pk_mul_f32 v[82:83], v[82:83], v[100:101] op_sel_hi:[1,0]
	v_cvt_pk_bf16_f32 v88, v92, v93
	v_cvt_pk_bf16_f32 v89, v94, v95
	v_cvt_pk_bf16_f32 v90, v102, v103
	v_cvt_pk_bf16_f32 v91, v104, v105
	v_pk_mul_f32 v[84:85], v[84:85], v[100:101] op_sel_hi:[1,0]
	v_pk_mul_f32 v[80:81], v[80:81], v[100:101] op_sel_hi:[1,0]
	v_max_f32_e32 v82, 0, v82
	v_max_f32_e32 v83, 0, v83
	global_store_dwordx4 v[98:99], v[88:91], off
	v_pk_mul_f32 v[86:87], v[86:87], v[100:101] op_sel_hi:[1,0]
	v_max_f32_e32 v84, 0, v84
	v_max_f32_e32 v80, 0, v80
	v_max_f32_e32 v85, 0, v85
	v_max_f32_e32 v81, 0, v81
	v_pk_mul_f32 v[90:91], v[82:83], v[82:83]
	v_pk_mul_f32 v[84:85], v[84:85], v[84:85]
	v_pk_mul_f32 v[88:89], v[80:81], v[80:81]
	v_max_f32_e32 v80, 0, v86
	v_max_f32_e32 v81, 0, v87
	v_pk_mul_f32 v[86:87], v[80:81], v[80:81]
	v_cvt_pk_bf16_f32 v80, v84, v85
	v_cvt_pk_bf16_f32 v81, v86, v87
	v_cvt_pk_bf16_f32 v82, v88, v89
	v_cvt_pk_bf16_f32 v83, v90, v91
	global_store_dwordx4 v[98:99], v[80:83], off offset:256
	s_nop 1
	v_mov_b32_e32 v80, v231
	v_pk_mul_f32 v[72:73], v[72:73], v[80:81] op_sel_hi:[1,0]
	v_pk_mul_f32 v[78:79], v[78:79], v[80:81] op_sel_hi:[1,0]
	v_pk_mul_f32 v[76:77], v[76:77], v[80:81] op_sel_hi:[1,0]
	v_pk_mul_f32 v[74:75], v[74:75], v[80:81] op_sel_hi:[1,0]
	v_max_f32_e32 v72, 0, v72
	v_max_f32_e32 v73, 0, v73
	v_lshlrev_b64 v[82:83], 13, v[164:165]
	v_max_f32_e32 v76, 0, v76
	v_max_f32_e32 v77, 0, v77
	v_pk_mul_f32 v[84:85], v[72:73], v[72:73]
	v_max_f32_e32 v72, 0, v78
	v_max_f32_e32 v74, 0, v74
	v_max_f32_e32 v73, 0, v79
	v_max_f32_e32 v75, 0, v75
	v_lshl_add_u64 v[82:83], s[96:97], 0, v[82:83]
	v_pk_mul_f32 v[76:77], v[76:77], v[76:77]
	v_pk_mul_f32 v[78:79], v[72:73], v[72:73]
	v_pk_mul_f32 v[86:87], v[74:75], v[74:75]
	v_pk_mul_f32 v[64:65], v[64:65], v[80:81] op_sel_hi:[1,0]
	v_lshl_add_u64 v[82:83], v[82:83], 0, v[148:149]
	v_cvt_pk_bf16_f32 v72, v76, v77
	v_cvt_pk_bf16_f32 v73, v78, v79
	v_cvt_pk_bf16_f32 v74, v84, v85
	v_cvt_pk_bf16_f32 v75, v86, v87
	v_pk_mul_f32 v[70:71], v[70:71], v[80:81] op_sel_hi:[1,0]
	v_max_f32_e32 v64, 0, v64
	v_max_f32_e32 v65, 0, v65
	global_store_dwordx4 v[82:83], v[72:75], off
	v_pk_mul_f32 v[68:69], v[68:69], v[80:81] op_sel_hi:[1,0]
	v_pk_mul_f32 v[66:67], v[66:67], v[80:81] op_sel_hi:[1,0]
	v_pk_mul_f32 v[72:73], v[64:65], v[64:65]
	v_max_f32_e32 v64, 0, v70
	v_max_f32_e32 v65, 0, v71
	v_max_f32_e32 v68, 0, v68
	v_max_f32_e32 v69, 0, v69
	v_pk_mul_f32 v[68:69], v[68:69], v[68:69]
	v_pk_mul_f32 v[76:77], v[64:65], v[64:65]
	v_cvt_pk_bf16_f32 v64, v68, v69
	s_waitcnt lgkmcnt(0)
; __device__ __forceinline__ unsigned pk2(float lo, float hi) { const f32x2 v = (f32x2){lo, hi}; const bf16x2_t b = __builtin_convertvector(v, bf16x2_t); return __builtin_bit_cast(unsigned, b); }
;     __device__ __forceinline__ void operator()(const f32x4 (&acc)[2][2][4][2], const Unit& u, int wr, int wc, int fr, int fq, const float (&)[8]) const {
;     ...
;             for (int m = 0; m < 4; ++m) { const int row = row0 + ai * HALF + m * 16; const float rs = rsqrtf(ep[ai * 4 + m] * (1.0f / 1024.0f) + EPS);
;                 u16* rowp = O + (size_t)row * ldc + col0;
; #pragma unroll
;                 for (int bj = 0; bj < 2; ++bj) { f32x4 v0 = acc[ai][bj][m][0] * rs, v1 = acc[ai][bj][m][1] * rs;
;                     if (ACT == 1) {
; #pragma unroll
;                         for (int j = 0; j < 4; ++j) { const float a0 = fmaxf(v0[j], 0.f), a1 = fmaxf(v1[j], 0.f); v0[j] = a0 * a0; v1[j] = a1 * a1; } }
;                     u32x4 w; w.x = pk2(v0[0], v0[1]); w.y = pk2(v0[2], v0[3]); w.z = pk2(v1[0], v1[1]); w.w = pk2(v1[2], v1[3]);
;                     *(u32x4*)(rowp + bj * HALF) = w; } }
	v_max_f32_e32 v66, 0, v66
	v_max_f32_e32 v67, 0, v67
	v_pk_mul_f32 v[78:79], v[66:67], v[66:67]
	v_cvt_pk_bf16_f32 v65, v76, v77
	v_cvt_pk_bf16_f32 v66, v72, v73
	v_cvt_pk_bf16_f32 v67, v78, v79
	global_store_dwordx4 v[82:83], v[64:67], off offset:256
	s_waitcnt lgkmcnt(0)
	s_nop 0
	s_nop 0
	s_nop 0
	s_nop 1
	v_lshlrev_b64 v[66:67], 13, v[162:163]
	v_lshl_add_u64 v[66:67], s[96:97], 0, v[66:67]
	v_lshl_add_u64 v[66:67], v[66:67], 0, v[148:149]
	v_mov_b32_e32 v68, v232
	v_pk_mul_f32 v[56:57], v[56:57], v[68:69] op_sel_hi:[1,0]
	v_pk_mul_f32 v[62:63], v[62:63], v[68:69] op_sel_hi:[1,0]
	v_pk_mul_f32 v[60:61], v[60:61], v[68:69] op_sel_hi:[1,0]
	v_pk_mul_f32 v[58:59], v[58:59], v[68:69] op_sel_hi:[1,0]
	v_max_f32_e32 v56, 0, v56
	v_max_f32_e32 v57, 0, v57
	v_max_f32_e32 v60, 0, v60
	v_max_f32_e32 v61, 0, v61
	v_pk_mul_f32 v[70:71], v[56:57], v[56:57]
	v_max_f32_e32 v56, 0, v62
	v_max_f32_e32 v58, 0, v58
	v_max_f32_e32 v57, 0, v63
	v_max_f32_e32 v59, 0, v59
	v_pk_mul_f32 v[60:61], v[60:61], v[60:61]
	v_pk_mul_f32 v[62:63], v[56:57], v[56:57]
	v_pk_mul_f32 v[72:73], v[58:59], v[58:59]
	v_pk_mul_f32 v[50:51], v[50:51], v[68:69] op_sel_hi:[1,0]
	v_cvt_pk_bf16_f32 v56, v60, v61
	v_cvt_pk_bf16_f32 v57, v62, v63
	v_cvt_pk_bf16_f32 v58, v70, v71
	v_cvt_pk_bf16_f32 v59, v72, v73
	v_pk_mul_f32 v[52:53], v[52:53], v[68:69] op_sel_hi:[1,0]
	v_pk_mul_f32 v[48:49], v[48:49], v[68:69] op_sel_hi:[1,0]
	v_max_f32_e32 v50, 0, v50
	v_max_f32_e32 v51, 0, v51
	global_store_dwordx4 v[66:67], v[56:59], off
	v_pk_mul_f32 v[54:55], v[54:55], v[68:69] op_sel_hi:[1,0]
	v_max_f32_e32 v52, 0, v52
	v_max_f32_e32 v48, 0, v48
	v_max_f32_e32 v53, 0, v53
	v_max_f32_e32 v49, 0, v49
	v_pk_mul_f32 v[58:59], v[50:51], v[50:51]
	v_pk_mul_f32 v[52:53], v[52:53], v[52:53]
	v_pk_mul_f32 v[56:57], v[48:49], v[48:49]
	v_max_f32_e32 v48, 0, v54
	v_max_f32_e32 v49, 0, v55
	v_pk_mul_f32 v[54:55], v[48:49], v[48:49]
	v_cvt_pk_bf16_f32 v48, v52, v53
	v_cvt_pk_bf16_f32 v49, v54, v55
	v_cvt_pk_bf16_f32 v50, v56, v57
	v_cvt_pk_bf16_f32 v51, v58, v59
	global_store_dwordx4 v[66:67], v[48:51], off offset:256
	s_nop 1
	v_mov_b32_e32 v48, v233
	v_pk_mul_f32 v[40:41], v[40:41], v[48:49] op_sel_hi:[1,0]
	v_pk_mul_f32 v[46:47], v[46:47], v[48:49] op_sel_hi:[1,0]
	v_pk_mul_f32 v[44:45], v[44:45], v[48:49] op_sel_hi:[1,0]
	v_pk_mul_f32 v[42:43], v[42:43], v[48:49] op_sel_hi:[1,0]
	v_max_f32_e32 v40, 0, v40
	v_max_f32_e32 v41, 0, v41
	v_lshlrev_b64 v[50:51], 13, v[156:157]
	v_max_f32_e32 v44, 0, v44
	v_max_f32_e32 v45, 0, v45
	v_pk_mul_f32 v[52:53], v[40:41], v[40:41]
	v_max_f32_e32 v40, 0, v46
	v_max_f32_e32 v42, 0, v42
	v_max_f32_e32 v41, 0, v47
	v_max_f32_e32 v43, 0, v43
	v_lshl_add_u64 v[50:51], s[96:97], 0, v[50:51]
	v_pk_mul_f32 v[44:45], v[44:45], v[44:45]
	v_pk_mul_f32 v[46:47], v[40:41], v[40:41]
	v_pk_mul_f32 v[54:55], v[42:43], v[42:43]
	v_pk_mul_f32 v[32:33], v[32:33], v[48:49] op_sel_hi:[1,0]
	v_lshl_add_u64 v[50:51], v[50:51], 0, v[148:149]
	v_cvt_pk_bf16_f32 v236, v44, v45
	v_cvt_pk_bf16_f32 v237, v46, v47
	v_cvt_pk_bf16_f32 v238, v52, v53
	v_cvt_pk_bf16_f32 v239, v54, v55
	v_pk_mul_f32 v[38:39], v[38:39], v[48:49] op_sel_hi:[1,0]
	v_max_f32_e32 v32, 0, v32
	v_max_f32_e32 v33, 0, v33
	v_mov_b64_e32 v[248:249], v[50:51]
	v_pk_mul_f32 v[36:37], v[36:37], v[48:49] op_sel_hi:[1,0]
	v_pk_mul_f32 v[34:35], v[34:35], v[48:49] op_sel_hi:[1,0]
	v_pk_mul_f32 v[40:41], v[32:33], v[32:33]
	v_max_f32_e32 v32, 0, v38
	v_max_f32_e32 v33, 0, v39
	v_max_f32_e32 v36, 0, v36
	v_max_f32_e32 v37, 0, v37
	v_pk_mul_f32 v[36:37], v[36:37], v[36:37]
	v_pk_mul_f32 v[44:45], v[32:33], v[32:33]
	v_cvt_pk_bf16_f32 v240, v36, v37
	s_waitcnt lgkmcnt(0)
	v_max_f32_e32 v34, 0, v34
	v_max_f32_e32 v35, 0, v35
	v_pk_mul_f32 v[46:47], v[34:35], v[34:35]
	v_cvt_pk_bf16_f32 v241, v44, v45
	v_cvt_pk_bf16_f32 v242, v40, v41
	v_cvt_pk_bf16_f32 v243, v46, v47
	s_waitcnt lgkmcnt(0)
; __device__ __forceinline__ unsigned pk2(float lo, float hi) { const f32x2 v = (f32x2){lo, hi}; const bf16x2_t b = __builtin_convertvector(v, bf16x2_t); return __builtin_bit_cast(unsigned, b); }
;     __device__ __forceinline__ void operator()(const f32x4 (&acc)[2][2][4][2], const Unit& u, int wr, int wc, int fr, int fq, const float (&)[8]) const {
;     ...
;             for (int m = 0; m < 4; ++m) { const int row = row0 + ai * HALF + m * 16; const float rs = rsqrtf(ep[ai * 4 + m] * (1.0f / 1024.0f) + EPS);
;                 u16* rowp = O + (size_t)row * ldc + col0;
; #pragma unroll
;                 for (int bj = 0; bj < 2; ++bj) { f32x4 v0 = acc[ai][bj][m][0] * rs, v1 = acc[ai][bj][m][1] * rs;
;                     if (ACT == 1) {
; #pragma unroll
;                         for (int j = 0; j < 4; ++j) { const float a0 = fmaxf(v0[j], 0.f), a1 = fmaxf(v1[j], 0.f); v0[j] = a0 * a0; v1[j] = a1 * a1; } }
;                     u32x4 w; w.x = pk2(v0[0], v0[1]); w.y = pk2(v0[2], v0[3]); w.z = pk2(v1[0], v1[1]); w.w = pk2(v1[2], v1[3]);
;                     *(u32x4*)(rowp + bj * HALF) = w; } }
; template <class Epi>
; __device__ __forceinline__ void gemm_phase(LAS unsigned char* lds, const Gemm g, const StaticOrder& S, const Epi& E) {
;     ...
;         if (!has_next) break;
	s_nop 0
	s_nop 0
	s_nop 0
	s_nop 1
	v_lshlrev_b64 v[34:35], 13, v[150:151]
	v_lshl_add_u64 v[34:35], s[96:97], 0, v[34:35]
	v_lshl_add_u64 v[34:35], v[34:35], 0, v[148:149]
	v_mov_b32_e32 v36, v234
	v_pk_mul_f32 v[24:25], v[24:25], v[36:37] op_sel_hi:[1,0]
	v_pk_mul_f32 v[30:31], v[30:31], v[36:37] op_sel_hi:[1,0]
	v_pk_mul_f32 v[28:29], v[28:29], v[36:37] op_sel_hi:[1,0]
	v_pk_mul_f32 v[26:27], v[26:27], v[36:37] op_sel_hi:[1,0]
	v_max_f32_e32 v24, 0, v24
	v_max_f32_e32 v25, 0, v25
	v_max_f32_e32 v28, 0, v28
	v_max_f32_e32 v29, 0, v29
	v_pk_mul_f32 v[38:39], v[24:25], v[24:25]
	v_max_f32_e32 v24, 0, v30
	v_max_f32_e32 v26, 0, v26
	v_max_f32_e32 v25, 0, v31
	v_max_f32_e32 v27, 0, v27
	v_pk_mul_f32 v[28:29], v[28:29], v[28:29]
	v_pk_mul_f32 v[30:31], v[24:25], v[24:25]
	v_pk_mul_f32 v[40:41], v[26:27], v[26:27]
	v_pk_mul_f32 v[18:19], v[18:19], v[36:37] op_sel_hi:[1,0]
	v_cvt_pk_bf16_f32 v244, v28, v29
	v_cvt_pk_bf16_f32 v245, v30, v31
	v_cvt_pk_bf16_f32 v246, v38, v39
	v_cvt_pk_bf16_f32 v247, v40, v41
	v_pk_mul_f32 v[20:21], v[20:21], v[36:37] op_sel_hi:[1,0]
	v_pk_mul_f32 v[16:17], v[16:17], v[36:37] op_sel_hi:[1,0]
	v_max_f32_e32 v18, 0, v18
	v_max_f32_e32 v19, 0, v19
	v_pk_mul_f32 v[22:23], v[22:23], v[36:37] op_sel_hi:[1,0]
	v_max_f32_e32 v20, 0, v20
	v_max_f32_e32 v16, 0, v16
	v_max_f32_e32 v21, 0, v21
	v_max_f32_e32 v17, 0, v17
	v_pk_mul_f32 v[26:27], v[18:19], v[18:19]
	v_pk_mul_f32 v[20:21], v[20:21], v[20:21]
	v_pk_mul_f32 v[24:25], v[16:17], v[16:17]
	v_max_f32_e32 v16, 0, v22
	v_max_f32_e32 v17, 0, v23
	v_pk_mul_f32 v[22:23], v[16:17], v[16:17]
	v_cvt_pk_bf16_f32 v252, v20, v21
	v_cvt_pk_bf16_f32 v253, v22, v23
	v_cvt_pk_bf16_f32 v254, v24, v25
	v_cvt_pk_bf16_f32 v255, v26, v27
	s_nop 1
	v_mov_b32_e32 v16, v235
	v_pk_mul_f32 v[8:9], v[8:9], v[16:17] op_sel_hi:[1,0]
	v_pk_mul_f32 v[14:15], v[14:15], v[16:17] op_sel_hi:[1,0]
	v_pk_mul_f32 v[12:13], v[12:13], v[16:17] op_sel_hi:[1,0]
	v_pk_mul_f32 v[10:11], v[10:11], v[16:17] op_sel_hi:[1,0]
	v_max_f32_e32 v8, 0, v8
	v_max_f32_e32 v9, 0, v9
	v_lshlrev_b64 v[18:19], 13, v[146:147]
	v_max_f32_e32 v12, 0, v12
	v_max_f32_e32 v13, 0, v13
	v_pk_mul_f32 v[20:21], v[8:9], v[8:9]
	v_max_f32_e32 v8, 0, v14
	v_max_f32_e32 v10, 0, v10
	v_max_f32_e32 v9, 0, v15
	v_max_f32_e32 v11, 0, v11
	v_lshl_add_u64 v[18:19], s[96:97], 0, v[18:19]
	v_pk_mul_f32 v[12:13], v[12:13], v[12:13]
	v_pk_mul_f32 v[14:15], v[8:9], v[8:9]
	v_pk_mul_f32 v[22:23], v[10:11], v[10:11]
	v_pk_mul_f32 v[0:1], v[0:1], v[16:17] op_sel_hi:[1,0]
	v_lshl_add_u64 v[18:19], v[18:19], 0, v[148:149]
	v_cvt_pk_bf16_f32 v228, v12, v13
	v_cvt_pk_bf16_f32 v229, v14, v15
	v_cvt_pk_bf16_f32 v230, v20, v21
	v_cvt_pk_bf16_f32 v231, v22, v23
	v_pk_mul_f32 v[6:7], v[6:7], v[16:17] op_sel_hi:[1,0]
	v_pk_mul_f32 v[4:5], v[4:5], v[16:17] op_sel_hi:[1,0]
	v_pk_mul_f32 v[2:3], v[2:3], v[16:17] op_sel_hi:[1,0]
	v_max_f32_e32 v0, 0, v0
	v_max_f32_e32 v1, 0, v1
	v_max_f32_e32 v4, 0, v4
	v_max_f32_e32 v5, 0, v5
	v_pk_mul_f32 v[8:9], v[0:1], v[0:1]
	v_max_f32_e32 v0, 0, v6
	v_max_f32_e32 v2, 0, v2
	v_max_f32_e32 v1, 0, v7
	v_max_f32_e32 v3, 0, v3
	v_pk_mul_f32 v[4:5], v[4:5], v[4:5]
	v_pk_mul_f32 v[6:7], v[0:1], v[0:1]
	v_pk_mul_f32 v[10:11], v[2:3], v[2:3]
	v_cvt_pk_bf16_f32 v232, v4, v5
	v_cvt_pk_bf16_f32 v233, v6, v7
	v_cvt_pk_bf16_f32 v234, v8, v9
	v_cvt_pk_bf16_f32 v235, v10, v11
	s_and_b64 vcc, exec, s[0:1]
	s_cbranch_vccz .Ldf6_head
	global_store_dwordx4 v[248:249], v[236:239], off
	global_store_dwordx4 v[248:249], v[240:243], off offset:256
	v_lshl_add_u64 v[248:249], v[248:249], 0, s[98:99]
	global_store_dwordx4 v[248:249], v[244:247], off
	global_store_dwordx4 v[248:249], v[252:255], off offset:256
	v_lshl_add_u64 v[248:249], v[248:249], 0, s[98:99]
	global_store_dwordx4 v[248:249], v[228:231], off
	global_store_dwordx4 v[248:249], v[232:235], off offset:256
	s_waitcnt vmcnt(0)
	s_cmpk_gt_u32 s9, 0xff
	s_cbranch_scc1 .LBB0_774
	s_barrier

; #define PG8_STAGE(bufoff, gbase, voff) do { _Pragma("unroll") for (int _i = 0; _i < 2; ++_i) \
;         __builtin_amdgcn_global_load_lds((const unsigned*)((const char*)(gbase) + (voff)[_i]), (LAS unsigned*)(lds + (bufoff) + ldsw + _i * 8192), 16, 0, 0); } while (0)
; #define PG8_WAIT_V(n) asm volatile("s_waitcnt vmcnt(" #n ")" ::: "memory")
; #define PG8_BAR __builtin_amdgcn_s_barrier()
; template <class Epi>
; __device__ __forceinline__ void gemm_phase(LAS unsigned char* lds, const Gemm g, const StaticOrder& S, const Epi& E) {
;     ...
;     for (int i = 0; i < 2; ++i) { int R, C; stage_rc(tid * 16 + i * 8192, R, C); const int Rb = Epi::PERM ? ((R & ~31) + perm32(R & 31)) : R;
;         voffA[i] = (unsigned)(R * lda + C) * 2u; voffB[i] = (unsigned)(Rb * K + C) * 2u; }
;     const size_t kstep = (size_t)(BK * 2);
;     const size_t hstepA = (size_t)HALF * lda * 2, hstepB = (size_t)HALF * K * 2;
;     const size_t tstepA = 2 * hstepA, tstepB = 2 * hstepB;
;     const unsigned ldsw = (unsigned)wid * 1024u;
;     const int aoff = lds_byte(wr * 64 + fr, fq * 8), boff = lds_byte(wc * 32 + fr, fq * 8);
;     ...
;     const char* cA = (const char*)g.A + (size_t)cur.pm * tstepA; const char* cB = (const char*)g.Bt + (size_t)cur.pn * tstepB;
;     PG8_STAGE(PG8_SB(0, 0), cB, voffB); PG8_STAGE(PG8_SA(0, 0), cA, voffA); PG8_STAGE(PG8_SB(0, 1), cB + hstepB, voffB); PG8_STAGE(PG8_SA(0, 1), cA + hstepA, voffA);
;     if (wr == 1) PG8_BAR;
;     PG8_WAIT_V(4); PG8_BAR;
;     PG8_STAGE(PG8_SB(1, 0), cB + kstep, voffB); PG8_STAGE(PG8_SA(1, 0), cA + kstep, voffA); PG8_STAGE(PG8_SB(1, 1), cB + hstepB + kstep, voffB);
;     PG8_WAIT_V(6); PG8_BAR;
.LBB0_1196:
	s_lshl_b32 s4, s4, 5
	s_and_b32 s8, s4, 0x60
	s_mov_b64 s[4:5], 0x80
	s_add_i32 m0, s19, 0x18000
	v_lshl_add_u64 v[6:7], v[6:7], 0, s[4:5]
	s_lshl_b32 s6, s1, 13
	s_lshl_b32 s12, s8, 7
	s_waitcnt vmcnt(4)
	s_barrier
	global_load_lds_dwordx4 v[6:7], off
	v_lshl_add_u64 v[4:5], v[4:5], 0, s[4:5]
	s_add_i32 m0, s19, 0x1a000
	s_add_i32 s34, s19, 0x8000
	s_add_i32 s35, s19, 0xa000
	global_load_lds_dwordx4 v[4:5], off
	v_lshl_add_u64 v[2:3], v[2:3], 0, s[4:5]
	s_mov_b32 m0, s34
	s_add_u32 s10, s22, 0x40080
	global_load_lds_dwordx4 v[2:3], off
	v_lshl_add_u64 v[0:1], v[0:1], 0, s[4:5]
	s_mov_b32 m0, s35
	s_addc_u32 s11, s23, 0
	global_load_lds_dwordx4 v[0:1], off
	s_add_i32 m0, s19, 0x1c000
	v_lshl_add_u64 v[0:1], s[10:11], 0, v[130:131]
	global_load_lds_dwordx4 v[0:1], off
	v_lshl_add_u64 v[0:1], s[10:11], 0, v[134:135]
	s_add_i32 m0, s19, 0x1e000
	v_bfe_u32 v2, v152, 4, 2
	global_load_lds_dwordx4 v[0:1], off
	v_and_b32_e32 v1, 15, v152
	v_lshlrev_b32_e32 v0, 4, v2
	v_lshlrev_b32_e32 v3, 2, v152
	v_lshl_or_b32 v153, s1, 6, v1
	v_lshl_or_b32 v1, v1, 6, v0
	v_and_b32_e32 v3, 32, v3
	s_sext_i32_i8 s40, s0
	v_bitop3_b32 v4, v1, s6, v3 bitop3:0xde
	v_lshlrev_b32_e32 v1, 6, v152
	s_movk_i32 s0, 0x3c0
	v_and_or_b32 v1, v1, s0, v0
	v_bitop3_b32 v174, s12, v1, v3 bitop3:0xf6
	v_mov_b32_e32 v1, v131
	v_lshl_add_u64 v[0:1], s[74:75], 0, v[0:1]
	s_mov_b64 s[0:1], 0x3cbc4000
	v_lshl_add_u64 v[136:137], v[0:1], 0, s[0:1]
	v_lshlrev_b32_e32 v0, 8, v152
	v_and_b32_e32 v0, 0x38000, v0
	v_lshlrev_b32_e32 v1, 11, v10
	v_or3_b32 v0, v8, v0, v1
	v_add_u32_e32 v138, v0, v9
	v_lshlrev_b32_e32 v0, 4, v11
	v_and_b32_e32 v0, 0x78000, v0
	s_waitcnt vmcnt(6)
	v_or3_b32 v0, v8, v0, v1
	v_add_u32_e32 v140, v0, v9
	s_add_i32 s37, 0, 0x10000
	s_add_i32 s38, 0, 0x14000
	v_mbcnt_lo_u32_b32 v0, -1, 0
	s_ashr_i32 s36, s92, 31
	v_lshl_or_b32 v175, v2, 3, s8
	v_mov_b32_e32 v139, v131
	v_mov_b32_e32 v141, v131
	v_mov_b64_e32 v[142:143], 0x1000
	v_mov_b64_e32 v[144:145], 0xfff
	v_add_u32_e32 v176, s37, v174
	v_add_u32_e32 v177, 0, v4
	v_add_u32_e32 v178, s38, v174
	v_mbcnt_hi_u32_b32 v179, -1, v0
	s_mov_b32 s6, 0x3a800000
	s_mov_b32 s8, 0x358637bd
	s_mov_b32 s39, 0x800000
	s_barrier
	s_mov_b64 s[98:99], 0x20000
	s_branch .LBB0_1197

; #define PG8_STAGE(bufoff, gbase, voff) do { _Pragma("unroll") for (int _i = 0; _i < 2; ++_i) \
;         __builtin_amdgcn_global_load_lds((const unsigned*)((const char*)(gbase) + (voff)[_i]), (LAS unsigned*)(lds + (bufoff) + ldsw + _i * 8192), 16, 0, 0); } while (0)
; #define PG8_LDA(dst, b, h) do { _Pragma("unroll") for (int m = 0; m < 4; ++m) _Pragma("unroll") for (int k = 0; k < 2; ++k) dst[m][k] = *(const LAS bf16x8*)(lds + PG8_SA(b, h) + aoff + m * 2048 + k * 1024); } while (0)
; #define PG8_LDB(dst, b, h) do { _Pragma("unroll") for (int n = 0; n < 2; ++n) _Pragma("unroll") for (int k = 0; k < 2; ++k) dst[n][k] = *(const LAS bf16x8*)(lds + PG8_SB(b, h) + boff + n * 2048 + k * 1024); } while (0)
; #define PG8_MMA(ai, bj, At, Bt) do { __builtin_amdgcn_s_setprio(1); _Pragma("unroll") for (int m = 0; m < 4; ++m) _Pragma("unroll") for (int n = 0; n < 2; ++n) _Pragma("unroll") for (int k = 0; k < 2; ++k) \
;         acc[ai][bj][m][n] = __builtin_amdgcn_mfma_f32_16x16x32_bf16(Bt[n][k], At[m][k], acc[ai][bj][m][n], 0, 0, 0); __builtin_amdgcn_s_setprio(0); } while (0)
; #define PG8_BAR __builtin_amdgcn_s_barrier()
; template <class Epi>
; __device__ __forceinline__ void gemm_phase(LAS unsigned char* lds, const Gemm g, const StaticOrder& S, const Epi& E) {
;     ...
;         const bool has_next = S.next(ui + 1, nxt);
;         const char* nA = has_next ? (const char*)g.A + (size_t)nxt.pm * tstepA : cA; const char* nB = has_next ? (const char*)g.Bt + (size_t)nxt.pn * tstepB : cB;
;         for (int t = 0; t < nt; t += 2) {
;             const bool last = (t == nt - 2);
;             const char* a1 = cA + (size_t)(t + 1) * kstep;
;             const char* a2 = last ? nA : cA + (size_t)(t + 2) * kstep; const char* b2 = last ? nB : cB + (size_t)(t + 2) * kstep;
;             const char* a3 = a2 + kstep; const char* b3 = b2 + kstep;
;             if (last) E.pre(cur, wr, fr, epre);
;             PG8_LDB(B0, 0, 0); PG8_SCHED; PG8_LDA(At, 0, 0); PG8_STAGE(PG8_SA(1, 1), a1 + hstepA, voffA);
;             PG8_WAIT_L(8); PG8_BAR; PG8_WAIT_L(0); PG8_MMA(0, 0, At, B0); PG8_BAR; PG8_SCHED;
;             PG8_LDB(B1, 0, 1); PG8_STAGE(PG8_SB(0, 0), b2, voffB);
;             PG8_BAR; PG8_WAIT_L(0); PG8_MMA(0, 1, At, B1); PG8_BAR;
;             PG8_LDA(At, 0, 1); PG8_STAGE(PG8_SA(0, 0), a2, voffA);
;             PG8_BAR; PG8_WAIT_L(0); PG8_MMA(1, 0, At, B0); PG8_BAR; PG8_SCHED;
.Ldf12_1203:
	s_ashr_i32 s13, s12, 31
	v_cmp_lt_i64_e32 vcc, s[14:15], v[142:143]
	s_lshl_b64 s[14:15], s[12:13], 19
	s_add_u32 s14, s76, s14
	s_addc_u32 s15, s77, s15
	s_and_b64 s[16:17], vcc, exec
	s_cselect_b32 s13, s15, s21
	s_cselect_b32 s41, s14, s20
	s_ashr_i32 s11, s10, 31
	s_lshl_b64 s[16:17], s[10:11], 19
	s_add_u32 s16, s26, s16
	s_addc_u32 s17, s27, s17
	s_and_b64 s[24:25], vcc, exec
	s_cselect_b32 s11, s17, s23
	s_cselect_b32 s42, s16, s22
	s_add_u32 s20, s20, 0x40080
	s_addc_u32 s21, s21, 0
	s_add_u32 s43, s22, 0x100
	s_addc_u32 s44, s23, 0
	s_mov_b32 s45, -2
	ds_read_b128 v[146:149], v176
	ds_read_b128 v[154:157], v176 offset:1024
	ds_read_b128 v[158:161], v176 offset:2048
	ds_read_b128 v[162:165], v176 offset:3072
	s_add_u32 s22, s20, 0xfffc0080
	s_addc_u32 s23, s21, -1
	s_cmp_eq_u32 s45, 12
	s_cselect_b32 s25, s13, s23
	s_cselect_b32 s24, s41, s22
	s_cselect_b32 s23, s11, s44
	s_cselect_b32 s22, s42, s43
	v_lshl_add_u64 v[150:151], s[20:21], 0, v[138:139]
	s_add_i32 m0, s19, 0xc000
	ds_read_b128 v[166:169], v177
	ds_read_b128 v[170:173], v177 offset:1024
	ds_read_b128 v[180:183], v177 offset:2048
	ds_read_b128 v[184:187], v177 offset:3072
	ds_read_b128 v[188:191], v177 offset:4096
	ds_read_b128 v[192:195], v177 offset:5120
	ds_read_b128 v[196:199], v177 offset:6144
	ds_read_b128 v[200:203], v177 offset:7168
	global_load_lds_dwordx4 v[150:151], off
	v_lshl_add_u64 v[150:151], s[20:21], 0, v[140:141]
	s_add_i32 m0, s19, 0xe000
	s_nop 0
	global_load_lds_dwordx4 v[150:151], off
	global_store_dwordx4 v[248:249], v[236:239], off
	s_waitcnt lgkmcnt(8)
	s_barrier
	s_waitcnt lgkmcnt(0)
	s_setprio 1
	s_waitcnt lgkmcnt(0)
	v_mfma_f32_16x16x32_bf16 v[124:127], v[146:149], v[166:169], 0
	v_mfma_f32_16x16x32_bf16 v[120:123], v[158:161], v[166:169], 0
	v_mfma_f32_16x16x32_bf16 v[108:111], v[146:149], v[180:183], 0
	v_mfma_f32_16x16x32_bf16 v[104:107], v[158:161], v[180:183], 0
	v_mfma_f32_16x16x32_bf16 v[92:95], v[146:149], v[188:191], 0
	v_mfma_f32_16x16x32_bf16 v[88:91], v[158:161], v[188:191], 0
	v_mfma_f32_16x16x32_bf16 v[76:79], v[146:149], v[196:199], 0
	v_mfma_f32_16x16x32_bf16 v[72:75], v[158:161], v[196:199], 0
	v_mfma_f32_16x16x32_bf16 v[124:127], v[154:157], v[170:173], v[124:127]
	v_mfma_f32_16x16x32_bf16 v[120:123], v[162:165], v[170:173], v[120:123]
	v_mfma_f32_16x16x32_bf16 v[108:111], v[154:157], v[184:187], v[108:111]
	v_mfma_f32_16x16x32_bf16 v[104:107], v[162:165], v[184:187], v[104:107]
	v_mfma_f32_16x16x32_bf16 v[92:95], v[154:157], v[192:195], v[92:95]
	v_mfma_f32_16x16x32_bf16 v[88:91], v[162:165], v[192:195], v[88:91]
	v_mfma_f32_16x16x32_bf16 v[76:79], v[154:157], v[200:203], v[76:79]
	v_mfma_f32_16x16x32_bf16 v[72:75], v[162:165], v[200:203], v[72:75]
	s_setprio 0
	s_barrier
	s_add_i32 s46, s37, s28
	v_lshl_add_u64 v[150:151], s[22:23], 0, v[130:131]
	s_mov_b32 m0, s46
	ds_read_b128 v[204:207], v178
	ds_read_b128 v[208:211], v178 offset:1024
	ds_read_b128 v[212:215], v178 offset:2048
	ds_read_b128 v[216:219], v178 offset:3072
	global_load_lds_dwordx4 v[150:151], off
	v_lshl_add_u64 v[220:221], s[22:23], 0, v[134:135]
	s_add_i32 m0, s46, 0x2000
	s_nop 0
	global_load_lds_dwordx4 v[220:221], off
	global_store_dwordx4 v[248:249], v[240:243], off offset:256
	v_lshl_add_u64 v[248:249], v[248:249], 0, s[98:99]
	s_barrier
	s_waitcnt lgkmcnt(0)
	s_setprio 1
	s_waitcnt lgkmcnt(0)
	v_mfma_f32_16x16x32_bf16 v[116:119], v[204:207], v[166:169], 0
	v_mfma_f32_16x16x32_bf16 v[112:115], v[212:215], v[166:169], 0
	v_mfma_f32_16x16x32_bf16 v[100:103], v[204:207], v[180:183], 0
	v_mfma_f32_16x16x32_bf16 v[96:99], v[212:215], v[180:183], 0
	v_mfma_f32_16x16x32_bf16 v[84:87], v[204:207], v[188:191], 0
	v_mfma_f32_16x16x32_bf16 v[80:83], v[212:215], v[188:191], 0
	v_mfma_f32_16x16x32_bf16 v[68:71], v[204:207], v[196:199], 0
	v_mfma_f32_16x16x32_bf16 v[64:67], v[212:215], v[196:199], 0
	v_mfma_f32_16x16x32_bf16 v[116:119], v[208:211], v[170:173], v[116:119]
	v_mfma_f32_16x16x32_bf16 v[112:115], v[216:219], v[170:173], v[112:115]
	v_mfma_f32_16x16x32_bf16 v[100:103], v[208:211], v[184:187], v[100:103]
	v_mfma_f32_16x16x32_bf16 v[96:99], v[216:219], v[184:187], v[96:99]
	v_mfma_f32_16x16x32_bf16 v[84:87], v[208:211], v[192:195], v[84:87]
	v_mfma_f32_16x16x32_bf16 v[80:83], v[216:219], v[192:195], v[80:83]
	v_mfma_f32_16x16x32_bf16 v[68:71], v[208:211], v[200:203], v[68:71]
	v_mfma_f32_16x16x32_bf16 v[64:67], v[216:219], v[200:203], v[64:67]
	s_setprio 0
	s_mov_b32 m0, s19
	v_lshl_add_u64 v[222:223], s[24:25], 0, v[128:129]
	s_barrier
	ds_read_b128 v[166:169], v177 offset:16384
	ds_read_b128 v[170:173], v177 offset:17408
	ds_read_b128 v[180:183], v177 offset:18432
	ds_read_b128 v[184:187], v177 offset:19456
	ds_read_b128 v[188:191], v177 offset:20480
	ds_read_b128 v[192:195], v177 offset:21504
	ds_read_b128 v[196:199], v177 offset:22528
	ds_read_b128 v[200:203], v177 offset:23552
	global_load_lds_dwordx4 v[222:223], off
	v_lshl_add_u64 v[224:225], s[24:25], 0, v[132:133]
	s_mov_b32 m0, s29
	s_nop 0
	global_load_lds_dwordx4 v[224:225], off
	global_store_dwordx4 v[248:249], v[244:247], off
	s_barrier
; #define PG8_STAGE(bufoff, gbase, voff) do { _Pragma("unroll") for (int _i = 0; _i < 2; ++_i) \
;         __builtin_amdgcn_global_load_lds((const unsigned*)((const char*)(gbase) + (voff)[_i]), (LAS unsigned*)(lds + (bufoff) + ldsw + _i * 8192), 16, 0, 0); } while (0)
; #define PG8_LDA(dst, b, h) do { _Pragma("unroll") for (int m = 0; m < 4; ++m) _Pragma("unroll") for (int k = 0; k < 2; ++k) dst[m][k] = *(const LAS bf16x8*)(lds + PG8_SA(b, h) + aoff + m * 2048 + k * 1024); } while (0)
; #define PG8_LDB(dst, b, h) do { _Pragma("unroll") for (int n = 0; n < 2; ++n) _Pragma("unroll") for (int k = 0; k < 2; ++k) dst[n][k] = *(const LAS bf16x8*)(lds + PG8_SB(b, h) + boff + n * 2048 + k * 1024); } while (0)
; #define PG8_MMA(ai, bj, At, Bt) do { __builtin_amdgcn_s_setprio(1); _Pragma("unroll") for (int m = 0; m < 4; ++m) _Pragma("unroll") for (int n = 0; n < 2; ++n) _Pragma("unroll") for (int k = 0; k < 2; ++k) \
;         acc[ai][bj][m][n] = __builtin_amdgcn_mfma_f32_16x16x32_bf16(Bt[n][k], At[m][k], acc[ai][bj][m][n], 0, 0, 0); __builtin_amdgcn_s_setprio(0); } while (0)
; #define PG8_WAIT_V(n) asm volatile("s_waitcnt vmcnt(" #n ")" ::: "memory")
; #define PG8_WAIT_L(n) asm volatile("s_waitcnt lgkmcnt(" #n ")" ::: "memory")
; #define PG8_BAR __builtin_amdgcn_s_barrier()
; #define PG8_SCHED __builtin_amdgcn_sched_barrier(0)
; template <class Epi>
; __device__ __forceinline__ void gemm_phase(LAS unsigned char* lds, const Gemm g, const StaticOrder& S, const Epi& E) {
;     ...
;             PG8_BAR; PG8_WAIT_L(0); PG8_MMA(1, 0, At, B0); PG8_BAR; PG8_SCHED;
;             PG8_STAGE(PG8_SB(0, 1), b2 + hstepB, voffB);
;             PG8_WAIT_V(6); PG8_BAR; PG8_MMA(1, 1, At, B1); PG8_BAR;
;             PG8_LDB(B0, 1, 0); PG8_SCHED; PG8_LDA(At, 1, 0); PG8_STAGE(PG8_SA(0, 1), a2 + hstepA, voffA);
;             PG8_WAIT_L(8); PG8_BAR; PG8_WAIT_L(0); PG8_MMA(0, 0, At, B0); PG8_BAR; PG8_SCHED;
	s_waitcnt lgkmcnt(0)
	s_setprio 1
	s_waitcnt lgkmcnt(0)
	v_mfma_f32_16x16x32_bf16 v[60:63], v[146:149], v[166:169], 0
	v_mfma_f32_16x16x32_bf16 v[56:59], v[158:161], v[166:169], 0
	v_mfma_f32_16x16x32_bf16 v[44:47], v[146:149], v[180:183], 0
	v_mfma_f32_16x16x32_bf16 v[40:43], v[158:161], v[180:183], 0
	v_mfma_f32_16x16x32_bf16 v[28:31], v[146:149], v[188:191], 0
	v_mfma_f32_16x16x32_bf16 v[24:27], v[158:161], v[188:191], 0
	v_mfma_f32_16x16x32_bf16 v[12:15], v[146:149], v[196:199], 0
	v_mfma_f32_16x16x32_bf16 v[8:11], v[158:161], v[196:199], 0
	v_mfma_f32_16x16x32_bf16 v[60:63], v[154:157], v[170:173], v[60:63]
	v_mfma_f32_16x16x32_bf16 v[56:59], v[162:165], v[170:173], v[56:59]
	v_mfma_f32_16x16x32_bf16 v[44:47], v[154:157], v[184:187], v[44:47]
	v_mfma_f32_16x16x32_bf16 v[40:43], v[162:165], v[184:187], v[40:43]
	v_mfma_f32_16x16x32_bf16 v[28:31], v[154:157], v[192:195], v[28:31]
	v_mfma_f32_16x16x32_bf16 v[24:27], v[162:165], v[192:195], v[24:27]
	v_mfma_f32_16x16x32_bf16 v[12:15], v[154:157], v[200:203], v[12:15]
	v_mfma_f32_16x16x32_bf16 v[8:11], v[162:165], v[200:203], v[8:11]
	s_setprio 0
	s_barrier
	s_add_u32 s46, s22, 0x40000
	s_addc_u32 s47, s23, 0
	s_add_i32 s48, s38, s28
	v_lshl_add_u64 v[146:147], s[46:47], 0, v[130:131]
	s_mov_b32 m0, s48
	s_nop 0
	global_load_lds_dwordx4 v[146:147], off
	v_lshl_add_u64 v[146:147], s[46:47], 0, v[134:135]
	s_add_i32 m0, s48, 0x2000
	s_nop 0
	global_load_lds_dwordx4 v[146:147], off
	global_store_dwordx4 v[248:249], v[252:255], off offset:256
	v_lshl_add_u64 v[248:249], v[248:249], 0, s[98:99]
	s_waitcnt vmcnt(10)
	s_barrier
	s_setprio 1
	v_mfma_f32_16x16x32_bf16 v[52:55], v[204:207], v[166:169], 0
	v_mfma_f32_16x16x32_bf16 v[48:51], v[212:215], v[166:169], 0
	v_mfma_f32_16x16x32_bf16 v[36:39], v[204:207], v[180:183], 0
	v_mfma_f32_16x16x32_bf16 v[32:35], v[212:215], v[180:183], 0
	v_mfma_f32_16x16x32_bf16 v[20:23], v[204:207], v[188:191], 0
	v_mfma_f32_16x16x32_bf16 v[16:19], v[212:215], v[188:191], 0
	v_mfma_f32_16x16x32_bf16 v[4:7], v[204:207], v[196:199], 0
	v_mfma_f32_16x16x32_bf16 v[0:3], v[212:215], v[196:199], 0
	v_mfma_f32_16x16x32_bf16 v[52:55], v[208:211], v[170:173], v[52:55]
	v_mfma_f32_16x16x32_bf16 v[48:51], v[216:219], v[170:173], v[48:51]
	v_mfma_f32_16x16x32_bf16 v[36:39], v[208:211], v[184:187], v[36:39]
	v_mfma_f32_16x16x32_bf16 v[32:35], v[216:219], v[184:187], v[32:35]
	v_mfma_f32_16x16x32_bf16 v[20:23], v[208:211], v[192:195], v[20:23]
	v_mfma_f32_16x16x32_bf16 v[16:19], v[216:219], v[192:195], v[16:19]
	v_mfma_f32_16x16x32_bf16 v[4:7], v[208:211], v[200:203], v[4:7]
	v_mfma_f32_16x16x32_bf16 v[0:3], v[216:219], v[200:203], v[0:3]
	s_setprio 0
	s_add_i32 s46, 0, 0x18000
	v_add_u32_e32 v162, s46, v174
	s_barrier
	ds_read_b128 v[146:149], v162
	ds_read_b128 v[154:157], v162 offset:1024
	ds_read_b128 v[158:161], v162 offset:2048
	ds_read_b128 v[162:165], v162 offset:3072
	s_add_u32 s24, s24, 0x40000
	s_addc_u32 s25, s25, 0
	s_mov_b32 m0, s30
	v_lshl_add_u64 v[204:205], s[24:25], 0, v[128:129]
	ds_read_b128 v[166:169], v177 offset:32768
	ds_read_b128 v[170:173], v177 offset:33792
	ds_read_b128 v[180:183], v177 offset:34816
	ds_read_b128 v[184:187], v177 offset:35840
	ds_read_b128 v[188:191], v177 offset:36864
	ds_read_b128 v[192:195], v177 offset:37888
	ds_read_b128 v[196:199], v177 offset:38912
	ds_read_b128 v[200:203], v177 offset:39936
	global_load_lds_dwordx4 v[204:205], off
	v_lshl_add_u64 v[204:205], s[24:25], 0, v[132:133]
	s_mov_b32 m0, s31
	s_nop 0
	global_load_lds_dwordx4 v[204:205], off
	global_store_dwordx4 v[248:249], v[228:231], off
	s_waitcnt lgkmcnt(8)
	s_barrier
	s_waitcnt lgkmcnt(0)
	s_setprio 1
	s_waitcnt lgkmcnt(0)
	v_mfma_f32_16x16x32_bf16 v[124:127], v[146:149], v[166:169], v[124:127]
	v_mfma_f32_16x16x32_bf16 v[120:123], v[158:161], v[166:169], v[120:123]
	v_mfma_f32_16x16x32_bf16 v[108:111], v[146:149], v[180:183], v[108:111]
	v_mfma_f32_16x16x32_bf16 v[104:107], v[158:161], v[180:183], v[104:107]
	v_mfma_f32_16x16x32_bf16 v[92:95], v[146:149], v[188:191], v[92:95]
	v_mfma_f32_16x16x32_bf16 v[88:91], v[158:161], v[188:191], v[88:91]
	v_mfma_f32_16x16x32_bf16 v[76:79], v[146:149], v[196:199], v[76:79]
	v_mfma_f32_16x16x32_bf16 v[72:75], v[158:161], v[196:199], v[72:75]
	v_mfma_f32_16x16x32_bf16 v[124:127], v[154:157], v[170:173], v[124:127]
	v_mfma_f32_16x16x32_bf16 v[120:123], v[162:165], v[170:173], v[120:123]
	v_mfma_f32_16x16x32_bf16 v[108:111], v[154:157], v[184:187], v[108:111]
	v_mfma_f32_16x16x32_bf16 v[104:107], v[162:165], v[184:187], v[104:107]
	v_mfma_f32_16x16x32_bf16 v[92:95], v[154:157], v[192:195], v[92:95]
	v_mfma_f32_16x16x32_bf16 v[88:91], v[162:165], v[192:195], v[88:91]
	v_mfma_f32_16x16x32_bf16 v[76:79], v[154:157], v[200:203], v[76:79]
	v_mfma_f32_16x16x32_bf16 v[72:75], v[162:165], v[200:203], v[72:75]
	s_setprio 0
	s_barrier
; #define PG8_STAGE(bufoff, gbase, voff) do { _Pragma("unroll") for (int _i = 0; _i < 2; ++_i) \
;         __builtin_amdgcn_global_load_lds((const unsigned*)((const char*)(gbase) + (voff)[_i]), (LAS unsigned*)(lds + (bufoff) + ldsw + _i * 8192), 16, 0, 0); } while (0)
; #define PG8_LDA(dst, b, h) do { _Pragma("unroll") for (int m = 0; m < 4; ++m) _Pragma("unroll") for (int k = 0; k < 2; ++k) dst[m][k] = *(const LAS bf16x8*)(lds + PG8_SA(b, h) + aoff + m * 2048 + k * 1024); } while (0)
; #define PG8_LDB(dst, b, h) do { _Pragma("unroll") for (int n = 0; n < 2; ++n) _Pragma("unroll") for (int k = 0; k < 2; ++k) dst[n][k] = *(const LAS bf16x8*)(lds + PG8_SB(b, h) + boff + n * 2048 + k * 1024); } while (0)
; #define PG8_MMA(ai, bj, At, Bt) do { __builtin_amdgcn_s_setprio(1); _Pragma("unroll") for (int m = 0; m < 4; ++m) _Pragma("unroll") for (int n = 0; n < 2; ++n) _Pragma("unroll") for (int k = 0; k < 2; ++k) \
;         acc[ai][bj][m][n] = __builtin_amdgcn_mfma_f32_16x16x32_bf16(Bt[n][k], At[m][k], acc[ai][bj][m][n], 0, 0, 0); __builtin_amdgcn_s_setprio(0); } while (0)
; #define PG8_WAIT_V(n) asm volatile("s_waitcnt vmcnt(" #n ")" ::: "memory")
; #define PG8_WAIT_L(n) asm volatile("s_waitcnt lgkmcnt(" #n ")" ::: "memory")
; #define PG8_BAR __builtin_amdgcn_s_barrier()
; #define PG8_SCHED __builtin_amdgcn_sched_barrier(0)
; template <class Epi>
; __device__ __forceinline__ void gemm_phase(LAS unsigned char* lds, const Gemm g, const StaticOrder& S, const Epi& E) {
;     ...
;             PG8_LDB(B1, 1, 1); PG8_STAGE(PG8_SB(1, 0), b3, voffB);
;             PG8_BAR; PG8_WAIT_L(0); PG8_MMA(0, 1, At, B1); PG8_BAR;
;             PG8_LDA(At, 1, 1); PG8_STAGE(PG8_SA(1, 0), a3, voffA);
;             PG8_BAR; PG8_WAIT_L(0); PG8_MMA(1, 0, At, B0); PG8_BAR; PG8_SCHED;
;             PG8_STAGE(PG8_SB(1, 1), b3 + hstepB, voffB);
;             PG8_WAIT_V(6); PG8_BAR; PG8_MMA(1, 1, At, B1); PG8_BAR;
	s_add_i32 s24, 0, 0x1c000
	s_add_i32 s25, s46, s28
	v_add_u32_e32 v216, s24, v174
	v_lshl_add_u64 v[150:151], v[150:151], 0, s[4:5]
	s_mov_b32 m0, s25
	ds_read_b128 v[204:207], v216
	ds_read_b128 v[208:211], v216 offset:1024
	ds_read_b128 v[212:215], v216 offset:2048
	ds_read_b128 v[216:219], v216 offset:3072
	global_load_lds_dwordx4 v[150:151], off
	v_lshl_add_u64 v[150:151], v[220:221], 0, s[4:5]
	s_add_i32 m0, s25, 0x2000
	s_nop 0
	global_load_lds_dwordx4 v[150:151], off
	global_store_dwordx4 v[248:249], v[232:235], off offset:256
	s_barrier
	s_waitcnt lgkmcnt(0)
	s_setprio 1
	s_waitcnt lgkmcnt(0)
	v_mfma_f32_16x16x32_bf16 v[116:119], v[204:207], v[166:169], v[116:119]
	v_mfma_f32_16x16x32_bf16 v[112:115], v[212:215], v[166:169], v[112:115]
	v_mfma_f32_16x16x32_bf16 v[100:103], v[204:207], v[180:183], v[100:103]
	v_mfma_f32_16x16x32_bf16 v[96:99], v[212:215], v[180:183], v[96:99]
	v_mfma_f32_16x16x32_bf16 v[84:87], v[204:207], v[188:191], v[84:87]
	v_mfma_f32_16x16x32_bf16 v[80:83], v[212:215], v[188:191], v[80:83]
	v_mfma_f32_16x16x32_bf16 v[68:71], v[204:207], v[196:199], v[68:71]
	v_mfma_f32_16x16x32_bf16 v[64:67], v[212:215], v[196:199], v[64:67]
	v_mfma_f32_16x16x32_bf16 v[116:119], v[208:211], v[170:173], v[116:119]
	v_mfma_f32_16x16x32_bf16 v[112:115], v[216:219], v[170:173], v[112:115]
	v_mfma_f32_16x16x32_bf16 v[100:103], v[208:211], v[184:187], v[100:103]
	v_mfma_f32_16x16x32_bf16 v[96:99], v[216:219], v[184:187], v[96:99]
	v_mfma_f32_16x16x32_bf16 v[84:87], v[208:211], v[192:195], v[84:87]
	v_mfma_f32_16x16x32_bf16 v[80:83], v[216:219], v[192:195], v[80:83]
	v_mfma_f32_16x16x32_bf16 v[68:71], v[208:211], v[200:203], v[68:71]
	v_mfma_f32_16x16x32_bf16 v[64:67], v[216:219], v[200:203], v[64:67]
	s_setprio 0
	s_mov_b32 m0, s34
	v_lshl_add_u64 v[150:151], v[222:223], 0, s[4:5]
	s_barrier
	ds_read_b128 v[166:169], v177 offset:49152
	ds_read_b128 v[170:173], v177 offset:50176
	ds_read_b128 v[180:183], v177 offset:51200
	ds_read_b128 v[184:187], v177 offset:52224
	ds_read_b128 v[188:191], v177 offset:53248
	ds_read_b128 v[192:195], v177 offset:54272
	ds_read_b128 v[196:199], v177 offset:55296
	ds_read_b128 v[200:203], v177 offset:56320
	global_load_lds_dwordx4 v[150:151], off
	v_lshl_add_u64 v[150:151], v[224:225], 0, s[4:5]
	s_mov_b32 m0, s35
	s_nop 0
	global_load_lds_dwordx4 v[150:151], off
	s_barrier
	s_waitcnt lgkmcnt(0)
	s_setprio 1
	s_waitcnt lgkmcnt(0)
	v_mfma_f32_16x16x32_bf16 v[60:63], v[146:149], v[166:169], v[60:63]
	v_mfma_f32_16x16x32_bf16 v[56:59], v[158:161], v[166:169], v[56:59]
	v_mfma_f32_16x16x32_bf16 v[44:47], v[146:149], v[180:183], v[44:47]
	v_mfma_f32_16x16x32_bf16 v[40:43], v[158:161], v[180:183], v[40:43]
	v_mfma_f32_16x16x32_bf16 v[28:31], v[146:149], v[188:191], v[28:31]
	v_mfma_f32_16x16x32_bf16 v[24:27], v[158:161], v[188:191], v[24:27]
	v_mfma_f32_16x16x32_bf16 v[12:15], v[146:149], v[196:199], v[12:15]
	v_mfma_f32_16x16x32_bf16 v[8:11], v[158:161], v[196:199], v[8:11]
	v_mfma_f32_16x16x32_bf16 v[60:63], v[154:157], v[170:173], v[60:63]
	v_mfma_f32_16x16x32_bf16 v[56:59], v[162:165], v[170:173], v[56:59]
	v_mfma_f32_16x16x32_bf16 v[44:47], v[154:157], v[184:187], v[44:47]
	v_mfma_f32_16x16x32_bf16 v[40:43], v[162:165], v[184:187], v[40:43]
	v_mfma_f32_16x16x32_bf16 v[28:31], v[154:157], v[192:195], v[28:31]
	v_mfma_f32_16x16x32_bf16 v[24:27], v[162:165], v[192:195], v[24:27]
	v_mfma_f32_16x16x32_bf16 v[12:15], v[154:157], v[200:203], v[12:15]
	v_mfma_f32_16x16x32_bf16 v[8:11], v[162:165], v[200:203], v[8:11]
	s_setprio 0
	s_barrier
	s_add_u32 s22, s22, 0x40080
	s_addc_u32 s23, s23, 0
	s_add_i32 s24, s24, s28
	v_lshl_add_u64 v[146:147], s[22:23], 0, v[130:131]
	s_mov_b32 m0, s24
	s_nop 0
	global_load_lds_dwordx4 v[146:147], off
	v_lshl_add_u64 v[146:147], s[22:23], 0, v[134:135]
	s_add_i32 m0, s24, 0x2000
	s_nop 0
	global_load_lds_dwordx4 v[146:147], off
	s_waitcnt vmcnt(8)
	s_barrier
	s_setprio 1
	v_mfma_f32_16x16x32_bf16 v[52:55], v[204:207], v[166:169], v[52:55]
	v_mfma_f32_16x16x32_bf16 v[48:51], v[212:215], v[166:169], v[48:51]
	v_mfma_f32_16x16x32_bf16 v[36:39], v[204:207], v[180:183], v[36:39]
	v_mfma_f32_16x16x32_bf16 v[32:35], v[212:215], v[180:183], v[32:35]
	v_mfma_f32_16x16x32_bf16 v[20:23], v[204:207], v[188:191], v[20:23]
	v_mfma_f32_16x16x32_bf16 v[16:19], v[212:215], v[188:191], v[16:19]
	v_mfma_f32_16x16x32_bf16 v[4:7], v[204:207], v[196:199], v[4:7]
	v_mfma_f32_16x16x32_bf16 v[0:3], v[212:215], v[196:199], v[0:3]
	v_mfma_f32_16x16x32_bf16 v[52:55], v[208:211], v[170:173], v[52:55]
	v_mfma_f32_16x16x32_bf16 v[48:51], v[216:219], v[170:173], v[48:51]
	v_mfma_f32_16x16x32_bf16 v[36:39], v[208:211], v[184:187], v[36:39]
	v_mfma_f32_16x16x32_bf16 v[32:35], v[216:219], v[184:187], v[32:35]
	v_mfma_f32_16x16x32_bf16 v[20:23], v[208:211], v[192:195], v[20:23]
	v_mfma_f32_16x16x32_bf16 v[16:19], v[216:219], v[192:195], v[16:19]
	v_mfma_f32_16x16x32_bf16 v[4:7], v[208:211], v[200:203], v[4:7]
	v_mfma_f32_16x16x32_bf16 v[0:3], v[216:219], v[200:203], v[0:3]
	s_setprio 0
	s_add_i32 s45, s45, 2
	s_add_u32 s20, s20, 0x100
	s_addc_u32 s21, s21, 0
	s_add_u32 s43, s43, 0x100
	s_addc_u32 s44, s44, 0
	s_cmp_gt_u32 s45, 13
	s_barrier
	s_branch .LBB0_1204

; #define PG8_STAGE(bufoff, gbase, voff) do { _Pragma("unroll") for (int _i = 0; _i < 2; ++_i) \
;         __builtin_amdgcn_global_load_lds((const unsigned*)((const char*)(gbase) + (voff)[_i]), (LAS unsigned*)(lds + (bufoff) + ldsw + _i * 8192), 16, 0, 0); } while (0)
; #define PG8_LDA(dst, b, h) do { _Pragma("unroll") for (int m = 0; m < 4; ++m) _Pragma("unroll") for (int k = 0; k < 2; ++k) dst[m][k] = *(const LAS bf16x8*)(lds + PG8_SA(b, h) + aoff + m * 2048 + k * 1024); } while (0)
; #define PG8_LDB(dst, b, h) do { _Pragma("unroll") for (int n = 0; n < 2; ++n) _Pragma("unroll") for (int k = 0; k < 2; ++k) dst[n][k] = *(const LAS bf16x8*)(lds + PG8_SB(b, h) + boff + n * 2048 + k * 1024); } while (0)
; #define PG8_MMA(ai, bj, At, Bt) do { __builtin_amdgcn_s_setprio(1); _Pragma("unroll") for (int m = 0; m < 4; ++m) _Pragma("unroll") for (int n = 0; n < 2; ++n) _Pragma("unroll") for (int k = 0; k < 2; ++k) \
;         acc[ai][bj][m][n] = __builtin_amdgcn_mfma_f32_16x16x32_bf16(Bt[n][k], At[m][k], acc[ai][bj][m][n], 0, 0, 0); __builtin_amdgcn_s_setprio(0); } while (0)
; #define PG8_WAIT_V(n) asm volatile("s_waitcnt vmcnt(" #n ")" ::: "memory")
; #define PG8_WAIT_L(n) asm volatile("s_waitcnt lgkmcnt(" #n ")" ::: "memory")
; #define PG8_BAR __builtin_amdgcn_s_barrier()
; #define PG8_SCHED __builtin_amdgcn_sched_barrier(0)
; template <class Epi>
; __device__ __forceinline__ void gemm_phase(LAS unsigned char* lds, const Gemm g, const StaticOrder& S, const Epi& E) {
;     ...
;             PG8_LDB(B0, 0, 0); PG8_SCHED; PG8_LDA(At, 0, 0); PG8_STAGE(PG8_SA(1, 1), a1 + hstepA, voffA);
;             PG8_WAIT_L(8); PG8_BAR; PG8_WAIT_L(0); PG8_MMA(0, 0, At, B0); PG8_BAR; PG8_SCHED;
;             PG8_LDB(B1, 0, 1); PG8_STAGE(PG8_SB(0, 0), b2, voffB);
;             PG8_BAR; PG8_WAIT_L(0); PG8_MMA(0, 1, At, B1); PG8_BAR;
;             PG8_LDA(At, 0, 1); PG8_STAGE(PG8_SA(0, 0), a2, voffA);
;             PG8_BAR; PG8_WAIT_L(0); PG8_MMA(1, 0, At, B0); PG8_BAR; PG8_SCHED;
;             PG8_STAGE(PG8_SB(0, 1), b2 + hstepB, voffB);
;             PG8_WAIT_V(6); PG8_BAR; PG8_MMA(1, 1, At, B1); PG8_BAR;
.LBB0_1204:
	ds_read_b128 v[146:149], v176
	ds_read_b128 v[154:157], v176 offset:1024
	ds_read_b128 v[158:161], v176 offset:2048
	ds_read_b128 v[162:165], v176 offset:3072
	s_add_u32 s22, s20, 0xfffc0080
	s_addc_u32 s23, s21, -1
	s_cmp_eq_u32 s45, 12
	s_cselect_b32 s25, s13, s23
	s_cselect_b32 s24, s41, s22
	s_cselect_b32 s23, s11, s44
	s_cselect_b32 s22, s42, s43
	v_lshl_add_u64 v[150:151], s[20:21], 0, v[138:139]
	s_add_i32 m0, s19, 0xc000
	ds_read_b128 v[166:169], v177
	ds_read_b128 v[170:173], v177 offset:1024
	ds_read_b128 v[180:183], v177 offset:2048
	ds_read_b128 v[184:187], v177 offset:3072
	ds_read_b128 v[188:191], v177 offset:4096
	ds_read_b128 v[192:195], v177 offset:5120
	ds_read_b128 v[196:199], v177 offset:6144
	ds_read_b128 v[200:203], v177 offset:7168
	global_load_lds_dwordx4 v[150:151], off
	v_lshl_add_u64 v[150:151], s[20:21], 0, v[140:141]
	s_add_i32 m0, s19, 0xe000
	s_nop 0
	global_load_lds_dwordx4 v[150:151], off
	s_waitcnt lgkmcnt(8)
	s_barrier
	s_waitcnt lgkmcnt(0)
	s_setprio 1
	s_waitcnt lgkmcnt(0)
	v_mfma_f32_16x16x32_bf16 v[124:127], v[146:149], v[166:169], v[124:127]
	v_mfma_f32_16x16x32_bf16 v[120:123], v[158:161], v[166:169], v[120:123]
	v_mfma_f32_16x16x32_bf16 v[108:111], v[146:149], v[180:183], v[108:111]
	v_mfma_f32_16x16x32_bf16 v[104:107], v[158:161], v[180:183], v[104:107]
	v_mfma_f32_16x16x32_bf16 v[92:95], v[146:149], v[188:191], v[92:95]
	v_mfma_f32_16x16x32_bf16 v[88:91], v[158:161], v[188:191], v[88:91]
	v_mfma_f32_16x16x32_bf16 v[76:79], v[146:149], v[196:199], v[76:79]
	v_mfma_f32_16x16x32_bf16 v[72:75], v[158:161], v[196:199], v[72:75]
	v_mfma_f32_16x16x32_bf16 v[124:127], v[154:157], v[170:173], v[124:127]
	v_mfma_f32_16x16x32_bf16 v[120:123], v[162:165], v[170:173], v[120:123]
	v_mfma_f32_16x16x32_bf16 v[108:111], v[154:157], v[184:187], v[108:111]
	v_mfma_f32_16x16x32_bf16 v[104:107], v[162:165], v[184:187], v[104:107]
	v_mfma_f32_16x16x32_bf16 v[92:95], v[154:157], v[192:195], v[92:95]
	v_mfma_f32_16x16x32_bf16 v[88:91], v[162:165], v[192:195], v[88:91]
	v_mfma_f32_16x16x32_bf16 v[76:79], v[154:157], v[200:203], v[76:79]
	v_mfma_f32_16x16x32_bf16 v[72:75], v[162:165], v[200:203], v[72:75]
	s_setprio 0
	s_barrier
	s_add_i32 s46, s37, s28
	v_lshl_add_u64 v[150:151], s[22:23], 0, v[130:131]
	s_mov_b32 m0, s46
	ds_read_b128 v[204:207], v178
	ds_read_b128 v[208:211], v178 offset:1024
	ds_read_b128 v[212:215], v178 offset:2048
	ds_read_b128 v[216:219], v178 offset:3072
	global_load_lds_dwordx4 v[150:151], off
	v_lshl_add_u64 v[220:221], s[22:23], 0, v[134:135]
	s_add_i32 m0, s46, 0x2000
	s_nop 0
	global_load_lds_dwordx4 v[220:221], off
	s_barrier
	s_waitcnt lgkmcnt(0)
	s_setprio 1
	s_waitcnt lgkmcnt(0)
	v_mfma_f32_16x16x32_bf16 v[116:119], v[204:207], v[166:169], v[116:119]
	v_mfma_f32_16x16x32_bf16 v[112:115], v[212:215], v[166:169], v[112:115]
	v_mfma_f32_16x16x32_bf16 v[100:103], v[204:207], v[180:183], v[100:103]
	v_mfma_f32_16x16x32_bf16 v[96:99], v[212:215], v[180:183], v[96:99]
	v_mfma_f32_16x16x32_bf16 v[84:87], v[204:207], v[188:191], v[84:87]
	v_mfma_f32_16x16x32_bf16 v[80:83], v[212:215], v[188:191], v[80:83]
	v_mfma_f32_16x16x32_bf16 v[68:71], v[204:207], v[196:199], v[68:71]
	v_mfma_f32_16x16x32_bf16 v[64:67], v[212:215], v[196:199], v[64:67]
	v_mfma_f32_16x16x32_bf16 v[116:119], v[208:211], v[170:173], v[116:119]
	v_mfma_f32_16x16x32_bf16 v[112:115], v[216:219], v[170:173], v[112:115]
	v_mfma_f32_16x16x32_bf16 v[100:103], v[208:211], v[184:187], v[100:103]
	v_mfma_f32_16x16x32_bf16 v[96:99], v[216:219], v[184:187], v[96:99]
	v_mfma_f32_16x16x32_bf16 v[84:87], v[208:211], v[192:195], v[84:87]
	v_mfma_f32_16x16x32_bf16 v[80:83], v[216:219], v[192:195], v[80:83]
	v_mfma_f32_16x16x32_bf16 v[68:71], v[208:211], v[200:203], v[68:71]
	v_mfma_f32_16x16x32_bf16 v[64:67], v[216:219], v[200:203], v[64:67]
	s_setprio 0
	s_mov_b32 m0, s19
	v_lshl_add_u64 v[222:223], s[24:25], 0, v[128:129]
	s_barrier
	ds_read_b128 v[166:169], v177 offset:16384
	ds_read_b128 v[170:173], v177 offset:17408
	ds_read_b128 v[180:183], v177 offset:18432
	ds_read_b128 v[184:187], v177 offset:19456
	ds_read_b128 v[188:191], v177 offset:20480
	ds_read_b128 v[192:195], v177 offset:21504
	ds_read_b128 v[196:199], v177 offset:22528
	ds_read_b128 v[200:203], v177 offset:23552
	global_load_lds_dwordx4 v[222:223], off
	v_lshl_add_u64 v[224:225], s[24:25], 0, v[132:133]
	s_mov_b32 m0, s29
	s_nop 0
	global_load_lds_dwordx4 v[224:225], off
	s_barrier
	s_waitcnt lgkmcnt(0)
	s_setprio 1
	s_waitcnt lgkmcnt(0)
	v_mfma_f32_16x16x32_bf16 v[60:63], v[146:149], v[166:169], v[60:63]
	v_mfma_f32_16x16x32_bf16 v[56:59], v[158:161], v[166:169], v[56:59]
	v_mfma_f32_16x16x32_bf16 v[44:47], v[146:149], v[180:183], v[44:47]
	v_mfma_f32_16x16x32_bf16 v[40:43], v[158:161], v[180:183], v[40:43]
	v_mfma_f32_16x16x32_bf16 v[28:31], v[146:149], v[188:191], v[28:31]
	v_mfma_f32_16x16x32_bf16 v[24:27], v[158:161], v[188:191], v[24:27]
	v_mfma_f32_16x16x32_bf16 v[12:15], v[146:149], v[196:199], v[12:15]
	v_mfma_f32_16x16x32_bf16 v[8:11], v[158:161], v[196:199], v[8:11]
	v_mfma_f32_16x16x32_bf16 v[60:63], v[154:157], v[170:173], v[60:63]
	v_mfma_f32_16x16x32_bf16 v[56:59], v[162:165], v[170:173], v[56:59]
	v_mfma_f32_16x16x32_bf16 v[44:47], v[154:157], v[184:187], v[44:47]
	v_mfma_f32_16x16x32_bf16 v[40:43], v[162:165], v[184:187], v[40:43]
	v_mfma_f32_16x16x32_bf16 v[28:31], v[154:157], v[192:195], v[28:31]
	v_mfma_f32_16x16x32_bf16 v[24:27], v[162:165], v[192:195], v[24:27]
	v_mfma_f32_16x16x32_bf16 v[12:15], v[154:157], v[200:203], v[12:15]
	v_mfma_f32_16x16x32_bf16 v[8:11], v[162:165], v[200:203], v[8:11]
	s_setprio 0
	s_barrier
; #define PG8_STAGE(bufoff, gbase, voff) do { _Pragma("unroll") for (int _i = 0; _i < 2; ++_i) \
;         __builtin_amdgcn_global_load_lds((const unsigned*)((const char*)(gbase) + (voff)[_i]), (LAS unsigned*)(lds + (bufoff) + ldsw + _i * 8192), 16, 0, 0); } while (0)
; #define PG8_LDA(dst, b, h) do { _Pragma("unroll") for (int m = 0; m < 4; ++m) _Pragma("unroll") for (int k = 0; k < 2; ++k) dst[m][k] = *(const LAS bf16x8*)(lds + PG8_SA(b, h) + aoff + m * 2048 + k * 1024); } while (0)
; #define PG8_LDB(dst, b, h) do { _Pragma("unroll") for (int n = 0; n < 2; ++n) _Pragma("unroll") for (int k = 0; k < 2; ++k) dst[n][k] = *(const LAS bf16x8*)(lds + PG8_SB(b, h) + boff + n * 2048 + k * 1024); } while (0)
; #define PG8_MMA(ai, bj, At, Bt) do { __builtin_amdgcn_s_setprio(1); _Pragma("unroll") for (int m = 0; m < 4; ++m) _Pragma("unroll") for (int n = 0; n < 2; ++n) _Pragma("unroll") for (int k = 0; k < 2; ++k) \
;         acc[ai][bj][m][n] = __builtin_amdgcn_mfma_f32_16x16x32_bf16(Bt[n][k], At[m][k], acc[ai][bj][m][n], 0, 0, 0); __builtin_amdgcn_s_setprio(0); } while (0)
; #define PG8_WAIT_V(n) asm volatile("s_waitcnt vmcnt(" #n ")" ::: "memory")
; #define PG8_WAIT_L(n) asm volatile("s_waitcnt lgkmcnt(" #n ")" ::: "memory")
; #define PG8_BAR __builtin_amdgcn_s_barrier()
; #define PG8_SCHED __builtin_amdgcn_sched_barrier(0)
; template <class Epi>
; __device__ __forceinline__ void gemm_phase(LAS unsigned char* lds, const Gemm g, const StaticOrder& S, const Epi& E) {
;     ...
;             PG8_WAIT_V(6); PG8_BAR; PG8_MMA(1, 1, At, B1); PG8_BAR;
;             PG8_LDB(B0, 1, 0); PG8_SCHED; PG8_LDA(At, 1, 0); PG8_STAGE(PG8_SA(0, 1), a2 + hstepA, voffA);
;             PG8_WAIT_L(8); PG8_BAR; PG8_WAIT_L(0); PG8_MMA(0, 0, At, B0); PG8_BAR; PG8_SCHED;
;             PG8_LDB(B1, 1, 1); PG8_STAGE(PG8_SB(1, 0), b3, voffB);
;             PG8_BAR; PG8_WAIT_L(0); PG8_MMA(0, 1, At, B1); PG8_BAR;
;             PG8_LDA(At, 1, 1); PG8_STAGE(PG8_SA(1, 0), a3, voffA);
;             PG8_BAR; PG8_WAIT_L(0); PG8_MMA(1, 0, At, B0); PG8_BAR; PG8_SCHED;
	s_add_u32 s46, s22, 0x40000
	s_addc_u32 s47, s23, 0
	s_add_i32 s48, s38, s28
	v_lshl_add_u64 v[146:147], s[46:47], 0, v[130:131]
	s_mov_b32 m0, s48
	s_nop 0
	global_load_lds_dwordx4 v[146:147], off
	v_lshl_add_u64 v[146:147], s[46:47], 0, v[134:135]
	s_add_i32 m0, s48, 0x2000
	s_nop 0
	global_load_lds_dwordx4 v[146:147], off
	s_waitcnt vmcnt(6)
	s_barrier
	s_setprio 1
	v_mfma_f32_16x16x32_bf16 v[52:55], v[204:207], v[166:169], v[52:55]
	v_mfma_f32_16x16x32_bf16 v[48:51], v[212:215], v[166:169], v[48:51]
	v_mfma_f32_16x16x32_bf16 v[36:39], v[204:207], v[180:183], v[36:39]
	v_mfma_f32_16x16x32_bf16 v[32:35], v[212:215], v[180:183], v[32:35]
	v_mfma_f32_16x16x32_bf16 v[20:23], v[204:207], v[188:191], v[20:23]
	v_mfma_f32_16x16x32_bf16 v[16:19], v[212:215], v[188:191], v[16:19]
	v_mfma_f32_16x16x32_bf16 v[4:7], v[204:207], v[196:199], v[4:7]
	v_mfma_f32_16x16x32_bf16 v[0:3], v[212:215], v[196:199], v[0:3]
	v_mfma_f32_16x16x32_bf16 v[52:55], v[208:211], v[170:173], v[52:55]
	v_mfma_f32_16x16x32_bf16 v[48:51], v[216:219], v[170:173], v[48:51]
	v_mfma_f32_16x16x32_bf16 v[36:39], v[208:211], v[184:187], v[36:39]
	v_mfma_f32_16x16x32_bf16 v[32:35], v[216:219], v[184:187], v[32:35]
	v_mfma_f32_16x16x32_bf16 v[20:23], v[208:211], v[192:195], v[20:23]
	v_mfma_f32_16x16x32_bf16 v[16:19], v[216:219], v[192:195], v[16:19]
	v_mfma_f32_16x16x32_bf16 v[4:7], v[208:211], v[200:203], v[4:7]
	v_mfma_f32_16x16x32_bf16 v[0:3], v[216:219], v[200:203], v[0:3]
	s_setprio 0
	s_add_i32 s46, 0, 0x18000
	v_add_u32_e32 v162, s46, v174
	s_barrier
	ds_read_b128 v[146:149], v162
	ds_read_b128 v[154:157], v162 offset:1024
	ds_read_b128 v[158:161], v162 offset:2048
	ds_read_b128 v[162:165], v162 offset:3072
	s_add_u32 s24, s24, 0x40000
	s_addc_u32 s25, s25, 0
	s_mov_b32 m0, s30
	v_lshl_add_u64 v[204:205], s[24:25], 0, v[128:129]
	ds_read_b128 v[166:169], v177 offset:32768
	ds_read_b128 v[170:173], v177 offset:33792
	ds_read_b128 v[180:183], v177 offset:34816
	ds_read_b128 v[184:187], v177 offset:35840
	ds_read_b128 v[188:191], v177 offset:36864
	ds_read_b128 v[192:195], v177 offset:37888
	ds_read_b128 v[196:199], v177 offset:38912
	ds_read_b128 v[200:203], v177 offset:39936
	global_load_lds_dwordx4 v[204:205], off
	v_lshl_add_u64 v[204:205], s[24:25], 0, v[132:133]
	s_mov_b32 m0, s31
	s_nop 0
	global_load_lds_dwordx4 v[204:205], off
	s_waitcnt lgkmcnt(8)
	s_barrier
	s_waitcnt lgkmcnt(0)
	s_setprio 1
	s_waitcnt lgkmcnt(0)
	v_mfma_f32_16x16x32_bf16 v[124:127], v[146:149], v[166:169], v[124:127]
	v_mfma_f32_16x16x32_bf16 v[120:123], v[158:161], v[166:169], v[120:123]
	v_mfma_f32_16x16x32_bf16 v[108:111], v[146:149], v[180:183], v[108:111]
	v_mfma_f32_16x16x32_bf16 v[104:107], v[158:161], v[180:183], v[104:107]
	v_mfma_f32_16x16x32_bf16 v[92:95], v[146:149], v[188:191], v[92:95]
	v_mfma_f32_16x16x32_bf16 v[88:91], v[158:161], v[188:191], v[88:91]
	v_mfma_f32_16x16x32_bf16 v[76:79], v[146:149], v[196:199], v[76:79]
	v_mfma_f32_16x16x32_bf16 v[72:75], v[158:161], v[196:199], v[72:75]
	v_mfma_f32_16x16x32_bf16 v[124:127], v[154:157], v[170:173], v[124:127]
	v_mfma_f32_16x16x32_bf16 v[120:123], v[162:165], v[170:173], v[120:123]
	v_mfma_f32_16x16x32_bf16 v[108:111], v[154:157], v[184:187], v[108:111]
	v_mfma_f32_16x16x32_bf16 v[104:107], v[162:165], v[184:187], v[104:107]
	v_mfma_f32_16x16x32_bf16 v[92:95], v[154:157], v[192:195], v[92:95]
	v_mfma_f32_16x16x32_bf16 v[88:91], v[162:165], v[192:195], v[88:91]
	v_mfma_f32_16x16x32_bf16 v[76:79], v[154:157], v[200:203], v[76:79]
	v_mfma_f32_16x16x32_bf16 v[72:75], v[162:165], v[200:203], v[72:75]
	s_setprio 0
	s_barrier
	s_add_i32 s24, 0, 0x1c000
	s_add_i32 s25, s46, s28
	v_add_u32_e32 v216, s24, v174
	v_lshl_add_u64 v[150:151], v[150:151], 0, s[4:5]
	s_mov_b32 m0, s25
	ds_read_b128 v[204:207], v216
	ds_read_b128 v[208:211], v216 offset:1024
	ds_read_b128 v[212:215], v216 offset:2048
	ds_read_b128 v[216:219], v216 offset:3072
	global_load_lds_dwordx4 v[150:151], off
	v_lshl_add_u64 v[150:151], v[220:221], 0, s[4:5]
	s_add_i32 m0, s25, 0x2000
	s_nop 0
	global_load_lds_dwordx4 v[150:151], off
	s_barrier
	s_waitcnt lgkmcnt(0)
	s_setprio 1
	s_waitcnt lgkmcnt(0)
	v_mfma_f32_16x16x32_bf16 v[116:119], v[204:207], v[166:169], v[116:119]
	v_mfma_f32_16x16x32_bf16 v[112:115], v[212:215], v[166:169], v[112:115]
	v_mfma_f32_16x16x32_bf16 v[100:103], v[204:207], v[180:183], v[100:103]
	v_mfma_f32_16x16x32_bf16 v[96:99], v[212:215], v[180:183], v[96:99]
	v_mfma_f32_16x16x32_bf16 v[84:87], v[204:207], v[188:191], v[84:87]
	v_mfma_f32_16x16x32_bf16 v[80:83], v[212:215], v[188:191], v[80:83]
	v_mfma_f32_16x16x32_bf16 v[68:71], v[204:207], v[196:199], v[68:71]
	v_mfma_f32_16x16x32_bf16 v[64:67], v[212:215], v[196:199], v[64:67]
	v_mfma_f32_16x16x32_bf16 v[116:119], v[208:211], v[170:173], v[116:119]
	v_mfma_f32_16x16x32_bf16 v[112:115], v[216:219], v[170:173], v[112:115]
	v_mfma_f32_16x16x32_bf16 v[100:103], v[208:211], v[184:187], v[100:103]
	v_mfma_f32_16x16x32_bf16 v[96:99], v[216:219], v[184:187], v[96:99]
	v_mfma_f32_16x16x32_bf16 v[84:87], v[208:211], v[192:195], v[84:87]
	v_mfma_f32_16x16x32_bf16 v[80:83], v[216:219], v[192:195], v[80:83]
	v_mfma_f32_16x16x32_bf16 v[68:71], v[208:211], v[200:203], v[68:71]
	v_mfma_f32_16x16x32_bf16 v[64:67], v[216:219], v[200:203], v[64:67]
	s_setprio 0
	s_mov_b32 m0, s34
	v_lshl_add_u64 v[150:151], v[222:223], 0, s[4:5]
	s_barrier
	ds_read_b128 v[166:169], v177 offset:49152
	ds_read_b128 v[170:173], v177 offset:50176
	ds_read_b128 v[180:183], v177 offset:51200
	ds_read_b128 v[184:187], v177 offset:52224
	ds_read_b128 v[188:191], v177 offset:53248
	ds_read_b128 v[192:195], v177 offset:54272
	ds_read_b128 v[196:199], v177 offset:55296
	ds_read_b128 v[200:203], v177 offset:56320
	global_load_lds_dwordx4 v[150:151], off
	v_lshl_add_u64 v[150:151], v[224:225], 0, s[4:5]
	s_mov_b32 m0, s35
	s_nop 0
	global_load_lds_dwordx4 v[150:151], off
	s_barrier
; __device__ __forceinline__ unsigned pk2(float lo, float hi) { const f32x2 v = (f32x2){lo, hi}; const bf16x2_t b = __builtin_convertvector(v, bf16x2_t); return __builtin_bit_cast(unsigned, b); }
; #define PG8_STAGE(bufoff, gbase, voff) do { _Pragma("unroll") for (int _i = 0; _i < 2; ++_i) \
;         __builtin_amdgcn_global_load_lds((const unsigned*)((const char*)(gbase) + (voff)[_i]), (LAS unsigned*)(lds + (bufoff) + ldsw + _i * 8192), 16, 0, 0); } while (0)
; #define PG8_MMA(ai, bj, At, Bt) do { __builtin_amdgcn_s_setprio(1); _Pragma("unroll") for (int m = 0; m < 4; ++m) _Pragma("unroll") for (int n = 0; n < 2; ++n) _Pragma("unroll") for (int k = 0; k < 2; ++k) \
;         acc[ai][bj][m][n] = __builtin_amdgcn_mfma_f32_16x16x32_bf16(Bt[n][k], At[m][k], acc[ai][bj][m][n], 0, 0, 0); __builtin_amdgcn_s_setprio(0); } while (0)
; #define PG8_WAIT_V(n) asm volatile("s_waitcnt vmcnt(" #n ")" ::: "memory")
; #define PG8_WAIT_L(n) asm volatile("s_waitcnt lgkmcnt(" #n ")" ::: "memory")
;     __device__ __forceinline__ void operator()(const f32x4 (&acc)[2][2][4][2], const Unit& u, int wr, int wc, int fr, int fq, const float (&)[8]) const {
;     ...
;         const int col0 = u.pn * BM + wc * 32 + 8 * fq;
; #pragma unroll
;         for (int ai = 0; ai < 2; ++ai)
; #pragma unroll
;             for (int m = 0; m < 4; ++m) { const int row = row0 + ai * HALF + m * 16; const float rs = rsqrtf(ep[ai * 4 + m] * (1.0f / 1024.0f) + EPS);
;                 u16* rowp = O + (size_t)row * ldc + col0;
; #pragma unroll
;                 for (int bj = 0; bj < 2; ++bj) { f32x4 v0 = acc[ai][bj][m][0] * rs, v1 = acc[ai][bj][m][1] * rs;
;                     if (ACT == 1) {
; #pragma unroll
;                         for (int j = 0; j < 4; ++j) { const float a0 = fmaxf(v0[j], 0.f), a1 = fmaxf(v1[j], 0.f); v0[j] = a0 * a0; v1[j] = a1 * a1; } }
;                     u32x4 w; w.x = pk2(v0[0], v0[1]); w.y = pk2(v0[2], v0[3]); w.z = pk2(v1[0], v1[1]); w.w = pk2(v1[2], v1[3]);
;                     *(u32x4*)(rowp + bj * HALF) = w; } }
; template <class Epi>
; __device__ __forceinline__ void gemm_phase(LAS unsigned char* lds, const Gemm g, const StaticOrder& S, const Epi& E) {
;     ...
;             PG8_BAR; PG8_WAIT_L(0); PG8_MMA(1, 0, At, B0); PG8_BAR; PG8_SCHED;
;             PG8_STAGE(PG8_SB(1, 1), b3 + hstepB, voffB);
;             PG8_WAIT_V(6); PG8_BAR; PG8_MMA(1, 1, At, B1); PG8_BAR;
	s_waitcnt lgkmcnt(0)
	s_setprio 1
	s_waitcnt lgkmcnt(0)
	v_mfma_f32_16x16x32_bf16 v[60:63], v[146:149], v[166:169], v[60:63]
	v_mfma_f32_16x16x32_bf16 v[56:59], v[158:161], v[166:169], v[56:59]
	v_mfma_f32_16x16x32_bf16 v[44:47], v[146:149], v[180:183], v[44:47]
	v_mfma_f32_16x16x32_bf16 v[40:43], v[158:161], v[180:183], v[40:43]
	v_mfma_f32_16x16x32_bf16 v[28:31], v[146:149], v[188:191], v[28:31]
	v_mfma_f32_16x16x32_bf16 v[24:27], v[158:161], v[188:191], v[24:27]
	v_mfma_f32_16x16x32_bf16 v[12:15], v[146:149], v[196:199], v[12:15]
	v_mfma_f32_16x16x32_bf16 v[8:11], v[158:161], v[196:199], v[8:11]
	v_mfma_f32_16x16x32_bf16 v[60:63], v[154:157], v[170:173], v[60:63]
	v_mfma_f32_16x16x32_bf16 v[56:59], v[162:165], v[170:173], v[56:59]
	v_mfma_f32_16x16x32_bf16 v[44:47], v[154:157], v[184:187], v[44:47]
	v_mfma_f32_16x16x32_bf16 v[40:43], v[162:165], v[184:187], v[40:43]
	v_mfma_f32_16x16x32_bf16 v[28:31], v[154:157], v[192:195], v[28:31]
	v_mfma_f32_16x16x32_bf16 v[24:27], v[162:165], v[192:195], v[24:27]
	v_mfma_f32_16x16x32_bf16 v[12:15], v[154:157], v[200:203], v[12:15]
	v_mfma_f32_16x16x32_bf16 v[8:11], v[162:165], v[200:203], v[8:11]
	s_setprio 0
	s_barrier
	s_add_u32 s22, s22, 0x40080
	s_addc_u32 s23, s23, 0
	s_add_i32 s24, s24, s28
	v_lshl_add_u64 v[146:147], s[22:23], 0, v[130:131]
	s_mov_b32 m0, s24
	s_nop 0
	global_load_lds_dwordx4 v[146:147], off
	v_lshl_add_u64 v[146:147], s[22:23], 0, v[134:135]
	s_add_i32 m0, s24, 0x2000
	s_nop 0
	global_load_lds_dwordx4 v[146:147], off
	s_waitcnt vmcnt(6)
	s_barrier
	s_setprio 1
	v_mfma_f32_16x16x32_bf16 v[52:55], v[204:207], v[166:169], v[52:55]
	v_mfma_f32_16x16x32_bf16 v[48:51], v[212:215], v[166:169], v[48:51]
	v_mfma_f32_16x16x32_bf16 v[36:39], v[204:207], v[180:183], v[36:39]
	v_mfma_f32_16x16x32_bf16 v[32:35], v[212:215], v[180:183], v[32:35]
	v_mfma_f32_16x16x32_bf16 v[20:23], v[204:207], v[188:191], v[20:23]
	v_mfma_f32_16x16x32_bf16 v[16:19], v[212:215], v[188:191], v[16:19]
	v_mfma_f32_16x16x32_bf16 v[4:7], v[204:207], v[196:199], v[4:7]
	v_mfma_f32_16x16x32_bf16 v[0:3], v[212:215], v[196:199], v[0:3]
	v_mfma_f32_16x16x32_bf16 v[52:55], v[208:211], v[170:173], v[52:55]
	v_mfma_f32_16x16x32_bf16 v[48:51], v[216:219], v[170:173], v[48:51]
	v_mfma_f32_16x16x32_bf16 v[36:39], v[208:211], v[184:187], v[36:39]
	v_mfma_f32_16x16x32_bf16 v[32:35], v[216:219], v[184:187], v[32:35]
	v_mfma_f32_16x16x32_bf16 v[20:23], v[208:211], v[192:195], v[20:23]
	v_mfma_f32_16x16x32_bf16 v[16:19], v[216:219], v[192:195], v[16:19]
	v_mfma_f32_16x16x32_bf16 v[4:7], v[208:211], v[200:203], v[4:7]
	v_mfma_f32_16x16x32_bf16 v[0:3], v[216:219], v[200:203], v[0:3]
	s_setprio 0
	s_add_i32 s45, s45, 2
	s_add_u32 s20, s20, 0x100
	s_addc_u32 s21, s21, 0
	s_add_u32 s43, s43, 0x100
	s_addc_u32 s44, s44, 0
	s_cmp_gt_u32 s45, 13
	s_barrier
	s_cbranch_scc0 .LBB0_1204
	s_bfe_u32 vcc_lo, s18, 0x20003
	s_lshl_b32 vcc_lo, vcc_lo, 10
	s_add_i32 vcc_lo, vcc_lo, 0x20010
	v_lshl_add_u32 v236, v153, 2, vcc_lo
	ds_read_b32 v228, v236
	ds_read_b32 v229, v236 offset:64
	ds_read_b32 v230, v236 offset:128
	ds_read_b32 v231, v236 offset:192
	ds_read_b32 v232, v236 offset:512
	ds_read_b32 v233, v236 offset:576
	ds_read_b32 v234, v236 offset:640
	ds_read_b32 v235, v236 offset:704
	s_waitcnt lgkmcnt(0)
	v_lshl_add_u32 v148, s18, 8, v153
	v_ashrrev_i32_e32 v149, 31, v148
	v_or_b32_e32 v172, 16, v148
	v_ashrrev_i32_e32 v173, 31, v172
	v_or_b32_e32 v168, 32, v148
	v_or_b32_e32 v164, 48, v148
	v_ashrrev_i32_e32 v169, 31, v168
	v_ashrrev_i32_e32 v165, 31, v164
	v_add_u32_e32 v162, 0x80, v148
	v_add_u32_e32 v156, 0x90, v148
	v_ashrrev_i32_e32 v163, 31, v162
	v_ashrrev_i32_e32 v157, 31, v156
	v_add_u32_e32 v150, 0xa0, v148
	v_ashrrev_i32_e32 v151, 31, v150
	v_add_u32_e32 v146, 0xb0, v148
	v_ashrrev_i32_e32 v147, 31, v146
	v_lshl_or_b32 v166, s40, 8, v175
	v_ashrrev_i32_e32 v167, 31, v166
	v_lshlrev_b64 v[170:171], 13, v[148:149]
	v_lshlrev_b64 v[148:149], 1, v[166:167]
	v_lshl_add_u64 v[166:167], s[96:97], 0, v[170:171]
	v_lshl_add_u64 v[210:211], v[166:167], 0, v[148:149]
	s_mov_b32 s40, s10
	s_mov_b32 s18, s12
	s_mov_b64 s[22:23], s[16:17]
	s_mov_b64 s[20:21], s[14:15]
	s_waitcnt vmcnt(8)
	s_waitcnt lgkmcnt(0)
	s_waitcnt lgkmcnt(0)
	v_mov_b32_e32 v182, v228
	v_pk_mul_f32 v[120:121], v[120:121], v[182:183] op_sel_hi:[1,0]
	v_pk_mul_f32 v[126:127], v[126:127], v[182:183] op_sel_hi:[1,0]
	v_pk_mul_f32 v[124:125], v[124:125], v[182:183] op_sel_hi:[1,0]
	v_pk_mul_f32 v[122:123], v[122:123], v[182:183] op_sel_hi:[1,0]
	v_max_f32_e32 v120, 0, v120
	v_max_f32_e32 v121, 0, v121
	v_max_f32_e32 v124, 0, v124
	v_max_f32_e32 v125, 0, v125
	v_pk_mul_f32 v[188:189], v[120:121], v[120:121]
	v_max_f32_e32 v120, 0, v126
	v_max_f32_e32 v122, 0, v122
	v_max_f32_e32 v121, 0, v127
	v_max_f32_e32 v123, 0, v123
	v_pk_mul_f32 v[124:125], v[124:125], v[124:125]
	v_pk_mul_f32 v[126:127], v[120:121], v[120:121]
	v_pk_mul_f32 v[192:193], v[122:123], v[122:123]
	v_pk_mul_f32 v[114:115], v[114:115], v[182:183] op_sel_hi:[1,0]
	v_cvt_pk_bf16_f32 v120, v124, v125
	v_cvt_pk_bf16_f32 v121, v126, v127
	v_cvt_pk_bf16_f32 v122, v188, v189
	v_cvt_pk_bf16_f32 v123, v192, v193
	v_pk_mul_f32 v[116:117], v[116:117], v[182:183] op_sel_hi:[1,0]
	v_pk_mul_f32 v[112:113], v[112:113], v[182:183] op_sel_hi:[1,0]
	v_max_f32_e32 v114, 0, v114
	v_max_f32_e32 v115, 0, v115
	global_store_dwordx4 v[210:211], v[120:123], off
	v_pk_mul_f32 v[118:119], v[118:119], v[182:183] op_sel_hi:[1,0]
	v_max_f32_e32 v116, 0, v116
	v_max_f32_e32 v112, 0, v112
	v_max_f32_e32 v117, 0, v117
	v_max_f32_e32 v113, 0, v113
	v_pk_mul_f32 v[122:123], v[114:115], v[114:115]
	v_pk_mul_f32 v[116:117], v[116:117], v[116:117]
; __device__ __forceinline__ unsigned pk2(float lo, float hi) { const f32x2 v = (f32x2){lo, hi}; const bf16x2_t b = __builtin_convertvector(v, bf16x2_t); return __builtin_bit_cast(unsigned, b); }
;     __device__ __forceinline__ void operator()(const f32x4 (&acc)[2][2][4][2], const Unit& u, int wr, int wc, int fr, int fq, const float (&)[8]) const {
;     ...
;             for (int m = 0; m < 4; ++m) { const int row = row0 + ai * HALF + m * 16; const float rs = rsqrtf(ep[ai * 4 + m] * (1.0f / 1024.0f) + EPS);
;                 u16* rowp = O + (size_t)row * ldc + col0;
; #pragma unroll
;                 for (int bj = 0; bj < 2; ++bj) { f32x4 v0 = acc[ai][bj][m][0] * rs, v1 = acc[ai][bj][m][1] * rs;
;                     if (ACT == 1) {
; #pragma unroll
;                         for (int j = 0; j < 4; ++j) { const float a0 = fmaxf(v0[j], 0.f), a1 = fmaxf(v1[j], 0.f); v0[j] = a0 * a0; v1[j] = a1 * a1; } }
;                     u32x4 w; w.x = pk2(v0[0], v0[1]); w.y = pk2(v0[2], v0[3]); w.z = pk2(v1[0], v1[1]); w.w = pk2(v1[2], v1[3]);
;                     *(u32x4*)(rowp + bj * HALF) = w; } }
	v_pk_mul_f32 v[120:121], v[112:113], v[112:113]
	v_max_f32_e32 v112, 0, v118
	v_max_f32_e32 v113, 0, v119
	v_pk_mul_f32 v[118:119], v[112:113], v[112:113]
	v_cvt_pk_bf16_f32 v112, v116, v117
	v_cvt_pk_bf16_f32 v113, v118, v119
	v_cvt_pk_bf16_f32 v114, v120, v121
	v_cvt_pk_bf16_f32 v115, v122, v123
	global_store_dwordx4 v[210:211], v[112:115], off offset:256
	s_nop 1
	v_mov_b32_e32 v112, v229
	v_pk_mul_f32 v[104:105], v[104:105], v[112:113] op_sel_hi:[1,0]
	v_pk_mul_f32 v[110:111], v[110:111], v[112:113] op_sel_hi:[1,0]
	v_pk_mul_f32 v[108:109], v[108:109], v[112:113] op_sel_hi:[1,0]
	v_pk_mul_f32 v[106:107], v[106:107], v[112:113] op_sel_hi:[1,0]
	v_max_f32_e32 v104, 0, v104
	v_max_f32_e32 v105, 0, v105
	v_lshlrev_b64 v[114:115], 13, v[172:173]
	v_max_f32_e32 v108, 0, v108
	v_max_f32_e32 v109, 0, v109
	v_pk_mul_f32 v[116:117], v[104:105], v[104:105]
	v_max_f32_e32 v104, 0, v110
	v_max_f32_e32 v106, 0, v106
	v_max_f32_e32 v105, 0, v111
	v_max_f32_e32 v107, 0, v107
	v_lshl_add_u64 v[114:115], s[96:97], 0, v[114:115]
	v_pk_mul_f32 v[108:109], v[108:109], v[108:109]
	v_pk_mul_f32 v[110:111], v[104:105], v[104:105]
	v_pk_mul_f32 v[118:119], v[106:107], v[106:107]
	v_pk_mul_f32 v[96:97], v[96:97], v[112:113] op_sel_hi:[1,0]
	v_lshl_add_u64 v[114:115], v[114:115], 0, v[148:149]
	v_cvt_pk_bf16_f32 v104, v108, v109
	v_cvt_pk_bf16_f32 v105, v110, v111
	v_cvt_pk_bf16_f32 v106, v116, v117
	v_cvt_pk_bf16_f32 v107, v118, v119
	v_pk_mul_f32 v[102:103], v[102:103], v[112:113] op_sel_hi:[1,0]
	v_max_f32_e32 v96, 0, v96
	v_max_f32_e32 v97, 0, v97
	global_store_dwordx4 v[114:115], v[104:107], off
	v_pk_mul_f32 v[100:101], v[100:101], v[112:113] op_sel_hi:[1,0]
	v_pk_mul_f32 v[98:99], v[98:99], v[112:113] op_sel_hi:[1,0]
	v_pk_mul_f32 v[104:105], v[96:97], v[96:97]
	v_max_f32_e32 v96, 0, v102
	v_max_f32_e32 v97, 0, v103
	v_max_f32_e32 v100, 0, v100
	v_max_f32_e32 v101, 0, v101
	v_pk_mul_f32 v[100:101], v[100:101], v[100:101]
	v_pk_mul_f32 v[108:109], v[96:97], v[96:97]
	v_cvt_pk_bf16_f32 v96, v100, v101
	s_waitcnt lgkmcnt(0)
	v_max_f32_e32 v98, 0, v98
	v_max_f32_e32 v99, 0, v99
	v_pk_mul_f32 v[110:111], v[98:99], v[98:99]
	v_cvt_pk_bf16_f32 v97, v108, v109
	v_cvt_pk_bf16_f32 v98, v104, v105
	v_cvt_pk_bf16_f32 v99, v110, v111
	global_store_dwordx4 v[114:115], v[96:99], off offset:256
	s_waitcnt lgkmcnt(0)
	s_nop 0
	s_nop 0
	s_nop 0
	s_nop 1
	v_lshlrev_b64 v[98:99], 13, v[168:169]
	v_lshl_add_u64 v[98:99], s[96:97], 0, v[98:99]
	v_lshl_add_u64 v[98:99], v[98:99], 0, v[148:149]
	v_mov_b32_e32 v100, v230
	v_pk_mul_f32 v[88:89], v[88:89], v[100:101] op_sel_hi:[1,0]
	v_pk_mul_f32 v[94:95], v[94:95], v[100:101] op_sel_hi:[1,0]
	v_pk_mul_f32 v[92:93], v[92:93], v[100:101] op_sel_hi:[1,0]
	v_pk_mul_f32 v[90:91], v[90:91], v[100:101] op_sel_hi:[1,0]
	v_max_f32_e32 v88, 0, v88
	v_max_f32_e32 v89, 0, v89
	v_max_f32_e32 v92, 0, v92
	v_max_f32_e32 v93, 0, v93
	v_pk_mul_f32 v[102:103], v[88:89], v[88:89]
	v_max_f32_e32 v88, 0, v94
	v_max_f32_e32 v90, 0, v90
	v_max_f32_e32 v89, 0, v95
	v_max_f32_e32 v91, 0, v91
	v_pk_mul_f32 v[92:93], v[92:93], v[92:93]
	v_pk_mul_f32 v[94:95], v[88:89], v[88:89]
	v_pk_mul_f32 v[104:105], v[90:91], v[90:91]
	v_pk_mul_f32 v[82:83], v[82:83], v[100:101] op_sel_hi:[1,0]
	v_cvt_pk_bf16_f32 v88, v92, v93
	v_cvt_pk_bf16_f32 v89, v94, v95
	v_cvt_pk_bf16_f32 v90, v102, v103
	v_cvt_pk_bf16_f32 v91, v104, v105
	v_pk_mul_f32 v[84:85], v[84:85], v[100:101] op_sel_hi:[1,0]
	v_pk_mul_f32 v[80:81], v[80:81], v[100:101] op_sel_hi:[1,0]
	v_max_f32_e32 v82, 0, v82
	v_max_f32_e32 v83, 0, v83
	global_store_dwordx4 v[98:99], v[88:91], off
	v_pk_mul_f32 v[86:87], v[86:87], v[100:101] op_sel_hi:[1,0]
	v_max_f32_e32 v84, 0, v84
	v_max_f32_e32 v80, 0, v80
	v_max_f32_e32 v85, 0, v85
	v_max_f32_e32 v81, 0, v81
	v_pk_mul_f32 v[90:91], v[82:83], v[82:83]
	v_pk_mul_f32 v[84:85], v[84:85], v[84:85]
	v_pk_mul_f32 v[88:89], v[80:81], v[80:81]
	v_max_f32_e32 v80, 0, v86
	v_max_f32_e32 v81, 0, v87
	v_pk_mul_f32 v[86:87], v[80:81], v[80:81]
	v_cvt_pk_bf16_f32 v80, v84, v85
	v_cvt_pk_bf16_f32 v81, v86, v87
	v_cvt_pk_bf16_f32 v82, v88, v89
	v_cvt_pk_bf16_f32 v83, v90, v91
	global_store_dwordx4 v[98:99], v[80:83], off offset:256
	s_nop 1
	v_mov_b32_e32 v80, v231
	v_pk_mul_f32 v[72:73], v[72:73], v[80:81] op_sel_hi:[1,0]
	v_pk_mul_f32 v[78:79], v[78:79], v[80:81] op_sel_hi:[1,0]
	v_pk_mul_f32 v[76:77], v[76:77], v[80:81] op_sel_hi:[1,0]
	v_pk_mul_f32 v[74:75], v[74:75], v[80:81] op_sel_hi:[1,0]
	v_max_f32_e32 v72, 0, v72
	v_max_f32_e32 v73, 0, v73
	v_lshlrev_b64 v[82:83], 13, v[164:165]
	v_max_f32_e32 v76, 0, v76
	v_max_f32_e32 v77, 0, v77
	v_pk_mul_f32 v[84:85], v[72:73], v[72:73]
	v_max_f32_e32 v72, 0, v78
	v_max_f32_e32 v74, 0, v74
	v_max_f32_e32 v73, 0, v79
	v_max_f32_e32 v75, 0, v75
	v_lshl_add_u64 v[82:83], s[96:97], 0, v[82:83]
	v_pk_mul_f32 v[76:77], v[76:77], v[76:77]
	v_pk_mul_f32 v[78:79], v[72:73], v[72:73]
	v_pk_mul_f32 v[86:87], v[74:75], v[74:75]
	v_pk_mul_f32 v[64:65], v[64:65], v[80:81] op_sel_hi:[1,0]
	v_lshl_add_u64 v[82:83], v[82:83], 0, v[148:149]
	v_cvt_pk_bf16_f32 v72, v76, v77
	v_cvt_pk_bf16_f32 v73, v78, v79
	v_cvt_pk_bf16_f32 v74, v84, v85
	v_cvt_pk_bf16_f32 v75, v86, v87
	v_pk_mul_f32 v[70:71], v[70:71], v[80:81] op_sel_hi:[1,0]
	v_max_f32_e32 v64, 0, v64
	v_max_f32_e32 v65, 0, v65
	global_store_dwordx4 v[82:83], v[72:75], off
	v_pk_mul_f32 v[68:69], v[68:69], v[80:81] op_sel_hi:[1,0]
	v_pk_mul_f32 v[66:67], v[66:67], v[80:81] op_sel_hi:[1,0]
	v_pk_mul_f32 v[72:73], v[64:65], v[64:65]
	v_max_f32_e32 v64, 0, v70
	v_max_f32_e32 v65, 0, v71
	v_max_f32_e32 v68, 0, v68
	v_max_f32_e32 v69, 0, v69
	v_pk_mul_f32 v[68:69], v[68:69], v[68:69]
	v_pk_mul_f32 v[76:77], v[64:65], v[64:65]
	v_cvt_pk_bf16_f32 v64, v68, v69
	s_waitcnt lgkmcnt(0)
; __device__ __forceinline__ unsigned pk2(float lo, float hi) { const f32x2 v = (f32x2){lo, hi}; const bf16x2_t b = __builtin_convertvector(v, bf16x2_t); return __builtin_bit_cast(unsigned, b); }
;     __device__ __forceinline__ void operator()(const f32x4 (&acc)[2][2][4][2], const Unit& u, int wr, int wc, int fr, int fq, const float (&)[8]) const {
;     ...
;             for (int m = 0; m < 4; ++m) { const int row = row0 + ai * HALF + m * 16; const float rs = rsqrtf(ep[ai * 4 + m] * (1.0f / 1024.0f) + EPS);
;                 u16* rowp = O + (size_t)row * ldc + col0;
; #pragma unroll
;                 for (int bj = 0; bj < 2; ++bj) { f32x4 v0 = acc[ai][bj][m][0] * rs, v1 = acc[ai][bj][m][1] * rs;
;                     if (ACT == 1) {
; #pragma unroll
;                         for (int j = 0; j < 4; ++j) { const float a0 = fmaxf(v0[j], 0.f), a1 = fmaxf(v1[j], 0.f); v0[j] = a0 * a0; v1[j] = a1 * a1; } }
;                     u32x4 w; w.x = pk2(v0[0], v0[1]); w.y = pk2(v0[2], v0[3]); w.z = pk2(v1[0], v1[1]); w.w = pk2(v1[2], v1[3]);
;                     *(u32x4*)(rowp + bj * HALF) = w; } }
	v_max_f32_e32 v66, 0, v66
	v_max_f32_e32 v67, 0, v67
	v_pk_mul_f32 v[78:79], v[66:67], v[66:67]
	v_cvt_pk_bf16_f32 v65, v76, v77
	v_cvt_pk_bf16_f32 v66, v72, v73
	v_cvt_pk_bf16_f32 v67, v78, v79
	global_store_dwordx4 v[82:83], v[64:67], off offset:256
	s_waitcnt lgkmcnt(0)
	s_nop 0
	s_nop 0
	s_nop 0
	s_nop 1
	v_lshlrev_b64 v[66:67], 13, v[162:163]
	v_lshl_add_u64 v[66:67], s[96:97], 0, v[66:67]
	v_lshl_add_u64 v[66:67], v[66:67], 0, v[148:149]
	v_mov_b32_e32 v68, v232
	v_pk_mul_f32 v[56:57], v[56:57], v[68:69] op_sel_hi:[1,0]
	v_pk_mul_f32 v[62:63], v[62:63], v[68:69] op_sel_hi:[1,0]
	v_pk_mul_f32 v[60:61], v[60:61], v[68:69] op_sel_hi:[1,0]
	v_pk_mul_f32 v[58:59], v[58:59], v[68:69] op_sel_hi:[1,0]
	v_max_f32_e32 v56, 0, v56
	v_max_f32_e32 v57, 0, v57
	v_max_f32_e32 v60, 0, v60
	v_max_f32_e32 v61, 0, v61
	v_pk_mul_f32 v[70:71], v[56:57], v[56:57]
	v_max_f32_e32 v56, 0, v62
	v_max_f32_e32 v58, 0, v58
	v_max_f32_e32 v57, 0, v63
	v_max_f32_e32 v59, 0, v59
	v_pk_mul_f32 v[60:61], v[60:61], v[60:61]
	v_pk_mul_f32 v[62:63], v[56:57], v[56:57]
	v_pk_mul_f32 v[72:73], v[58:59], v[58:59]
	v_pk_mul_f32 v[50:51], v[50:51], v[68:69] op_sel_hi:[1,0]
	v_cvt_pk_bf16_f32 v56, v60, v61
	v_cvt_pk_bf16_f32 v57, v62, v63
	v_cvt_pk_bf16_f32 v58, v70, v71
	v_cvt_pk_bf16_f32 v59, v72, v73
	v_pk_mul_f32 v[52:53], v[52:53], v[68:69] op_sel_hi:[1,0]
	v_pk_mul_f32 v[48:49], v[48:49], v[68:69] op_sel_hi:[1,0]
	v_max_f32_e32 v50, 0, v50
	v_max_f32_e32 v51, 0, v51
	global_store_dwordx4 v[66:67], v[56:59], off
	v_pk_mul_f32 v[54:55], v[54:55], v[68:69] op_sel_hi:[1,0]
	v_max_f32_e32 v52, 0, v52
	v_max_f32_e32 v48, 0, v48
	v_max_f32_e32 v53, 0, v53
	v_max_f32_e32 v49, 0, v49
	v_pk_mul_f32 v[58:59], v[50:51], v[50:51]
	v_pk_mul_f32 v[52:53], v[52:53], v[52:53]
	v_pk_mul_f32 v[56:57], v[48:49], v[48:49]
	v_max_f32_e32 v48, 0, v54
	v_max_f32_e32 v49, 0, v55
	v_pk_mul_f32 v[54:55], v[48:49], v[48:49]
	v_cvt_pk_bf16_f32 v48, v52, v53
	v_cvt_pk_bf16_f32 v49, v54, v55
	v_cvt_pk_bf16_f32 v50, v56, v57
	v_cvt_pk_bf16_f32 v51, v58, v59
	global_store_dwordx4 v[66:67], v[48:51], off offset:256
	s_nop 1
	v_mov_b32_e32 v48, v233
	v_pk_mul_f32 v[40:41], v[40:41], v[48:49] op_sel_hi:[1,0]
	v_pk_mul_f32 v[46:47], v[46:47], v[48:49] op_sel_hi:[1,0]
	v_pk_mul_f32 v[44:45], v[44:45], v[48:49] op_sel_hi:[1,0]
	v_pk_mul_f32 v[42:43], v[42:43], v[48:49] op_sel_hi:[1,0]
	v_max_f32_e32 v40, 0, v40
	v_max_f32_e32 v41, 0, v41
	v_lshlrev_b64 v[50:51], 13, v[156:157]
	v_max_f32_e32 v44, 0, v44
	v_max_f32_e32 v45, 0, v45
	v_pk_mul_f32 v[52:53], v[40:41], v[40:41]
	v_max_f32_e32 v40, 0, v46
	v_max_f32_e32 v42, 0, v42
	v_max_f32_e32 v41, 0, v47
	v_max_f32_e32 v43, 0, v43
	v_lshl_add_u64 v[50:51], s[96:97], 0, v[50:51]
	v_pk_mul_f32 v[44:45], v[44:45], v[44:45]
	v_pk_mul_f32 v[46:47], v[40:41], v[40:41]
	v_pk_mul_f32 v[54:55], v[42:43], v[42:43]
	v_pk_mul_f32 v[32:33], v[32:33], v[48:49] op_sel_hi:[1,0]
	v_lshl_add_u64 v[50:51], v[50:51], 0, v[148:149]
	v_cvt_pk_bf16_f32 v236, v44, v45
	v_cvt_pk_bf16_f32 v237, v46, v47
	v_cvt_pk_bf16_f32 v238, v52, v53
	v_cvt_pk_bf16_f32 v239, v54, v55
	v_pk_mul_f32 v[38:39], v[38:39], v[48:49] op_sel_hi:[1,0]
	v_max_f32_e32 v32, 0, v32
	v_max_f32_e32 v33, 0, v33
	v_mov_b64_e32 v[248:249], v[50:51]
	v_pk_mul_f32 v[36:37], v[36:37], v[48:49] op_sel_hi:[1,0]
	v_pk_mul_f32 v[34:35], v[34:35], v[48:49] op_sel_hi:[1,0]
	v_pk_mul_f32 v[40:41], v[32:33], v[32:33]
	v_max_f32_e32 v32, 0, v38
	v_max_f32_e32 v33, 0, v39
	v_max_f32_e32 v36, 0, v36
	v_max_f32_e32 v37, 0, v37
	v_pk_mul_f32 v[36:37], v[36:37], v[36:37]
	v_pk_mul_f32 v[44:45], v[32:33], v[32:33]
	v_cvt_pk_bf16_f32 v240, v36, v37
	s_waitcnt lgkmcnt(0)
	v_max_f32_e32 v34, 0, v34
	v_max_f32_e32 v35, 0, v35
	v_pk_mul_f32 v[46:47], v[34:35], v[34:35]
	v_cvt_pk_bf16_f32 v241, v44, v45
	v_cvt_pk_bf16_f32 v242, v40, v41
	v_cvt_pk_bf16_f32 v243, v46, v47
	s_waitcnt lgkmcnt(0)
; __device__ __forceinline__ unsigned pk2(float lo, float hi) { const f32x2 v = (f32x2){lo, hi}; const bf16x2_t b = __builtin_convertvector(v, bf16x2_t); return __builtin_bit_cast(unsigned, b); }
;     __device__ __forceinline__ void operator()(const f32x4 (&acc)[2][2][4][2], const Unit& u, int wr, int wc, int fr, int fq, const float (&)[8]) const {
;     ...
;             for (int m = 0; m < 4; ++m) { const int row = row0 + ai * HALF + m * 16; const float rs = rsqrtf(ep[ai * 4 + m] * (1.0f / 1024.0f) + EPS);
;                 u16* rowp = O + (size_t)row * ldc + col0;
; #pragma unroll
;                 for (int bj = 0; bj < 2; ++bj) { f32x4 v0 = acc[ai][bj][m][0] * rs, v1 = acc[ai][bj][m][1] * rs;
;                     if (ACT == 1) {
; #pragma unroll
;                         for (int j = 0; j < 4; ++j) { const float a0 = fmaxf(v0[j], 0.f), a1 = fmaxf(v1[j], 0.f); v0[j] = a0 * a0; v1[j] = a1 * a1; } }
;                     u32x4 w; w.x = pk2(v0[0], v0[1]); w.y = pk2(v0[2], v0[3]); w.z = pk2(v1[0], v1[1]); w.w = pk2(v1[2], v1[3]);
;                     *(u32x4*)(rowp + bj * HALF) = w; } }
; template <class Epi>
; __device__ __forceinline__ void gemm_phase(LAS unsigned char* lds, const Gemm g, const StaticOrder& S, const Epi& E) {
;     ...
;         if (!has_next) break;
	s_nop 0
	s_nop 0
	s_nop 0
	s_nop 1
	v_lshlrev_b64 v[34:35], 13, v[150:151]
	v_lshl_add_u64 v[34:35], s[96:97], 0, v[34:35]
	v_lshl_add_u64 v[34:35], v[34:35], 0, v[148:149]
	v_mov_b32_e32 v36, v234
	v_pk_mul_f32 v[24:25], v[24:25], v[36:37] op_sel_hi:[1,0]
	v_pk_mul_f32 v[30:31], v[30:31], v[36:37] op_sel_hi:[1,0]
	v_pk_mul_f32 v[28:29], v[28:29], v[36:37] op_sel_hi:[1,0]
	v_pk_mul_f32 v[26:27], v[26:27], v[36:37] op_sel_hi:[1,0]
	v_max_f32_e32 v24, 0, v24
	v_max_f32_e32 v25, 0, v25
	v_max_f32_e32 v28, 0, v28
	v_max_f32_e32 v29, 0, v29
	v_pk_mul_f32 v[38:39], v[24:25], v[24:25]
	v_max_f32_e32 v24, 0, v30
	v_max_f32_e32 v26, 0, v26
	v_max_f32_e32 v25, 0, v31
	v_max_f32_e32 v27, 0, v27
	v_pk_mul_f32 v[28:29], v[28:29], v[28:29]
	v_pk_mul_f32 v[30:31], v[24:25], v[24:25]
	v_pk_mul_f32 v[40:41], v[26:27], v[26:27]
	v_pk_mul_f32 v[18:19], v[18:19], v[36:37] op_sel_hi:[1,0]
	v_cvt_pk_bf16_f32 v244, v28, v29
	v_cvt_pk_bf16_f32 v245, v30, v31
	v_cvt_pk_bf16_f32 v246, v38, v39
	v_cvt_pk_bf16_f32 v247, v40, v41
	v_pk_mul_f32 v[20:21], v[20:21], v[36:37] op_sel_hi:[1,0]
	v_pk_mul_f32 v[16:17], v[16:17], v[36:37] op_sel_hi:[1,0]
	v_max_f32_e32 v18, 0, v18
	v_max_f32_e32 v19, 0, v19
	v_pk_mul_f32 v[22:23], v[22:23], v[36:37] op_sel_hi:[1,0]
	v_max_f32_e32 v20, 0, v20
	v_max_f32_e32 v16, 0, v16
	v_max_f32_e32 v21, 0, v21
	v_max_f32_e32 v17, 0, v17
	v_pk_mul_f32 v[26:27], v[18:19], v[18:19]
	v_pk_mul_f32 v[20:21], v[20:21], v[20:21]
	v_pk_mul_f32 v[24:25], v[16:17], v[16:17]
	v_max_f32_e32 v16, 0, v22
	v_max_f32_e32 v17, 0, v23
	v_pk_mul_f32 v[22:23], v[16:17], v[16:17]
	v_cvt_pk_bf16_f32 v252, v20, v21
	v_cvt_pk_bf16_f32 v253, v22, v23
	v_cvt_pk_bf16_f32 v254, v24, v25
	v_cvt_pk_bf16_f32 v255, v26, v27
	s_nop 1
	v_mov_b32_e32 v16, v235
	v_pk_mul_f32 v[8:9], v[8:9], v[16:17] op_sel_hi:[1,0]
	v_pk_mul_f32 v[14:15], v[14:15], v[16:17] op_sel_hi:[1,0]
	v_pk_mul_f32 v[12:13], v[12:13], v[16:17] op_sel_hi:[1,0]
	v_pk_mul_f32 v[10:11], v[10:11], v[16:17] op_sel_hi:[1,0]
	v_max_f32_e32 v8, 0, v8
	v_max_f32_e32 v9, 0, v9
	v_lshlrev_b64 v[18:19], 13, v[146:147]
	v_max_f32_e32 v12, 0, v12
	v_max_f32_e32 v13, 0, v13
	v_pk_mul_f32 v[20:21], v[8:9], v[8:9]
	v_max_f32_e32 v8, 0, v14
	v_max_f32_e32 v10, 0, v10
	v_max_f32_e32 v9, 0, v15
	v_max_f32_e32 v11, 0, v11
	v_lshl_add_u64 v[18:19], s[96:97], 0, v[18:19]
	v_pk_mul_f32 v[12:13], v[12:13], v[12:13]
	v_pk_mul_f32 v[14:15], v[8:9], v[8:9]
	v_pk_mul_f32 v[22:23], v[10:11], v[10:11]
	v_pk_mul_f32 v[0:1], v[0:1], v[16:17] op_sel_hi:[1,0]
	v_lshl_add_u64 v[18:19], v[18:19], 0, v[148:149]
	v_cvt_pk_bf16_f32 v228, v12, v13
	v_cvt_pk_bf16_f32 v229, v14, v15
	v_cvt_pk_bf16_f32 v230, v20, v21
	v_cvt_pk_bf16_f32 v231, v22, v23
	v_pk_mul_f32 v[6:7], v[6:7], v[16:17] op_sel_hi:[1,0]
	v_pk_mul_f32 v[4:5], v[4:5], v[16:17] op_sel_hi:[1,0]
	v_pk_mul_f32 v[2:3], v[2:3], v[16:17] op_sel_hi:[1,0]
	v_max_f32_e32 v0, 0, v0
	v_max_f32_e32 v1, 0, v1
	v_max_f32_e32 v4, 0, v4
	v_max_f32_e32 v5, 0, v5
	v_pk_mul_f32 v[8:9], v[0:1], v[0:1]
	v_max_f32_e32 v0, 0, v6
	v_max_f32_e32 v2, 0, v2
	v_max_f32_e32 v1, 0, v7
	v_max_f32_e32 v3, 0, v3
	v_pk_mul_f32 v[4:5], v[4:5], v[4:5]
	v_pk_mul_f32 v[6:7], v[0:1], v[0:1]
	v_pk_mul_f32 v[10:11], v[2:3], v[2:3]
	v_cvt_pk_bf16_f32 v232, v4, v5
	v_cvt_pk_bf16_f32 v233, v6, v7
	v_cvt_pk_bf16_f32 v234, v8, v9
	v_cvt_pk_bf16_f32 v235, v10, v11
	s_and_b64 vcc, exec, s[0:1]
	s_cbranch_vccz .Ldf12_head
	global_store_dwordx4 v[248:249], v[236:239], off
	global_store_dwordx4 v[248:249], v[240:243], off offset:256
	v_lshl_add_u64 v[248:249], v[248:249], 0, s[98:99]
	global_store_dwordx4 v[248:249], v[244:247], off
	global_store_dwordx4 v[248:249], v[252:255], off offset:256
	v_lshl_add_u64 v[248:249], v[248:249], 0, s[98:99]
	global_store_dwordx4 v[248:249], v[228:231], off
	global_store_dwordx4 v[248:249], v[232:235], off offset:256
	s_waitcnt vmcnt(0)
	s_cmpk_gt_u32 s7, 0xff
	s_cbranch_scc1 .LBB0_1208
	s_barrier

; template <bool COOP>
; __global__ void __launch_bounds__(512, 2) mega(Args A) {
	.amdhsa_kernel _Z4megaILb1EEv4Args
		.amdhsa_group_segment_fixed_size 4096
		.amdhsa_private_segment_fixed_size 0
		.amdhsa_kernarg_size 472
		.amdhsa_user_sgpr_count 2
		.amdhsa_user_sgpr_dispatch_ptr 0
		.amdhsa_user_sgpr_queue_ptr 0
		.amdhsa_user_sgpr_kernarg_segment_ptr 1
		.amdhsa_user_sgpr_dispatch_id 0
		.amdhsa_user_sgpr_kernarg_preload_length 0
		.amdhsa_user_sgpr_kernarg_preload_offset 0
		.amdhsa_user_sgpr_private_segment_size 0
		.amdhsa_uses_dynamic_stack 0
		.amdhsa_enable_private_segment 0
		.amdhsa_system_sgpr_workgroup_id_x 1
		.amdhsa_system_sgpr_workgroup_id_y 0
		.amdhsa_system_sgpr_workgroup_id_z 0
		.amdhsa_system_sgpr_workgroup_info 0
		.amdhsa_system_vgpr_workitem_id 2
		.amdhsa_next_free_vgpr 256
		.amdhsa_next_free_sgpr 100
		.amdhsa_accum_offset 256
		.amdhsa_reserve_vcc 1
		.amdhsa_float_round_mode_32 0
		.amdhsa_float_round_mode_16_64 0
		.amdhsa_float_denorm_mode_32 3
		.amdhsa_float_denorm_mode_16_64 3
		.amdhsa_dx10_clamp 1
		.amdhsa_ieee_mode 1
		.amdhsa_fp16_overflow 0
		.amdhsa_tg_split 0
		.amdhsa_exception_fp_ieee_invalid_op 0
		.amdhsa_exception_fp_denorm_src 0
		.amdhsa_exception_fp_ieee_div_zero 0
		.amdhsa_exception_fp_ieee_overflow 0
		.amdhsa_exception_fp_ieee_underflow 0
		.amdhsa_exception_fp_ieee_inexact 0
		.amdhsa_exception_int_div_zero 0
	.end_amdhsa_kernel

; template <bool COOP>
; __global__ void __launch_bounds__(512, 2) mega(Args A) {
amdhsa.kernels:
  - .agpr_count:     0
    .args:
      - .offset:         0
        .size:           216
        .value_kind:     by_value
      - .offset:         216
        .size:           4
        .value_kind:     hidden_block_count_x
      - .offset:         220
        .size:           4
        .value_kind:     hidden_block_count_y
      - .offset:         224
        .size:           4
        .value_kind:     hidden_block_count_z
      - .offset:         228
        .size:           2
        .value_kind:     hidden_group_size_x
      - .offset:         230
        .size:           2
        .value_kind:     hidden_group_size_y
      - .offset:         232
        .size:           2
        .value_kind:     hidden_group_size_z
      - .offset:         234
        .size:           2
        .value_kind:     hidden_remainder_x
      - .offset:         236
        .size:           2
        .value_kind:     hidden_remainder_y
      - .offset:         238
        .size:           2
        .value_kind:     hidden_remainder_z
      - .offset:         256
        .size:           8
        .value_kind:     hidden_global_offset_x
      - .offset:         264
        .size:           8
        .value_kind:     hidden_global_offset_y
      - .offset:         272
        .size:           8
        .value_kind:     hidden_global_offset_z
      - .offset:         280
        .size:           2
        .value_kind:     hidden_grid_dims
      - .offset:         304
        .size:           8
        .value_kind:     hidden_multigrid_sync_arg
      - .offset:         336
        .size:           4
        .value_kind:     hidden_dynamic_lds_size
    .group_segment_fixed_size: 4096
    .kernarg_segment_align: 8
    .kernarg_segment_size: 472
    .language:       OpenCL C
    .language_version:
      - 2
      - 0
    .max_flat_workgroup_size: 512
    .name:           _Z4megaILb1EEv4Args
    .private_segment_fixed_size: 0
    .sgpr_count:     106
    .sgpr_spill_count: 86
    .symbol:         _Z4megaILb1EEv4Args.kd
    .uniform_work_group_size: 1
    .uses_dynamic_stack: false
    .vgpr_count:     256
    .vgpr_spill_count: 0
    .wavefront_size: 64
